# GEMM K-loop: staging writes and next-tile loads spread one per MFMA slot (finer interleave)
# speedup vs baseline: 1.1036x; 1.0082x over previous
.LBB0_147:
	s_waitcnt lgkmcnt(0)
	s_barrier
	ds_read_b128 v[224:227], v184
	ds_read_b128 v[228:231], v184 offset:1024
	ds_read_b128 v[232:235], v184 offset:2048
	ds_read_b128 v[236:239], v184 offset:3072
	ds_read_b128 v[190:193], v185
	ds_read_b128 v[194:197], v185 offset:1024
	ds_read_b128 v[198:201], v185 offset:2048
	ds_read_b128 v[204:207], v185 offset:3072
	ds_read_b128 v[208:211], v185 offset:4096
	ds_read_b128 v[212:215], v185 offset:5120
	ds_read_b128 v[216:219], v185 offset:6144
	ds_read_b128 v[220:223], v185 offset:7168
	s_movk_i32 vcc_lo, 0x6000
	s_cmp_eq_u32 m0, 2
	s_cselect_b32 vcc_lo, 0xffff4000, vcc_lo
	s_add_u32 m0, m0, 1
	s_cmp_eq_u32 m0, 3
	s_cselect_b32 m0, 0, m0
	v_add_u32_e32 v185, vcc_lo, v185
	v_add_u32_e32 v184, vcc_lo, v184
	v_xor_b32_e32 v185, 64, v185
	v_xor_b32_e32 v184, 64, v184
	s_waitcnt lgkmcnt(7)
	v_mfma_f32_16x16x32_bf16 v[172:175], v[224:227], v[190:193], v[172:175]
	v_mfma_f32_16x16x32_bf16 v[168:171], v[228:231], v[190:193], v[168:171]
	v_mfma_f32_16x16x32_bf16 v[164:167], v[232:235], v[190:193], v[164:167]
	v_mfma_f32_16x16x32_bf16 v[160:163], v[236:239], v[190:193], v[160:163]
	ds_read_b128 v[190:193], v185
	s_waitcnt lgkmcnt(7)
	v_mfma_f32_16x16x32_bf16 v[156:159], v[224:227], v[194:197], v[156:159]
	v_mfma_f32_16x16x32_bf16 v[152:155], v[228:231], v[194:197], v[152:155]
	v_mfma_f32_16x16x32_bf16 v[148:151], v[232:235], v[194:197], v[148:151]
	v_mfma_f32_16x16x32_bf16 v[144:147], v[236:239], v[194:197], v[144:147]
	ds_read_b128 v[194:197], v185 offset:1024
	s_waitcnt lgkmcnt(7)
	v_mfma_f32_16x16x32_bf16 v[136:139], v[224:227], v[198:201], v[136:139]
	v_mfma_f32_16x16x32_bf16 v[132:135], v[228:231], v[198:201], v[132:135]
	v_mfma_f32_16x16x32_bf16 v[128:131], v[232:235], v[198:201], v[128:131]
	v_mfma_f32_16x16x32_bf16 v[124:127], v[236:239], v[198:201], v[124:127]
	ds_read_b128 v[198:201], v185 offset:2048
	s_waitcnt lgkmcnt(7)
	v_mfma_f32_16x16x32_bf16 v[120:123], v[224:227], v[204:207], v[120:123]
	v_mfma_f32_16x16x32_bf16 v[108:111], v[228:231], v[204:207], v[108:111]
	v_mfma_f32_16x16x32_bf16 v[100:103], v[232:235], v[204:207], v[100:103]
	v_mfma_f32_16x16x32_bf16 v[96:99], v[236:239], v[204:207], v[96:99]
	ds_read_b128 v[204:207], v185 offset:3072
	s_waitcnt lgkmcnt(7)
	v_mfma_f32_16x16x32_bf16 v[92:95], v[224:227], v[208:211], v[92:95]
	v_mfma_f32_16x16x32_bf16 v[84:87], v[228:231], v[208:211], v[84:87]
	v_mfma_f32_16x16x32_bf16 v[76:79], v[232:235], v[208:211], v[76:79]
	v_mfma_f32_16x16x32_bf16 v[72:75], v[236:239], v[208:211], v[72:75]
	ds_read_b128 v[208:211], v185 offset:4096
	s_waitcnt lgkmcnt(7)
	v_mfma_f32_16x16x32_bf16 v[64:67], v[224:227], v[212:215], v[64:67]
	v_mfma_f32_16x16x32_bf16 v[52:55], v[228:231], v[212:215], v[52:55]
	v_mfma_f32_16x16x32_bf16 v[48:51], v[232:235], v[212:215], v[48:51]
	v_mfma_f32_16x16x32_bf16 v[44:47], v[236:239], v[212:215], v[44:47]
	ds_read_b128 v[212:215], v185 offset:5120
	s_waitcnt lgkmcnt(7)
	v_mfma_f32_16x16x32_bf16 v[36:39], v[224:227], v[216:219], v[36:39]
	v_mfma_f32_16x16x32_bf16 v[28:31], v[228:231], v[216:219], v[28:31]
	v_mfma_f32_16x16x32_bf16 v[24:27], v[232:235], v[216:219], v[24:27]
	v_mfma_f32_16x16x32_bf16 v[20:23], v[236:239], v[216:219], v[20:23]
	ds_read_b128 v[216:219], v185 offset:6144
	s_waitcnt lgkmcnt(7)
	v_mfma_f32_16x16x32_bf16 v[12:15], v[224:227], v[220:223], v[12:15]
	v_mfma_f32_16x16x32_bf16 v[4:7], v[228:231], v[220:223], v[4:7]
	v_mfma_f32_16x16x32_bf16 v[0:3], v[232:235], v[220:223], v[0:3]
	v_mfma_f32_16x16x32_bf16 v[140:143], v[236:239], v[220:223], v[140:143]
	ds_read_b128 v[220:223], v185 offset:7168
	ds_read_b128 v[224:227], v184
	ds_read_b128 v[228:231], v184 offset:1024
	ds_read_b128 v[232:235], v184 offset:2048
	ds_read_b128 v[236:239], v184 offset:3072
	s_movk_i32 vcc_lo, 0x6000
	s_cmp_eq_u32 m0, 2
	s_cselect_b32 vcc_lo, 0xffff4000, vcc_lo
	s_add_u32 m0, m0, 1
	s_cmp_eq_u32 m0, 3
	s_cselect_b32 m0, 0, m0
	v_add_u32_e32 v185, vcc_lo, v185
	v_add_u32_e32 v184, vcc_lo, v184
	v_xor_b32_e32 v185, 64, v185
	v_xor_b32_e32 v184, 64, v184
	s_sub_u32 vcc_lo, s8, s98
	v_add_u32_e32 v186, vcc_lo, v178
	v_add_u32_e32 v187, vcc_lo, v180
	s_barrier
	s_waitcnt lgkmcnt(0)
	v_mfma_f32_16x16x32_bf16 v[172:175], v[224:227], v[190:193], v[172:175]
	s_waitcnt vmcnt(11)
	v_mfma_f32_16x16x32_bf16 v[168:171], v[228:231], v[190:193], v[168:171]
	ds_write_b128 v183, v[116:119]
	v_add_u32_e32 v116, s26, v187
	v_mfma_f32_16x16x32_bf16 v[164:167], v[232:235], v[190:193], v[164:167]
	global_load_dwordx4 v[116:119], v116, s[98:99] offset:128
	v_mfma_f32_16x16x32_bf16 v[160:163], v[236:239], v[190:193], v[160:163]
	s_waitcnt vmcnt(11)
	ds_write_b128 v183, v[112:115] offset:2048
	v_mfma_f32_16x16x32_bf16 v[156:159], v[224:227], v[194:197], v[156:159]
	v_add_u32_e32 v112, s27, v187
	v_mfma_f32_16x16x32_bf16 v[152:155], v[228:231], v[194:197], v[152:155]
	global_load_dwordx4 v[112:115], v112, s[98:99] offset:128
	s_waitcnt vmcnt(11)
	v_mfma_f32_16x16x32_bf16 v[148:151], v[232:235], v[194:197], v[148:151]
	ds_write_b128 v183, v[104:107] offset:4096
	v_mfma_f32_16x16x32_bf16 v[144:147], v[236:239], v[194:197], v[144:147]
	v_add_u32_e32 v104, s20, v187
	global_load_dwordx4 v[104:107], v104, s[98:99] offset:128
	v_mfma_f32_16x16x32_bf16 v[136:139], v[224:227], v[198:201], v[136:139]
	s_waitcnt vmcnt(11)
	v_mfma_f32_16x16x32_bf16 v[132:135], v[228:231], v[198:201], v[132:135]
	ds_write_b128 v183, v[88:91] offset:6144
	v_add_u32_e32 v88, s21, v187
	v_mfma_f32_16x16x32_bf16 v[128:131], v[232:235], v[198:201], v[128:131]
	global_load_dwordx4 v[88:91], v88, s[98:99] offset:128
	v_mfma_f32_16x16x32_bf16 v[124:127], v[236:239], v[198:201], v[124:127]
	s_waitcnt vmcnt(11)
	ds_write_b128 v183, v[80:83] offset:8192
	v_mfma_f32_16x16x32_bf16 v[120:123], v[224:227], v[204:207], v[120:123]
	v_add_u32_e32 v80, s56, v187
	v_mfma_f32_16x16x32_bf16 v[108:111], v[228:231], v[204:207], v[108:111]
	global_load_dwordx4 v[80:83], v80, s[98:99] offset:128
	s_waitcnt vmcnt(11)
	v_mfma_f32_16x16x32_bf16 v[100:103], v[232:235], v[204:207], v[100:103]
	ds_write_b128 v183, v[68:71] offset:10240
	v_mfma_f32_16x16x32_bf16 v[96:99], v[236:239], v[204:207], v[96:99]
	v_add_u32_e32 v68, s57, v187
	global_load_dwordx4 v[68:71], v68, s[98:99] offset:128
	v_mfma_f32_16x16x32_bf16 v[92:95], v[224:227], v[208:211], v[92:95]
	s_waitcnt vmcnt(11)
	v_mfma_f32_16x16x32_bf16 v[84:87], v[228:231], v[208:211], v[84:87]
	ds_write_b128 v183, v[60:63] offset:12288
	v_add_u32_e32 v60, s24, v187
	v_mfma_f32_16x16x32_bf16 v[76:79], v[232:235], v[208:211], v[76:79]
	global_load_dwordx4 v[60:63], v60, s[98:99] offset:128
	v_mfma_f32_16x16x32_bf16 v[72:75], v[236:239], v[208:211], v[72:75]
	s_waitcnt vmcnt(11)
	ds_write_b128 v183, v[40:43] offset:14336
	v_mfma_f32_16x16x32_bf16 v[64:67], v[224:227], v[212:215], v[64:67]
	v_add_u32_e32 v40, s96, v187
	v_mfma_f32_16x16x32_bf16 v[52:55], v[228:231], v[212:215], v[52:55]
	global_load_dwordx4 v[40:43], v40, s[98:99] offset:128
	s_waitcnt vmcnt(11)
	v_mfma_f32_16x16x32_bf16 v[48:51], v[232:235], v[212:215], v[48:51]
	ds_write_b128 v183, v[56:59] offset:16384
	v_mfma_f32_16x16x32_bf16 v[44:47], v[236:239], v[212:215], v[44:47]
	v_mov_b32_e32 v56, v186
	global_load_dwordx4 v[56:59], v56, s[98:99] offset:128
	v_mfma_f32_16x16x32_bf16 v[36:39], v[224:227], v[216:219], v[36:39]
	s_waitcnt vmcnt(11)
	v_mfma_f32_16x16x32_bf16 v[28:31], v[228:231], v[216:219], v[28:31]
	ds_write_b128 v183, v[32:35] offset:18432
	v_add_u32_e32 v32, s31, v186
	v_mfma_f32_16x16x32_bf16 v[24:27], v[232:235], v[216:219], v[24:27]
	global_load_dwordx4 v[32:35], v32, s[98:99] offset:128
	v_mfma_f32_16x16x32_bf16 v[20:23], v[236:239], v[216:219], v[20:23]
	s_waitcnt vmcnt(11)
	ds_write_b128 v183, v[16:19] offset:20480
	v_mfma_f32_16x16x32_bf16 v[12:15], v[224:227], v[220:223], v[12:15]
	v_add_u32_e32 v16, s14, v186
	v_mfma_f32_16x16x32_bf16 v[4:7], v[228:231], v[220:223], v[4:7]
	global_load_dwordx4 v[16:19], v16, s[98:99] offset:128
	s_waitcnt vmcnt(11)
	v_mfma_f32_16x16x32_bf16 v[0:3], v[232:235], v[220:223], v[0:3]
	ds_write_b128 v183, v[8:11] offset:22528
	v_mfma_f32_16x16x32_bf16 v[140:143], v[236:239], v[220:223], v[140:143]
	v_add_u32_e32 v8, s13, v186
	global_load_dwordx4 v[8:11], v8, s[98:99] offset:128
	v_cmp_gt_u32_e32 vcc, 0x6000, v183
	v_add_u32_e32 v182, 0xc000, v183
	v_add_u32_e32 v183, 0xffffa000, v183
	s_nop 0
	v_cndmask_b32_e32 v183, v183, v182, vcc
	s_add_u32 s8, s8, 0x80
	s_addc_u32 s9, s9, 0
	s_cmpk_lg_i32 s8, 0x780
	s_cbranch_scc1 .LBB0_147
	s_waitcnt lgkmcnt(0)
	s_barrier
	ds_read_b128 v[224:227], v184
	ds_read_b128 v[228:231], v184 offset:1024
	ds_read_b128 v[232:235], v184 offset:2048
	ds_read_b128 v[236:239], v184 offset:3072
	ds_read_b128 v[190:193], v185
	ds_read_b128 v[194:197], v185 offset:1024
	ds_read_b128 v[198:201], v185 offset:2048
	ds_read_b128 v[204:207], v185 offset:3072
	ds_read_b128 v[208:211], v185 offset:4096
	ds_read_b128 v[212:215], v185 offset:5120
	ds_read_b128 v[216:219], v185 offset:6144
	ds_read_b128 v[220:223], v185 offset:7168
	s_movk_i32 vcc_lo, 0x6000
	s_cmp_eq_u32 m0, 2
	s_cselect_b32 vcc_lo, 0xffff4000, vcc_lo
	s_add_u32 m0, m0, 1
	s_cmp_eq_u32 m0, 3
	s_cselect_b32 m0, 0, m0
	v_add_u32_e32 v185, vcc_lo, v185
	v_add_u32_e32 v184, vcc_lo, v184
	v_xor_b32_e32 v185, 64, v185
	v_xor_b32_e32 v184, 64, v184
	s_waitcnt lgkmcnt(7)
	v_mfma_f32_16x16x32_bf16 v[172:175], v[224:227], v[190:193], v[172:175]
	v_mfma_f32_16x16x32_bf16 v[168:171], v[228:231], v[190:193], v[168:171]
	v_mfma_f32_16x16x32_bf16 v[164:167], v[232:235], v[190:193], v[164:167]
	v_mfma_f32_16x16x32_bf16 v[160:163], v[236:239], v[190:193], v[160:163]
	ds_read_b128 v[190:193], v185
	s_waitcnt lgkmcnt(7)
	v_mfma_f32_16x16x32_bf16 v[156:159], v[224:227], v[194:197], v[156:159]
	v_mfma_f32_16x16x32_bf16 v[152:155], v[228:231], v[194:197], v[152:155]
	v_mfma_f32_16x16x32_bf16 v[148:151], v[232:235], v[194:197], v[148:151]
	v_mfma_f32_16x16x32_bf16 v[144:147], v[236:239], v[194:197], v[144:147]
	ds_read_b128 v[194:197], v185 offset:1024
	s_waitcnt lgkmcnt(7)
	v_mfma_f32_16x16x32_bf16 v[136:139], v[224:227], v[198:201], v[136:139]
	v_mfma_f32_16x16x32_bf16 v[132:135], v[228:231], v[198:201], v[132:135]
	v_mfma_f32_16x16x32_bf16 v[128:131], v[232:235], v[198:201], v[128:131]
	v_mfma_f32_16x16x32_bf16 v[124:127], v[236:239], v[198:201], v[124:127]
	ds_read_b128 v[198:201], v185 offset:2048
	s_waitcnt lgkmcnt(7)
	v_mfma_f32_16x16x32_bf16 v[120:123], v[224:227], v[204:207], v[120:123]
	v_mfma_f32_16x16x32_bf16 v[108:111], v[228:231], v[204:207], v[108:111]
	v_mfma_f32_16x16x32_bf16 v[100:103], v[232:235], v[204:207], v[100:103]
	v_mfma_f32_16x16x32_bf16 v[96:99], v[236:239], v[204:207], v[96:99]
	ds_read_b128 v[204:207], v185 offset:3072
	s_waitcnt lgkmcnt(7)
	v_mfma_f32_16x16x32_bf16 v[92:95], v[224:227], v[208:211], v[92:95]
	v_mfma_f32_16x16x32_bf16 v[84:87], v[228:231], v[208:211], v[84:87]
	v_mfma_f32_16x16x32_bf16 v[76:79], v[232:235], v[208:211], v[76:79]
	v_mfma_f32_16x16x32_bf16 v[72:75], v[236:239], v[208:211], v[72:75]
	ds_read_b128 v[208:211], v185 offset:4096
	s_waitcnt lgkmcnt(7)
	v_mfma_f32_16x16x32_bf16 v[64:67], v[224:227], v[212:215], v[64:67]
	v_mfma_f32_16x16x32_bf16 v[52:55], v[228:231], v[212:215], v[52:55]
	v_mfma_f32_16x16x32_bf16 v[48:51], v[232:235], v[212:215], v[48:51]
	v_mfma_f32_16x16x32_bf16 v[44:47], v[236:239], v[212:215], v[44:47]
	ds_read_b128 v[212:215], v185 offset:5120
	s_waitcnt lgkmcnt(7)
	v_mfma_f32_16x16x32_bf16 v[36:39], v[224:227], v[216:219], v[36:39]
	v_mfma_f32_16x16x32_bf16 v[28:31], v[228:231], v[216:219], v[28:31]
	v_mfma_f32_16x16x32_bf16 v[24:27], v[232:235], v[216:219], v[24:27]
	v_mfma_f32_16x16x32_bf16 v[20:23], v[236:239], v[216:219], v[20:23]
	ds_read_b128 v[216:219], v185 offset:6144
	s_waitcnt lgkmcnt(7)
	v_mfma_f32_16x16x32_bf16 v[12:15], v[224:227], v[220:223], v[12:15]
	v_mfma_f32_16x16x32_bf16 v[4:7], v[228:231], v[220:223], v[4:7]
	v_mfma_f32_16x16x32_bf16 v[0:3], v[232:235], v[220:223], v[0:3]
	v_mfma_f32_16x16x32_bf16 v[140:143], v[236:239], v[220:223], v[140:143]
	ds_read_b128 v[220:223], v185 offset:7168
	ds_read_b128 v[224:227], v184
	ds_read_b128 v[228:231], v184 offset:1024
	ds_read_b128 v[232:235], v184 offset:2048
	ds_read_b128 v[236:239], v184 offset:3072
	s_movk_i32 vcc_lo, 0x6000
	s_cmp_eq_u32 m0, 2
	s_cselect_b32 vcc_lo, 0xffff4000, vcc_lo
	s_add_u32 m0, m0, 1
	s_cmp_eq_u32 m0, 3
	s_cselect_b32 m0, 0, m0
	v_add_u32_e32 v185, vcc_lo, v185
	v_add_u32_e32 v184, vcc_lo, v184
	v_xor_b32_e32 v185, 64, v185
	v_xor_b32_e32 v184, 64, v184
	s_waitcnt lgkmcnt(0)
	v_mfma_f32_16x16x32_bf16 v[172:175], v[224:227], v[190:193], v[172:175]
	v_mfma_f32_16x16x32_bf16 v[168:171], v[228:231], v[190:193], v[168:171]
	v_mfma_f32_16x16x32_bf16 v[164:167], v[232:235], v[190:193], v[164:167]
	v_mfma_f32_16x16x32_bf16 v[160:163], v[236:239], v[190:193], v[160:163]
	v_mfma_f32_16x16x32_bf16 v[156:159], v[224:227], v[194:197], v[156:159]
	v_mfma_f32_16x16x32_bf16 v[152:155], v[228:231], v[194:197], v[152:155]
	v_mfma_f32_16x16x32_bf16 v[148:151], v[232:235], v[194:197], v[148:151]
	v_mfma_f32_16x16x32_bf16 v[144:147], v[236:239], v[194:197], v[144:147]
	v_mfma_f32_16x16x32_bf16 v[136:139], v[224:227], v[198:201], v[136:139]
	v_mfma_f32_16x16x32_bf16 v[132:135], v[228:231], v[198:201], v[132:135]
	v_mfma_f32_16x16x32_bf16 v[128:131], v[232:235], v[198:201], v[128:131]
	v_mfma_f32_16x16x32_bf16 v[124:127], v[236:239], v[198:201], v[124:127]
	v_mfma_f32_16x16x32_bf16 v[120:123], v[224:227], v[204:207], v[120:123]
	v_mfma_f32_16x16x32_bf16 v[108:111], v[228:231], v[204:207], v[108:111]
	v_mfma_f32_16x16x32_bf16 v[100:103], v[232:235], v[204:207], v[100:103]
	v_mfma_f32_16x16x32_bf16 v[96:99], v[236:239], v[204:207], v[96:99]
	v_mfma_f32_16x16x32_bf16 v[92:95], v[224:227], v[208:211], v[92:95]
	v_mfma_f32_16x16x32_bf16 v[84:87], v[228:231], v[208:211], v[84:87]
	v_mfma_f32_16x16x32_bf16 v[76:79], v[232:235], v[208:211], v[76:79]
	v_mfma_f32_16x16x32_bf16 v[72:75], v[236:239], v[208:211], v[72:75]
	v_mfma_f32_16x16x32_bf16 v[64:67], v[224:227], v[212:215], v[64:67]
	v_mfma_f32_16x16x32_bf16 v[52:55], v[228:231], v[212:215], v[52:55]
	v_mfma_f32_16x16x32_bf16 v[48:51], v[232:235], v[212:215], v[48:51]
	v_mfma_f32_16x16x32_bf16 v[44:47], v[236:239], v[212:215], v[44:47]
	v_mfma_f32_16x16x32_bf16 v[36:39], v[224:227], v[216:219], v[36:39]
	v_mfma_f32_16x16x32_bf16 v[28:31], v[228:231], v[216:219], v[28:31]
	v_mfma_f32_16x16x32_bf16 v[24:27], v[232:235], v[216:219], v[24:27]
	v_mfma_f32_16x16x32_bf16 v[20:23], v[236:239], v[216:219], v[20:23]
	v_mfma_f32_16x16x32_bf16 v[12:15], v[224:227], v[220:223], v[12:15]
	v_mfma_f32_16x16x32_bf16 v[4:7], v[228:231], v[220:223], v[4:7]
	v_mfma_f32_16x16x32_bf16 v[0:3], v[232:235], v[220:223], v[0:3]
	v_mfma_f32_16x16x32_bf16 v[140:143], v[236:239], v[220:223], v[140:143]
	v_lshrrev_b32_e32 v224, 4, v188
	v_and_b32_e32 v225, 7, v188
	v_bitop3_b32 v226, v224, v225, 3 bitop3:0x6c
	v_lshlrev_b32_e32 v227, 7, v188
	v_bfe_u32 v228, v188, 4, 2
	v_and_b32_e32 v229, 0xffffc780, v227
	v_and_b32_e32 v227, 0x2780, v227
	v_bitop3_b32 v228, v228, v225, 4 bitop3:0x36
	v_lshlrev_b32_e32 v226, 4, v226
	v_lshlrev_b32_e32 v228, 4, v228
	v_or_b32_e32 v185, v229, v226
	v_or_b32_e32 v184, v227, v226
	v_or_b32_e32 v183, v229, v228
	v_or_b32_e32 v182, v227, v228
	s_waitcnt vmcnt(0)
	s_barrier
	s_waitcnt vmcnt(10)
	ds_write_b128 v176, v[116:119]
	s_waitcnt vmcnt(9)
	ds_write_b128 v176, v[112:115] offset:4096
	s_waitcnt vmcnt(8)
	ds_write_b128 v176, v[104:107] offset:8192
	s_waitcnt vmcnt(7)
	ds_write_b128 v176, v[88:91] offset:12288
	s_waitcnt vmcnt(6)
	ds_write_b128 v176, v[80:83] offset:16384
	s_waitcnt vmcnt(5)
	ds_write_b128 v176, v[68:71] offset:20480
	s_waitcnt vmcnt(4)
	ds_write_b128 v176, v[60:63] offset:24576
	s_waitcnt vmcnt(3)
	ds_write_b128 v176, v[40:43] offset:28672
	ds_write_b128 v176, v[56:59] offset:32768
	s_waitcnt vmcnt(2)
	ds_write_b128 v176, v[32:35] offset:36864
	s_waitcnt vmcnt(1)
	ds_write_b128 v176, v[16:19] offset:40960
	s_waitcnt vmcnt(0)
	ds_write_b128 v176, v[8:11] offset:45056
	s_waitcnt lgkmcnt(0)
	s_barrier
	ds_read_b128 v[8:11], v185
	ds_read_b128 v[16:19], v185 offset:2048
	ds_read_b128 v[32:35], v185 offset:4096
	ds_read_b128 v[40:43], v185 offset:6144
	ds_read_b128 v[56:59], v185 offset:8192
	ds_read_b128 v[60:63], v185 offset:10240
	ds_read_b128 v[68:71], v185 offset:12288
	ds_read_b128 v[80:83], v185 offset:14336
	ds_read_b128 v[88:91], v184 offset:32768
	ds_read_b128 v[104:107], v184 offset:34816
	ds_read_b128 v[112:115], v184 offset:36864
	ds_read_b128 v[116:119], v184 offset:38912
	s_waitcnt lgkmcnt(3)
	v_mfma_f32_16x16x32_bf16 v[172:175], v[88:91], v[8:11], v[172:175]
	s_waitcnt lgkmcnt(2)
	v_mfma_f32_16x16x32_bf16 v[168:171], v[104:107], v[8:11], v[168:171]
	s_waitcnt lgkmcnt(1)
	v_mfma_f32_16x16x32_bf16 v[164:167], v[112:115], v[8:11], v[164:167]
	s_waitcnt lgkmcnt(0)
	v_mfma_f32_16x16x32_bf16 v[8:11], v[116:119], v[8:11], v[160:163]
	v_mfma_f32_16x16x32_bf16 v[156:159], v[88:91], v[16:19], v[156:159]
	v_mfma_f32_16x16x32_bf16 v[152:155], v[104:107], v[16:19], v[152:155]
	v_mfma_f32_16x16x32_bf16 v[148:151], v[112:115], v[16:19], v[148:151]
	v_mfma_f32_16x16x32_bf16 v[16:19], v[116:119], v[16:19], v[144:147]
	v_mfma_f32_16x16x32_bf16 v[136:139], v[88:91], v[32:35], v[136:139]
	v_mfma_f32_16x16x32_bf16 v[132:135], v[104:107], v[32:35], v[132:135]
	v_mfma_f32_16x16x32_bf16 v[128:131], v[112:115], v[32:35], v[128:131]
	v_mfma_f32_16x16x32_bf16 v[32:35], v[116:119], v[32:35], v[124:127]
	v_mfma_f32_16x16x32_bf16 v[120:123], v[88:91], v[40:43], v[120:123]
	v_mfma_f32_16x16x32_bf16 v[108:111], v[104:107], v[40:43], v[108:111]
	v_mfma_f32_16x16x32_bf16 v[100:103], v[112:115], v[40:43], v[100:103]
	v_mfma_f32_16x16x32_bf16 v[40:43], v[116:119], v[40:43], v[96:99]
	v_mfma_f32_16x16x32_bf16 v[92:95], v[88:91], v[56:59], v[92:95]
	v_mfma_f32_16x16x32_bf16 v[84:87], v[104:107], v[56:59], v[84:87]
	v_mfma_f32_16x16x32_bf16 v[76:79], v[112:115], v[56:59], v[76:79]
	v_mfma_f32_16x16x32_bf16 v[56:59], v[116:119], v[56:59], v[72:75]
	v_mfma_f32_16x16x32_bf16 v[64:67], v[88:91], v[60:63], v[64:67]
	v_mfma_f32_16x16x32_bf16 v[52:55], v[104:107], v[60:63], v[52:55]
	v_mfma_f32_16x16x32_bf16 v[72:75], v[112:115], v[60:63], v[48:51]
	v_mfma_f32_16x16x32_bf16 v[60:63], v[116:119], v[60:63], v[44:47]
	v_mfma_f32_16x16x32_bf16 v[96:99], v[88:91], v[68:71], v[36:39]
	v_mfma_f32_16x16x32_bf16 v[28:31], v[104:107], v[68:71], v[28:31]
	v_mfma_f32_16x16x32_bf16 v[124:127], v[112:115], v[68:71], v[24:27]
	v_mfma_f32_16x16x32_bf16 v[20:23], v[116:119], v[68:71], v[20:23]
	v_mfma_f32_16x16x32_bf16 v[12:15], v[88:91], v[80:83], v[12:15]
	v_mfma_f32_16x16x32_bf16 v[4:7], v[104:107], v[80:83], v[4:7]
	v_mfma_f32_16x16x32_bf16 v[0:3], v[112:115], v[80:83], v[0:3]
	v_mfma_f32_16x16x32_bf16 v[68:71], v[116:119], v[80:83], v[140:143]
	ds_read_b128 v[24:27], v183
	ds_read_b128 v[36:39], v183 offset:2048
	ds_read_b128 v[44:47], v183 offset:4096
	ds_read_b128 v[80:83], v183 offset:6144
	ds_read_b128 v[88:91], v183 offset:8192
	ds_read_b128 v[104:107], v183 offset:10240
	ds_read_b128 v[112:115], v183 offset:12288
	ds_read_b128 v[116:119], v183 offset:14336
	ds_read_b128 v[140:143], v182 offset:32768
	ds_read_b128 v[144:147], v182 offset:34816
	ds_read_b128 v[160:163], v182 offset:36864
	ds_read_b128 v[178:181], v182 offset:38912
	s_waitcnt lgkmcnt(3)
	v_mfma_f32_16x16x32_bf16 v[172:175], v[140:143], v[24:27], v[172:175]
	v_mov_b32_e32 v49, v188
	v_cmp_lt_i32_e32 vcc, v189, v202
	s_waitcnt lgkmcnt(2)
	v_mfma_f32_16x16x32_bf16 v[168:171], v[144:147], v[24:27], v[168:171]
	v_mov_b32_e32 v48, v188
	v_readlane_b32 s8, v253, 24
	s_waitcnt lgkmcnt(1)
	v_mfma_f32_16x16x32_bf16 v[164:167], v[160:163], v[24:27], v[164:167]
	v_and_b32_e32 v50, 0xffffff80, v48
	v_add_u32_e32 v51, s11, v50
	v_and_or_b32 v50, v48, 64, s12
	s_waitcnt lgkmcnt(0)
	v_mfma_f32_16x16x32_bf16 v[8:11], v[178:181], v[24:27], v[8:11]
	v_bfe_u32 v26, v49, 4, 1
	v_cndmask_b32_e32 v24, v203, v189, vcc
	v_cmp_eq_u32_e32 vcc, 0, v26
	v_lshlrev_b32_e32 v186, 2, v24
	v_mfma_f32_16x16x32_bf16 v[182:185], v[178:181], v[36:39], v[16:19]
	v_and_or_b32 v48, v49, 15, v51
	v_ashrrev_i32_e32 v51, 31, v50
	v_lshl_add_u64 v[50:51], v[50:51], 1, s[6:7]
	v_cndmask_b32_e32 v16, v172, v168, vcc
	v_cndmask_b32_e32 v17, v173, v169, vcc
	v_cndmask_b32_e32 v18, v174, v170, vcc
	v_cndmask_b32_e32 v19, v175, v171, vcc
	ds_bpermute_b32 v16, v186, v16
	ds_bpermute_b32 v17, v186, v17
	ds_bpermute_b32 v18, v186, v18
	ds_bpermute_b32 v19, v186, v19
	v_lshlrev_b32_e32 v176, 5, v26
	v_lshrrev_b32_e32 v27, 1, v49
	v_lshl_add_u64 v[24:25], v[50:51], 0, v[176:177]
	v_and_b32_e32 v176, 16, v27
	v_ashrrev_i32_e32 v49, 31, v48
	v_mfma_f32_16x16x32_bf16 v[156:159], v[140:143], v[36:39], v[156:159]
	v_lshl_add_u64 v[50:51], v[24:25], 0, v[176:177]
	v_lshlrev_b64 v[24:25], 11, v[48:49]
	s_waitcnt lgkmcnt(3)
	v_cndmask_b32_e32 v26, v16, v172, vcc
	v_mfma_f32_16x16x32_bf16 v[152:155], v[144:147], v[36:39], v[152:155]
	v_cndmask_b32_e32 v27, v168, v16, vcc
	s_waitcnt lgkmcnt(2)
	v_cndmask_b32_e32 v16, v17, v173, vcc
	v_lshl_add_u64 v[24:25], v[50:51], 0, v[24:25]
	v_mfma_f32_16x16x32_bf16 v[148:151], v[160:163], v[36:39], v[148:151]
	v_cndmask_b32_e32 v36, v169, v17, vcc
	s_waitcnt lgkmcnt(1)
	v_cndmask_b32_e32 v17, v18, v174, vcc
	v_cvt_pk_bf16_f32 v16, v26, v16
	v_mfma_f32_16x16x32_bf16 v[190:193], v[178:181], v[44:47], v[32:35]
	v_readlane_b32 s9, v253, 25
	s_nop 1
	v_cndmask_b32_e32 v32, v170, v18, vcc
	s_waitcnt lgkmcnt(0)
	v_cndmask_b32_e32 v18, v19, v175, vcc
	v_cndmask_b32_e32 v19, v171, v19, vcc
	v_cvt_pk_bf16_f32 v17, v17, v18
	v_cvt_pk_bf16_f32 v18, v27, v36
	v_cvt_pk_bf16_f32 v19, v32, v19
	global_store_dwordx4 v[24:25], v[16:19], off
	v_mfma_f32_16x16x32_bf16 v[120:123], v[140:143], v[80:83], v[120:123]
	s_nop 0
	v_cndmask_b32_e32 v16, v164, v8, vcc
	v_cndmask_b32_e32 v17, v165, v9, vcc
	v_cndmask_b32_e32 v18, v166, v10, vcc
	v_cndmask_b32_e32 v19, v167, v11, vcc
	ds_bpermute_b32 v16, v186, v16
	ds_bpermute_b32 v17, v186, v17
	ds_bpermute_b32 v18, v186, v18
	ds_bpermute_b32 v19, v186, v19
	v_mfma_f32_16x16x32_bf16 v[108:111], v[144:147], v[80:83], v[108:111]
	s_waitcnt lgkmcnt(3)
	v_cndmask_b32_e32 v26, v16, v164, vcc
	v_cndmask_b32_e32 v16, v8, v16, vcc
	s_waitcnt lgkmcnt(2)
	v_cndmask_b32_e32 v8, v17, v165, vcc
	v_cndmask_b32_e32 v17, v9, v17, vcc
	s_waitcnt lgkmcnt(1)
	v_cndmask_b32_e32 v9, v18, v166, vcc
	v_cndmask_b32_e32 v18, v10, v18, vcc
	s_waitcnt lgkmcnt(0)
	v_cndmask_b32_e32 v10, v19, v167, vcc
	v_cndmask_b32_e32 v11, v11, v19, vcc
	v_cvt_pk_bf16_f32 v8, v26, v8
	v_cvt_pk_bf16_f32 v9, v9, v10
	v_cvt_pk_bf16_f32 v10, v16, v17
	v_cvt_pk_bf16_f32 v11, v18, v11
	global_store_dwordx4 v[24:25], v[8:11], off offset:64
	v_mfma_f32_16x16x32_bf16 v[100:103], v[160:163], v[80:83], v[100:103]
	s_nop 0
	v_or_b32_e32 v8, 16, v48
	v_ashrrev_i32_e32 v9, 31, v8
	v_lshlrev_b64 v[8:9], 11, v[8:9]
	v_mfma_f32_16x16x32_bf16 v[80:83], v[178:181], v[80:83], v[40:43]
	v_cndmask_b32_e32 v10, v158, v154, vcc
	v_cndmask_b32_e32 v11, v159, v155, vcc
	ds_bpermute_b32 v10, v186, v10
	v_mfma_f32_16x16x32_bf16 v[40:43], v[140:143], v[104:107], v[64:67]
	ds_bpermute_b32 v11, v186, v11
	s_nop 1
	v_lshl_add_u64 v[64:65], v[50:51], 0, v[8:9]
	v_cndmask_b32_e32 v8, v156, v152, vcc
	v_cndmask_b32_e32 v9, v157, v153, vcc
	ds_bpermute_b32 v8, v186, v8
	ds_bpermute_b32 v9, v186, v9
	v_mfma_f32_16x16x32_bf16 v[136:139], v[140:143], v[44:47], v[136:139]
	s_waitcnt lgkmcnt(1)
	v_cndmask_b32_e32 v49, v8, v156, vcc
	v_mfma_f32_16x16x32_bf16 v[132:135], v[144:147], v[44:47], v[132:135]
	v_mfma_f32_16x16x32_bf16 v[128:131], v[160:163], v[44:47], v[128:131]
	v_mfma_f32_16x16x32_bf16 v[44:47], v[144:147], v[104:107], v[52:55]
	v_mfma_f32_16x16x32_bf16 v[36:39], v[178:181], v[104:107], v[60:63]
	s_nop 1
	v_cndmask_b32_e32 v54, v152, v8, vcc
	s_waitcnt lgkmcnt(0)
	v_cndmask_b32_e32 v8, v9, v157, vcc
	v_cndmask_b32_e32 v55, v153, v9, vcc
	v_cndmask_b32_e32 v53, v10, v158, vcc
	v_cndmask_b32_e32 v60, v154, v10, vcc
	v_cndmask_b32_e32 v61, v11, v159, vcc
	v_cndmask_b32_e32 v62, v155, v11, vcc
	v_cvt_pk_bf16_f32 v52, v49, v8
	v_cvt_pk_bf16_f32 v53, v53, v61
	v_cvt_pk_bf16_f32 v54, v54, v55
	v_cvt_pk_bf16_f32 v55, v60, v62
	v_mfma_f32_16x16x32_bf16 v[8:11], v[140:143], v[116:119], v[12:15]
	global_store_dwordx4 v[64:65], v[52:55], off
	v_cndmask_b32_e32 v49, v149, v183, vcc
	ds_bpermute_b32 v49, v186, v49
	v_mfma_f32_16x16x32_bf16 v[12:15], v[144:147], v[116:119], v[4:7]
	v_cndmask_b32_e32 v52, v150, v184, vcc
	v_cndmask_b32_e32 v53, v151, v185, vcc
	ds_bpermute_b32 v52, v186, v52
	v_cndmask_b32_e32 v4, v148, v182, vcc
	ds_bpermute_b32 v54, v186, v4
	ds_bpermute_b32 v53, v186, v53
	s_waitcnt lgkmcnt(3)
	v_cndmask_b32_e32 v60, v49, v149, vcc
	v_cndmask_b32_e32 v49, v183, v49, vcc
	s_waitcnt lgkmcnt(2)
	v_cndmask_b32_e32 v61, v52, v150, vcc
	s_waitcnt lgkmcnt(1)
	v_cndmask_b32_e32 v55, v54, v148, vcc
	v_cndmask_b32_e32 v54, v182, v54, vcc
	v_cndmask_b32_e32 v62, v184, v52, vcc
	s_waitcnt lgkmcnt(0)
	v_cndmask_b32_e32 v63, v53, v151, vcc
	v_cndmask_b32_e32 v66, v185, v53, vcc
	v_cvt_pk_bf16_f32 v52, v55, v60
	v_cvt_pk_bf16_f32 v53, v61, v63
	v_cvt_pk_bf16_f32 v54, v54, v49
	v_cvt_pk_bf16_f32 v55, v62, v66
	global_store_dwordx4 v[64:65], v[52:55], off offset:64
	v_cndmask_b32_e32 v49, v136, v132, vcc
	ds_bpermute_b32 v49, v186, v49
	v_or_b32_e32 v52, 32, v48
	v_ashrrev_i32_e32 v53, 31, v52
	v_lshlrev_b64 v[52:53], 11, v[52:53]
	v_lshl_add_u64 v[60:61], v[50:51], 0, v[52:53]
	v_cndmask_b32_e32 v52, v137, v133, vcc
	v_cndmask_b32_e32 v53, v138, v134, vcc
	v_cndmask_b32_e32 v54, v139, v135, vcc
	ds_bpermute_b32 v52, v186, v52
	ds_bpermute_b32 v53, v186, v53
	ds_bpermute_b32 v54, v186, v54
	s_waitcnt lgkmcnt(3)
	v_cndmask_b32_e32 v55, v49, v136, vcc
	v_cndmask_b32_e32 v49, v132, v49, vcc
	s_waitcnt lgkmcnt(2)
	v_cndmask_b32_e32 v62, v52, v137, vcc
	v_cndmask_b32_e32 v63, v133, v52, vcc
	s_waitcnt lgkmcnt(1)
	v_cndmask_b32_e32 v64, v53, v138, vcc
	v_cndmask_b32_e32 v65, v134, v53, vcc
	s_waitcnt lgkmcnt(0)
	v_cndmask_b32_e32 v53, v54, v139, vcc
	v_cndmask_b32_e32 v66, v135, v54, vcc
	v_cvt_pk_bf16_f32 v52, v55, v62
	v_cvt_pk_bf16_f32 v53, v64, v53
	v_cvt_pk_bf16_f32 v54, v49, v63
	v_cvt_pk_bf16_f32 v55, v65, v66
	global_store_dwordx4 v[60:61], v[52:55], off
	v_cndmask_b32_e32 v49, v128, v190, vcc
	ds_bpermute_b32 v49, v186, v49
	v_cndmask_b32_e32 v52, v129, v191, vcc
	v_cndmask_b32_e32 v53, v130, v192, vcc
	v_cndmask_b32_e32 v54, v131, v193, vcc
	ds_bpermute_b32 v52, v186, v52
	ds_bpermute_b32 v53, v186, v53
	ds_bpermute_b32 v54, v186, v54
	s_waitcnt lgkmcnt(3)
	v_cndmask_b32_e32 v55, v49, v128, vcc
	v_cndmask_b32_e32 v49, v190, v49, vcc
	s_waitcnt lgkmcnt(2)
	v_cndmask_b32_e32 v62, v52, v129, vcc
	v_cndmask_b32_e32 v63, v191, v52, vcc
	s_waitcnt lgkmcnt(1)
	v_cndmask_b32_e32 v64, v53, v130, vcc
	v_cndmask_b32_e32 v65, v192, v53, vcc
	s_waitcnt lgkmcnt(0)
	v_cndmask_b32_e32 v53, v54, v131, vcc
	v_cndmask_b32_e32 v66, v193, v54, vcc
	v_cvt_pk_bf16_f32 v52, v55, v62
	v_cvt_pk_bf16_f32 v53, v64, v53
	v_cvt_pk_bf16_f32 v54, v49, v63
	v_cvt_pk_bf16_f32 v55, v65, v66
	global_store_dwordx4 v[60:61], v[52:55], off offset:64
	v_cndmask_b32_e32 v49, v120, v108, vcc
	ds_bpermute_b32 v49, v186, v49
	v_or_b32_e32 v52, 48, v48
	v_ashrrev_i32_e32 v53, 31, v52
	v_lshlrev_b64 v[52:53], 11, v[52:53]
	v_lshl_add_u64 v[60:61], v[50:51], 0, v[52:53]
	v_cndmask_b32_e32 v52, v121, v109, vcc
	v_cndmask_b32_e32 v53, v122, v110, vcc
	v_cndmask_b32_e32 v54, v123, v111, vcc
	ds_bpermute_b32 v52, v186, v52
	ds_bpermute_b32 v53, v186, v53
	ds_bpermute_b32 v54, v186, v54
	s_waitcnt lgkmcnt(3)
	v_cndmask_b32_e32 v55, v49, v120, vcc
	v_cndmask_b32_e32 v49, v108, v49, vcc
	s_waitcnt lgkmcnt(2)
	v_cndmask_b32_e32 v62, v52, v121, vcc
	v_cndmask_b32_e32 v63, v109, v52, vcc
	s_waitcnt lgkmcnt(1)
	v_cndmask_b32_e32 v64, v53, v122, vcc
	v_cndmask_b32_e32 v65, v110, v53, vcc
	s_waitcnt lgkmcnt(0)
	v_cndmask_b32_e32 v53, v54, v123, vcc
	v_cndmask_b32_e32 v66, v111, v54, vcc
	v_cvt_pk_bf16_f32 v52, v55, v62
	v_cvt_pk_bf16_f32 v53, v64, v53
	v_cvt_pk_bf16_f32 v54, v49, v63
	v_cvt_pk_bf16_f32 v55, v65, v66
	global_store_dwordx4 v[60:61], v[52:55], off
	v_cndmask_b32_e32 v49, v100, v80, vcc
	ds_bpermute_b32 v49, v186, v49
	v_cndmask_b32_e32 v52, v101, v81, vcc
	v_cndmask_b32_e32 v53, v102, v82, vcc
	v_cndmask_b32_e32 v54, v103, v83, vcc
	ds_bpermute_b32 v52, v186, v52
	ds_bpermute_b32 v53, v186, v53
	ds_bpermute_b32 v54, v186, v54
	s_waitcnt lgkmcnt(3)
	v_cndmask_b32_e32 v55, v49, v100, vcc
	v_cndmask_b32_e32 v49, v80, v49, vcc
	s_waitcnt lgkmcnt(2)
	v_cndmask_b32_e32 v62, v52, v101, vcc
	v_cndmask_b32_e32 v63, v81, v52, vcc
	s_waitcnt lgkmcnt(1)
	v_cndmask_b32_e32 v64, v53, v102, vcc
	v_cndmask_b32_e32 v65, v82, v53, vcc
	s_waitcnt lgkmcnt(0)
	v_cndmask_b32_e32 v53, v54, v103, vcc
	v_cndmask_b32_e32 v66, v83, v54, vcc
	v_mfma_f32_16x16x32_bf16 v[92:95], v[140:143], v[88:91], v[92:95]
	v_cvt_pk_bf16_f32 v52, v55, v62
	v_cvt_pk_bf16_f32 v53, v64, v53
	v_cvt_pk_bf16_f32 v54, v49, v63
	v_mfma_f32_16x16x32_bf16 v[84:87], v[144:147], v[88:91], v[84:87]
	v_cvt_pk_bf16_f32 v55, v65, v66
	global_store_dwordx4 v[60:61], v[52:55], off offset:64
	v_mfma_f32_16x16x32_bf16 v[76:79], v[160:163], v[88:91], v[76:79]
	s_nop 0
	v_or_b32_e32 v52, 64, v48
	v_ashrrev_i32_e32 v53, 31, v52
	v_lshlrev_b64 v[52:53], 11, v[52:53]
	v_lshl_add_u64 v[60:61], v[50:51], 0, v[52:53]
	v_cndmask_b32_e32 v49, v92, v84, vcc
	v_cndmask_b32_e32 v52, v93, v85, vcc
	v_cndmask_b32_e32 v53, v94, v86, vcc
	v_cndmask_b32_e32 v54, v95, v87, vcc
	ds_bpermute_b32 v49, v186, v49
	ds_bpermute_b32 v52, v186, v52
	ds_bpermute_b32 v53, v186, v53
	ds_bpermute_b32 v54, v186, v54
	v_mfma_f32_16x16x32_bf16 v[56:59], v[178:181], v[88:91], v[56:59]
	s_waitcnt lgkmcnt(3)
	v_cndmask_b32_e32 v55, v49, v92, vcc
	v_cndmask_b32_e32 v49, v84, v49, vcc
	s_waitcnt lgkmcnt(2)
	v_cndmask_b32_e32 v62, v52, v93, vcc
	v_cndmask_b32_e32 v63, v85, v52, vcc
	s_waitcnt lgkmcnt(1)
	v_cndmask_b32_e32 v64, v53, v94, vcc
	v_cndmask_b32_e32 v65, v86, v53, vcc
	s_waitcnt lgkmcnt(0)
	v_cndmask_b32_e32 v53, v54, v95, vcc
	v_cndmask_b32_e32 v66, v87, v54, vcc
	v_cvt_pk_bf16_f32 v52, v55, v62
	v_cvt_pk_bf16_f32 v53, v64, v53
	v_cvt_pk_bf16_f32 v54, v49, v63
	v_cvt_pk_bf16_f32 v55, v65, v66
	global_store_dwordx4 v[60:61], v[52:55], off
	v_cndmask_b32_e32 v49, v76, v56, vcc
	ds_bpermute_b32 v49, v186, v49
	v_cndmask_b32_e32 v52, v77, v57, vcc
	v_cndmask_b32_e32 v53, v78, v58, vcc
	v_cndmask_b32_e32 v54, v79, v59, vcc
	ds_bpermute_b32 v52, v186, v52
	ds_bpermute_b32 v53, v186, v53
	ds_bpermute_b32 v54, v186, v54
	s_waitcnt lgkmcnt(3)
	v_cndmask_b32_e32 v55, v49, v76, vcc
	v_cndmask_b32_e32 v49, v56, v49, vcc
	s_waitcnt lgkmcnt(2)
	v_cndmask_b32_e32 v56, v52, v77, vcc
	v_cndmask_b32_e32 v57, v57, v52, vcc
	s_waitcnt lgkmcnt(1)
	v_cndmask_b32_e32 v62, v53, v78, vcc
	v_cndmask_b32_e32 v58, v58, v53, vcc
	s_waitcnt lgkmcnt(0)
	v_cndmask_b32_e32 v53, v54, v79, vcc
	v_cndmask_b32_e32 v59, v59, v54, vcc
	v_cvt_pk_bf16_f32 v52, v55, v56
	v_cvt_pk_bf16_f32 v53, v62, v53
	v_cvt_pk_bf16_f32 v54, v49, v57
	v_cvt_pk_bf16_f32 v55, v58, v59
	global_store_dwordx4 v[60:61], v[52:55], off offset:64
	v_cndmask_b32_e32 v49, v40, v44, vcc
	v_cndmask_b32_e32 v56, v43, v47, vcc
	v_cndmask_b32_e32 v54, v41, v45, vcc
	v_cndmask_b32_e32 v55, v42, v46, vcc
	ds_bpermute_b32 v49, v186, v49
	ds_bpermute_b32 v54, v186, v54
	ds_bpermute_b32 v55, v186, v55
	ds_bpermute_b32 v56, v186, v56
	v_mfma_f32_16x16x32_bf16 v[32:35], v[160:163], v[104:107], v[72:75]
	v_or_b32_e32 v52, 0x50, v48
	v_ashrrev_i32_e32 v53, 31, v52
	v_lshlrev_b64 v[52:53], 11, v[52:53]
	s_waitcnt lgkmcnt(3)
	v_cndmask_b32_e32 v40, v49, v40, vcc
	v_cndmask_b32_e32 v44, v44, v49, vcc
	s_waitcnt lgkmcnt(2)
	v_cndmask_b32_e32 v41, v54, v41, vcc
	v_cndmask_b32_e32 v45, v45, v54, vcc
	s_waitcnt lgkmcnt(1)
	v_cndmask_b32_e32 v42, v55, v42, vcc
	v_cndmask_b32_e32 v46, v46, v55, vcc
	s_waitcnt lgkmcnt(0)
	v_cndmask_b32_e32 v43, v56, v43, vcc
	v_cndmask_b32_e32 v47, v47, v56, vcc
	v_lshl_add_u64 v[52:53], v[50:51], 0, v[52:53]
	v_cvt_pk_bf16_f32 v40, v40, v41
	v_cvt_pk_bf16_f32 v41, v42, v43
	v_cvt_pk_bf16_f32 v42, v44, v45
	v_cvt_pk_bf16_f32 v43, v46, v47
	global_store_dwordx4 v[52:53], v[40:43], off
	v_mfma_f32_16x16x32_bf16 v[24:27], v[140:143], v[112:115], v[96:99]
	s_nop 0
	v_cndmask_b32_e32 v40, v32, v36, vcc
	v_cndmask_b32_e32 v41, v33, v37, vcc
	v_cndmask_b32_e32 v42, v34, v38, vcc
	v_cndmask_b32_e32 v43, v35, v39, vcc
	ds_bpermute_b32 v40, v186, v40
	ds_bpermute_b32 v41, v186, v41
	ds_bpermute_b32 v42, v186, v42
	ds_bpermute_b32 v43, v186, v43
	v_mfma_f32_16x16x32_bf16 v[28:31], v[144:147], v[112:115], v[28:31]
	s_waitcnt lgkmcnt(3)
	v_cndmask_b32_e32 v32, v40, v32, vcc
	v_cndmask_b32_e32 v36, v36, v40, vcc
	s_waitcnt lgkmcnt(2)
	v_cndmask_b32_e32 v33, v41, v33, vcc
	v_cndmask_b32_e32 v37, v37, v41, vcc
	s_waitcnt lgkmcnt(1)
	v_cndmask_b32_e32 v34, v42, v34, vcc
	v_cndmask_b32_e32 v38, v38, v42, vcc
	s_waitcnt lgkmcnt(0)
	v_cndmask_b32_e32 v35, v43, v35, vcc
	v_cndmask_b32_e32 v39, v39, v43, vcc
	v_cvt_pk_bf16_f32 v32, v32, v33
	v_cvt_pk_bf16_f32 v33, v34, v35
	v_cvt_pk_bf16_f32 v34, v36, v37
	v_cvt_pk_bf16_f32 v35, v38, v39
	global_store_dwordx4 v[52:53], v[32:35], off offset:64
	v_cndmask_b32_e32 v36, v26, v30, vcc
	v_cndmask_b32_e32 v37, v27, v31, vcc
	v_cndmask_b32_e32 v34, v24, v28, vcc
	v_cndmask_b32_e32 v35, v25, v29, vcc
	ds_bpermute_b32 v34, v186, v34
	ds_bpermute_b32 v35, v186, v35
	ds_bpermute_b32 v36, v186, v36
	ds_bpermute_b32 v37, v186, v37
	v_mfma_f32_16x16x32_bf16 v[16:19], v[160:163], v[112:115], v[124:127]
	v_or_b32_e32 v32, 0x60, v48
	v_ashrrev_i32_e32 v33, 31, v32
	v_lshlrev_b64 v[32:33], 11, v[32:33]
	v_mfma_f32_16x16x32_bf16 v[20:23], v[178:181], v[112:115], v[20:23]
	s_waitcnt lgkmcnt(3)
	v_cndmask_b32_e32 v24, v34, v24, vcc
	v_cndmask_b32_e32 v28, v28, v34, vcc
	s_waitcnt lgkmcnt(2)
	v_cndmask_b32_e32 v25, v35, v25, vcc
	v_cndmask_b32_e32 v29, v29, v35, vcc
	s_waitcnt lgkmcnt(1)
	v_cndmask_b32_e32 v26, v36, v26, vcc
	v_cndmask_b32_e32 v30, v30, v36, vcc
	s_waitcnt lgkmcnt(0)
	v_cndmask_b32_e32 v27, v37, v27, vcc
	v_cndmask_b32_e32 v31, v31, v37, vcc
	v_lshl_add_u64 v[32:33], v[50:51], 0, v[32:33]
	v_cvt_pk_bf16_f32 v24, v24, v25
	v_cvt_pk_bf16_f32 v25, v26, v27
	v_cvt_pk_bf16_f32 v26, v28, v29
	v_cvt_pk_bf16_f32 v27, v30, v31
	global_store_dwordx4 v[32:33], v[24:27], off
	v_mfma_f32_16x16x32_bf16 v[0:3], v[160:163], v[116:119], v[0:3]
	s_nop 0
	v_cndmask_b32_e32 v24, v16, v20, vcc
	v_cndmask_b32_e32 v25, v17, v21, vcc
	v_cndmask_b32_e32 v26, v18, v22, vcc
	v_cndmask_b32_e32 v27, v19, v23, vcc
	ds_bpermute_b32 v24, v186, v24
	ds_bpermute_b32 v25, v186, v25
	ds_bpermute_b32 v26, v186, v26
	ds_bpermute_b32 v27, v186, v27
	v_mfma_f32_16x16x32_bf16 v[4:7], v[178:181], v[116:119], v[68:71]
	s_waitcnt lgkmcnt(3)
	v_cndmask_b32_e32 v16, v24, v16, vcc
	v_cndmask_b32_e32 v20, v20, v24, vcc
	s_waitcnt lgkmcnt(2)
	v_cndmask_b32_e32 v17, v25, v17, vcc
	v_cndmask_b32_e32 v21, v21, v25, vcc
	s_waitcnt lgkmcnt(1)
	v_cndmask_b32_e32 v18, v26, v18, vcc
	v_cndmask_b32_e32 v22, v22, v26, vcc
	s_waitcnt lgkmcnt(0)
	v_cndmask_b32_e32 v19, v27, v19, vcc
	v_cndmask_b32_e32 v23, v23, v27, vcc
	v_cvt_pk_bf16_f32 v16, v16, v17
	v_cvt_pk_bf16_f32 v17, v18, v19
	v_cvt_pk_bf16_f32 v18, v20, v21
	v_cvt_pk_bf16_f32 v19, v22, v23
	global_store_dwordx4 v[32:33], v[16:19], off offset:64
	v_cndmask_b32_e32 v20, v10, v14, vcc
	v_cndmask_b32_e32 v21, v11, v15, vcc
	v_cndmask_b32_e32 v18, v8, v12, vcc
	v_cndmask_b32_e32 v19, v9, v13, vcc
	ds_bpermute_b32 v18, v186, v18
	ds_bpermute_b32 v19, v186, v19
	ds_bpermute_b32 v20, v186, v20
	ds_bpermute_b32 v21, v186, v21
	v_or_b32_e32 v16, 0x70, v48
	v_ashrrev_i32_e32 v17, 31, v16
	v_lshlrev_b64 v[16:17], 11, v[16:17]
	s_waitcnt lgkmcnt(3)
	v_cndmask_b32_e32 v8, v18, v8, vcc
	v_cndmask_b32_e32 v12, v12, v18, vcc
	s_waitcnt lgkmcnt(2)
	v_cndmask_b32_e32 v9, v19, v9, vcc
	v_cndmask_b32_e32 v13, v13, v19, vcc
	s_waitcnt lgkmcnt(1)
	v_cndmask_b32_e32 v10, v20, v10, vcc
	v_cndmask_b32_e32 v14, v14, v20, vcc
	s_waitcnt lgkmcnt(0)
	v_cndmask_b32_e32 v11, v21, v11, vcc
	v_cndmask_b32_e32 v15, v15, v21, vcc
	v_lshl_add_u64 v[16:17], v[50:51], 0, v[16:17]
	v_cvt_pk_bf16_f32 v8, v8, v9
	v_cvt_pk_bf16_f32 v9, v10, v11
	v_cvt_pk_bf16_f32 v10, v12, v13
	v_cvt_pk_bf16_f32 v11, v14, v15
	global_store_dwordx4 v[16:17], v[8:11], off
	s_nop 1
	v_cndmask_b32_e32 v8, v0, v4, vcc
	v_cndmask_b32_e32 v9, v1, v5, vcc
	v_cndmask_b32_e32 v10, v2, v6, vcc
	v_cndmask_b32_e32 v11, v3, v7, vcc
	ds_bpermute_b32 v8, v186, v8
	ds_bpermute_b32 v9, v186, v9
	ds_bpermute_b32 v10, v186, v10
	ds_bpermute_b32 v11, v186, v11
	s_waitcnt lgkmcnt(3)
	v_cndmask_b32_e32 v0, v8, v0, vcc
	v_cndmask_b32_e32 v4, v4, v8, vcc
	s_waitcnt lgkmcnt(2)
	v_cndmask_b32_e32 v1, v9, v1, vcc
	v_cndmask_b32_e32 v5, v5, v9, vcc
	s_waitcnt lgkmcnt(1)
	v_cndmask_b32_e32 v2, v10, v2, vcc
	v_cndmask_b32_e32 v6, v6, v10, vcc
	s_waitcnt lgkmcnt(0)
	v_cndmask_b32_e32 v3, v11, v3, vcc
	v_cndmask_b32_e32 v7, v7, v11, vcc
	v_cvt_pk_bf16_f32 v0, v0, v1
	v_cvt_pk_bf16_f32 v1, v2, v3
	v_cvt_pk_bf16_f32 v2, v4, v5
	v_cvt_pk_bf16_f32 v3, v6, v7
	global_store_dwordx4 v[16:17], v[0:3], off offset:64
	s_load_dword s8, s[8:9], 0x0
	s_waitcnt lgkmcnt(0)
	s_add_i32 s10, s8, s10
	s_cmpk_gt_i32 s10, 0xff
	s_cbranch_scc0 .LBB0_146

.LBB0_400:
	s_waitcnt lgkmcnt(0)
	s_barrier
	ds_read_b128 v[224:227], v184
	ds_read_b128 v[228:231], v184 offset:1024
	ds_read_b128 v[232:235], v184 offset:2048
	ds_read_b128 v[236:239], v184 offset:3072
	ds_read_b128 v[190:193], v185
	ds_read_b128 v[194:197], v185 offset:1024
	ds_read_b128 v[198:201], v185 offset:2048
	ds_read_b128 v[204:207], v185 offset:3072
	ds_read_b128 v[208:211], v185 offset:4096
	ds_read_b128 v[212:215], v185 offset:5120
	ds_read_b128 v[216:219], v185 offset:6144
	ds_read_b128 v[220:223], v185 offset:7168
	s_movk_i32 vcc_lo, 0x6000
	s_cmp_eq_u32 m0, 2
	s_cselect_b32 vcc_lo, 0xffff4000, vcc_lo
	s_add_u32 m0, m0, 1
	s_cmp_eq_u32 m0, 3
	s_cselect_b32 m0, 0, m0
	v_add_u32_e32 v185, vcc_lo, v185
	v_add_u32_e32 v184, vcc_lo, v184
	v_xor_b32_e32 v185, 64, v185
	v_xor_b32_e32 v184, 64, v184
	s_waitcnt lgkmcnt(7)
	v_mfma_f32_16x16x32_bf16 v[172:175], v[224:227], v[190:193], v[172:175]
	v_mfma_f32_16x16x32_bf16 v[164:167], v[228:231], v[190:193], v[164:167]
	v_mfma_f32_16x16x32_bf16 v[156:159], v[232:235], v[190:193], v[156:159]
	v_mfma_f32_16x16x32_bf16 v[144:147], v[236:239], v[190:193], v[144:147]
	ds_read_b128 v[190:193], v185
	s_waitcnt lgkmcnt(7)
	v_mfma_f32_16x16x32_bf16 v[140:143], v[224:227], v[194:197], v[140:143]
	v_mfma_f32_16x16x32_bf16 v[128:131], v[228:231], v[194:197], v[128:131]
	v_mfma_f32_16x16x32_bf16 v[124:127], v[232:235], v[194:197], v[124:127]
	v_mfma_f32_16x16x32_bf16 v[116:119], v[236:239], v[194:197], v[116:119]
	ds_read_b128 v[194:197], v185 offset:1024
	s_waitcnt lgkmcnt(7)
	v_mfma_f32_16x16x32_bf16 v[104:107], v[224:227], v[198:201], v[104:107]
	v_mfma_f32_16x16x32_bf16 v[100:103], v[228:231], v[198:201], v[100:103]
	v_mfma_f32_16x16x32_bf16 v[92:95], v[232:235], v[198:201], v[92:95]
	v_mfma_f32_16x16x32_bf16 v[84:87], v[236:239], v[198:201], v[84:87]
	ds_read_b128 v[198:201], v185 offset:2048
	s_waitcnt lgkmcnt(7)
	v_mfma_f32_16x16x32_bf16 v[80:83], v[224:227], v[204:207], v[80:83]
	v_mfma_f32_16x16x32_bf16 v[76:79], v[228:231], v[204:207], v[76:79]
	v_mfma_f32_16x16x32_bf16 v[64:67], v[232:235], v[204:207], v[64:67]
	v_mfma_f32_16x16x32_bf16 v[60:63], v[236:239], v[204:207], v[60:63]
	ds_read_b128 v[204:207], v185 offset:3072
	s_waitcnt lgkmcnt(7)
	v_mfma_f32_16x16x32_bf16 v[56:59], v[224:227], v[208:211], v[56:59]
	v_mfma_f32_16x16x32_bf16 v[52:55], v[228:231], v[208:211], v[52:55]
	v_mfma_f32_16x16x32_bf16 v[48:51], v[232:235], v[208:211], v[48:51]
	v_mfma_f32_16x16x32_bf16 v[44:47], v[236:239], v[208:211], v[44:47]
	ds_read_b128 v[208:211], v185 offset:4096
	s_waitcnt lgkmcnt(7)
	v_mfma_f32_16x16x32_bf16 v[40:43], v[224:227], v[212:215], v[40:43]
	v_mfma_f32_16x16x32_bf16 v[36:39], v[228:231], v[212:215], v[36:39]
	v_mfma_f32_16x16x32_bf16 v[32:35], v[232:235], v[212:215], v[32:35]
	v_mfma_f32_16x16x32_bf16 v[28:31], v[236:239], v[212:215], v[28:31]
	ds_read_b128 v[212:215], v185 offset:5120
	s_waitcnt lgkmcnt(7)
	v_mfma_f32_16x16x32_bf16 v[24:27], v[224:227], v[216:219], v[24:27]
	v_mfma_f32_16x16x32_bf16 v[20:23], v[228:231], v[216:219], v[20:23]
	v_mfma_f32_16x16x32_bf16 v[16:19], v[232:235], v[216:219], v[16:19]
	v_mfma_f32_16x16x32_bf16 v[12:15], v[236:239], v[216:219], v[12:15]
	ds_read_b128 v[216:219], v185 offset:6144
	s_waitcnt lgkmcnt(7)
	v_mfma_f32_16x16x32_bf16 v[8:11], v[224:227], v[220:223], v[8:11]
	v_mfma_f32_16x16x32_bf16 v[4:7], v[228:231], v[220:223], v[4:7]
	v_mfma_f32_16x16x32_bf16 v[0:3], v[232:235], v[220:223], v[0:3]
	v_mfma_f32_16x16x32_bf16 v[112:115], v[236:239], v[220:223], v[112:115]
	ds_read_b128 v[220:223], v185 offset:7168
	ds_read_b128 v[224:227], v184
	ds_read_b128 v[228:231], v184 offset:1024
	ds_read_b128 v[232:235], v184 offset:2048
	ds_read_b128 v[236:239], v184 offset:3072
	s_movk_i32 vcc_lo, 0x6000
	s_cmp_eq_u32 m0, 2
	s_cselect_b32 vcc_lo, 0xffff4000, vcc_lo
	s_add_u32 m0, m0, 1
	s_cmp_eq_u32 m0, 3
	s_cselect_b32 m0, 0, m0
	v_add_u32_e32 v185, vcc_lo, v185
	v_add_u32_e32 v184, vcc_lo, v184
	v_xor_b32_e32 v185, 64, v185
	v_xor_b32_e32 v184, 64, v184
	s_sub_u32 vcc_lo, s0, s98
	v_add_u32_e32 v186, vcc_lo, v178
	v_add_u32_e32 v187, vcc_lo, v180
	s_barrier
	s_waitcnt lgkmcnt(0)
	v_mfma_f32_16x16x32_bf16 v[172:175], v[224:227], v[190:193], v[172:175]
	s_waitcnt vmcnt(11)
	v_mfma_f32_16x16x32_bf16 v[164:167], v[228:231], v[190:193], v[164:167]
	ds_write_b128 v183, v[168:171]
	v_add_u32_e32 v168, 0xa700000, v186
	v_mfma_f32_16x16x32_bf16 v[156:159], v[232:235], v[190:193], v[156:159]
	global_load_dwordx4 v[168:171], v168, s[98:99] offset:128
	v_mfma_f32_16x16x32_bf16 v[144:147], v[236:239], v[190:193], v[144:147]
	s_waitcnt vmcnt(11)
	ds_write_b128 v183, v[160:163] offset:2048
	v_mfma_f32_16x16x32_bf16 v[140:143], v[224:227], v[194:197], v[140:143]
	v_add_u32_e32 v160, 0xa706000, v186
	v_mfma_f32_16x16x32_bf16 v[128:131], v[228:231], v[194:197], v[128:131]
	global_load_dwordx4 v[160:163], v160, s[98:99] offset:128
	s_waitcnt vmcnt(11)
	v_mfma_f32_16x16x32_bf16 v[124:127], v[232:235], v[194:197], v[124:127]
	ds_write_b128 v183, v[152:155] offset:4096
	v_mfma_f32_16x16x32_bf16 v[116:119], v[236:239], v[194:197], v[116:119]
	v_add_u32_e32 v152, 0xa70c000, v186
	global_load_dwordx4 v[152:155], v152, s[98:99] offset:128
	v_mfma_f32_16x16x32_bf16 v[104:107], v[224:227], v[198:201], v[104:107]
	s_waitcnt vmcnt(11)
	v_mfma_f32_16x16x32_bf16 v[100:103], v[228:231], v[198:201], v[100:103]
	ds_write_b128 v183, v[136:139] offset:6144
	v_add_u32_e32 v136, 0xa712000, v186
	v_mfma_f32_16x16x32_bf16 v[92:95], v[232:235], v[198:201], v[92:95]
	global_load_dwordx4 v[136:139], v136, s[98:99] offset:128
	v_mfma_f32_16x16x32_bf16 v[84:87], v[236:239], v[198:201], v[84:87]
	s_waitcnt vmcnt(11)
	ds_write_b128 v183, v[132:135] offset:8192
	v_mfma_f32_16x16x32_bf16 v[80:83], v[224:227], v[204:207], v[80:83]
	v_add_u32_e32 v132, 0xa718000, v186
	v_mfma_f32_16x16x32_bf16 v[76:79], v[228:231], v[204:207], v[76:79]
	global_load_dwordx4 v[132:135], v132, s[98:99] offset:128
	s_waitcnt vmcnt(11)
	v_mfma_f32_16x16x32_bf16 v[64:67], v[232:235], v[204:207], v[64:67]
	ds_write_b128 v183, v[120:123] offset:10240
	v_mfma_f32_16x16x32_bf16 v[60:63], v[236:239], v[204:207], v[60:63]
	v_add_u32_e32 v120, 0xa71e000, v186
	global_load_dwordx4 v[120:123], v120, s[98:99] offset:128
	v_mfma_f32_16x16x32_bf16 v[56:59], v[224:227], v[208:211], v[56:59]
	s_waitcnt vmcnt(11)
	v_mfma_f32_16x16x32_bf16 v[52:55], v[228:231], v[208:211], v[52:55]
	ds_write_b128 v183, v[108:111] offset:12288
	v_add_u32_e32 v108, 0xa724000, v186
	v_mfma_f32_16x16x32_bf16 v[48:51], v[232:235], v[208:211], v[48:51]
	global_load_dwordx4 v[108:111], v108, s[98:99] offset:128
	v_mfma_f32_16x16x32_bf16 v[44:47], v[236:239], v[208:211], v[44:47]
	s_waitcnt vmcnt(11)
	ds_write_b128 v183, v[96:99] offset:14336
	v_mfma_f32_16x16x32_bf16 v[40:43], v[224:227], v[212:215], v[40:43]
	v_add_u32_e32 v96, 0xa72a000, v186
	v_mfma_f32_16x16x32_bf16 v[36:39], v[228:231], v[212:215], v[36:39]
	global_load_dwordx4 v[96:99], v96, s[98:99] offset:128
	s_waitcnt vmcnt(11)
	v_mfma_f32_16x16x32_bf16 v[32:35], v[232:235], v[212:215], v[32:35]
	ds_write_b128 v183, v[148:151] offset:16384
	v_mfma_f32_16x16x32_bf16 v[28:31], v[236:239], v[212:215], v[28:31]
	v_add_u32_e32 v148, 0x1f00000, v187
	global_load_dwordx4 v[148:151], v148, s[98:99] offset:128
	v_mfma_f32_16x16x32_bf16 v[24:27], v[224:227], v[216:219], v[24:27]
	s_waitcnt vmcnt(11)
	v_mfma_f32_16x16x32_bf16 v[20:23], v[228:231], v[216:219], v[20:23]
	ds_write_b128 v183, v[88:91] offset:18432
	v_add_u32_e32 v88, 0x1f06000, v187
	v_mfma_f32_16x16x32_bf16 v[16:19], v[232:235], v[216:219], v[16:19]
	global_load_dwordx4 v[88:91], v88, s[98:99] offset:128
	v_mfma_f32_16x16x32_bf16 v[12:15], v[236:239], v[216:219], v[12:15]
	s_waitcnt vmcnt(11)
	ds_write_b128 v183, v[72:75] offset:20480
	v_mfma_f32_16x16x32_bf16 v[8:11], v[224:227], v[220:223], v[8:11]
	v_add_u32_e32 v72, 0x1f0c000, v187
	v_mfma_f32_16x16x32_bf16 v[4:7], v[228:231], v[220:223], v[4:7]
	global_load_dwordx4 v[72:75], v72, s[98:99] offset:128
	s_waitcnt vmcnt(11)
	v_mfma_f32_16x16x32_bf16 v[0:3], v[232:235], v[220:223], v[0:3]
	ds_write_b128 v183, v[68:71] offset:22528
	v_mfma_f32_16x16x32_bf16 v[112:115], v[236:239], v[220:223], v[112:115]
	v_add_u32_e32 v68, 0x1f12000, v187
	global_load_dwordx4 v[68:71], v68, s[98:99] offset:128
	v_cmp_gt_u32_e32 vcc, 0x6000, v183
	v_add_u32_e32 v182, 0xc000, v183
	v_add_u32_e32 v183, 0xffffa000, v183
	s_nop 0
	v_cndmask_b32_e32 v183, v183, v182, vcc
	s_add_u32 s0, s0, 0x80
	s_addc_u32 s1, s1, 0
	s_cmpk_lg_i32 s0, 0x280
	s_cbranch_scc1 .LBB0_400
	s_waitcnt lgkmcnt(0)
	s_barrier
	ds_read_b128 v[224:227], v184
	ds_read_b128 v[228:231], v184 offset:1024
	ds_read_b128 v[232:235], v184 offset:2048
	ds_read_b128 v[236:239], v184 offset:3072
	ds_read_b128 v[190:193], v185
	ds_read_b128 v[194:197], v185 offset:1024
	ds_read_b128 v[198:201], v185 offset:2048
	ds_read_b128 v[204:207], v185 offset:3072
	ds_read_b128 v[208:211], v185 offset:4096
	ds_read_b128 v[212:215], v185 offset:5120
	ds_read_b128 v[216:219], v185 offset:6144
	ds_read_b128 v[220:223], v185 offset:7168
	s_movk_i32 vcc_lo, 0x6000
	s_cmp_eq_u32 m0, 2
	s_cselect_b32 vcc_lo, 0xffff4000, vcc_lo
	s_add_u32 m0, m0, 1
	s_cmp_eq_u32 m0, 3
	s_cselect_b32 m0, 0, m0
	v_add_u32_e32 v185, vcc_lo, v185
	v_add_u32_e32 v184, vcc_lo, v184
	v_xor_b32_e32 v185, 64, v185
	v_xor_b32_e32 v184, 64, v184
	s_waitcnt lgkmcnt(7)
	v_mfma_f32_16x16x32_bf16 v[172:175], v[224:227], v[190:193], v[172:175]
	v_mfma_f32_16x16x32_bf16 v[164:167], v[228:231], v[190:193], v[164:167]
	v_mfma_f32_16x16x32_bf16 v[156:159], v[232:235], v[190:193], v[156:159]
	v_mfma_f32_16x16x32_bf16 v[144:147], v[236:239], v[190:193], v[144:147]
	ds_read_b128 v[190:193], v185
	s_waitcnt lgkmcnt(7)
	v_mfma_f32_16x16x32_bf16 v[140:143], v[224:227], v[194:197], v[140:143]
	v_mfma_f32_16x16x32_bf16 v[128:131], v[228:231], v[194:197], v[128:131]
	v_mfma_f32_16x16x32_bf16 v[124:127], v[232:235], v[194:197], v[124:127]
	v_mfma_f32_16x16x32_bf16 v[116:119], v[236:239], v[194:197], v[116:119]
	ds_read_b128 v[194:197], v185 offset:1024
	s_waitcnt lgkmcnt(7)
	v_mfma_f32_16x16x32_bf16 v[104:107], v[224:227], v[198:201], v[104:107]
	v_mfma_f32_16x16x32_bf16 v[100:103], v[228:231], v[198:201], v[100:103]
	v_mfma_f32_16x16x32_bf16 v[92:95], v[232:235], v[198:201], v[92:95]
	v_mfma_f32_16x16x32_bf16 v[84:87], v[236:239], v[198:201], v[84:87]
	ds_read_b128 v[198:201], v185 offset:2048
	s_waitcnt lgkmcnt(7)
	v_mfma_f32_16x16x32_bf16 v[80:83], v[224:227], v[204:207], v[80:83]
	v_mfma_f32_16x16x32_bf16 v[76:79], v[228:231], v[204:207], v[76:79]
	v_mfma_f32_16x16x32_bf16 v[64:67], v[232:235], v[204:207], v[64:67]
	v_mfma_f32_16x16x32_bf16 v[60:63], v[236:239], v[204:207], v[60:63]
	ds_read_b128 v[204:207], v185 offset:3072
	s_waitcnt lgkmcnt(7)
	v_mfma_f32_16x16x32_bf16 v[56:59], v[224:227], v[208:211], v[56:59]
	v_mfma_f32_16x16x32_bf16 v[52:55], v[228:231], v[208:211], v[52:55]
	v_mfma_f32_16x16x32_bf16 v[48:51], v[232:235], v[208:211], v[48:51]
	v_mfma_f32_16x16x32_bf16 v[44:47], v[236:239], v[208:211], v[44:47]
	ds_read_b128 v[208:211], v185 offset:4096
	s_waitcnt lgkmcnt(7)
	v_mfma_f32_16x16x32_bf16 v[40:43], v[224:227], v[212:215], v[40:43]
	v_mfma_f32_16x16x32_bf16 v[36:39], v[228:231], v[212:215], v[36:39]
	v_mfma_f32_16x16x32_bf16 v[32:35], v[232:235], v[212:215], v[32:35]
	v_mfma_f32_16x16x32_bf16 v[28:31], v[236:239], v[212:215], v[28:31]
	ds_read_b128 v[212:215], v185 offset:5120
	s_waitcnt lgkmcnt(7)
	v_mfma_f32_16x16x32_bf16 v[24:27], v[224:227], v[216:219], v[24:27]
	v_mfma_f32_16x16x32_bf16 v[20:23], v[228:231], v[216:219], v[20:23]
	v_mfma_f32_16x16x32_bf16 v[16:19], v[232:235], v[216:219], v[16:19]
	v_mfma_f32_16x16x32_bf16 v[12:15], v[236:239], v[216:219], v[12:15]
	ds_read_b128 v[216:219], v185 offset:6144
	s_waitcnt lgkmcnt(7)
	v_mfma_f32_16x16x32_bf16 v[8:11], v[224:227], v[220:223], v[8:11]
	v_mfma_f32_16x16x32_bf16 v[4:7], v[228:231], v[220:223], v[4:7]
	v_mfma_f32_16x16x32_bf16 v[0:3], v[232:235], v[220:223], v[0:3]
	v_mfma_f32_16x16x32_bf16 v[112:115], v[236:239], v[220:223], v[112:115]
	ds_read_b128 v[220:223], v185 offset:7168
	ds_read_b128 v[224:227], v184
	ds_read_b128 v[228:231], v184 offset:1024
	ds_read_b128 v[232:235], v184 offset:2048
	ds_read_b128 v[236:239], v184 offset:3072
	s_movk_i32 vcc_lo, 0x6000
	s_cmp_eq_u32 m0, 2
	s_cselect_b32 vcc_lo, 0xffff4000, vcc_lo
	s_add_u32 m0, m0, 1
	s_cmp_eq_u32 m0, 3
	s_cselect_b32 m0, 0, m0
	v_add_u32_e32 v185, vcc_lo, v185
	v_add_u32_e32 v184, vcc_lo, v184
	v_xor_b32_e32 v185, 64, v185
	v_xor_b32_e32 v184, 64, v184
	s_waitcnt lgkmcnt(0)
	v_mfma_f32_16x16x32_bf16 v[172:175], v[224:227], v[190:193], v[172:175]
	v_mfma_f32_16x16x32_bf16 v[164:167], v[228:231], v[190:193], v[164:167]
	v_mfma_f32_16x16x32_bf16 v[156:159], v[232:235], v[190:193], v[156:159]
	v_mfma_f32_16x16x32_bf16 v[144:147], v[236:239], v[190:193], v[144:147]
	v_mfma_f32_16x16x32_bf16 v[140:143], v[224:227], v[194:197], v[140:143]
	v_mfma_f32_16x16x32_bf16 v[128:131], v[228:231], v[194:197], v[128:131]
	v_mfma_f32_16x16x32_bf16 v[124:127], v[232:235], v[194:197], v[124:127]
	v_mfma_f32_16x16x32_bf16 v[116:119], v[236:239], v[194:197], v[116:119]
	v_mfma_f32_16x16x32_bf16 v[104:107], v[224:227], v[198:201], v[104:107]
	v_mfma_f32_16x16x32_bf16 v[100:103], v[228:231], v[198:201], v[100:103]
	v_mfma_f32_16x16x32_bf16 v[92:95], v[232:235], v[198:201], v[92:95]
	v_mfma_f32_16x16x32_bf16 v[84:87], v[236:239], v[198:201], v[84:87]
	v_mfma_f32_16x16x32_bf16 v[80:83], v[224:227], v[204:207], v[80:83]
	v_mfma_f32_16x16x32_bf16 v[76:79], v[228:231], v[204:207], v[76:79]
	v_mfma_f32_16x16x32_bf16 v[64:67], v[232:235], v[204:207], v[64:67]
	v_mfma_f32_16x16x32_bf16 v[60:63], v[236:239], v[204:207], v[60:63]
	v_mfma_f32_16x16x32_bf16 v[56:59], v[224:227], v[208:211], v[56:59]
	v_mfma_f32_16x16x32_bf16 v[52:55], v[228:231], v[208:211], v[52:55]
	v_mfma_f32_16x16x32_bf16 v[48:51], v[232:235], v[208:211], v[48:51]
	v_mfma_f32_16x16x32_bf16 v[44:47], v[236:239], v[208:211], v[44:47]
	v_mfma_f32_16x16x32_bf16 v[40:43], v[224:227], v[212:215], v[40:43]
	v_mfma_f32_16x16x32_bf16 v[36:39], v[228:231], v[212:215], v[36:39]
	v_mfma_f32_16x16x32_bf16 v[32:35], v[232:235], v[212:215], v[32:35]
	v_mfma_f32_16x16x32_bf16 v[28:31], v[236:239], v[212:215], v[28:31]
	v_mfma_f32_16x16x32_bf16 v[24:27], v[224:227], v[216:219], v[24:27]
	v_mfma_f32_16x16x32_bf16 v[20:23], v[228:231], v[216:219], v[20:23]
	v_mfma_f32_16x16x32_bf16 v[16:19], v[232:235], v[216:219], v[16:19]
	v_mfma_f32_16x16x32_bf16 v[12:15], v[236:239], v[216:219], v[12:15]
	v_mfma_f32_16x16x32_bf16 v[8:11], v[224:227], v[220:223], v[8:11]
	v_mfma_f32_16x16x32_bf16 v[4:7], v[228:231], v[220:223], v[4:7]
	v_mfma_f32_16x16x32_bf16 v[0:3], v[232:235], v[220:223], v[0:3]
	v_mfma_f32_16x16x32_bf16 v[112:115], v[236:239], v[220:223], v[112:115]
	v_lshrrev_b32_e32 v224, 4, v188
	v_and_b32_e32 v225, 7, v188
	v_bitop3_b32 v226, v224, v225, 3 bitop3:0x6c
	v_lshlrev_b32_e32 v227, 7, v188
	v_bfe_u32 v228, v188, 4, 2
	v_and_b32_e32 v229, 0xffffc780, v227
	v_and_b32_e32 v227, 0x2780, v227
	v_bitop3_b32 v228, v228, v225, 4 bitop3:0x36
	v_lshlrev_b32_e32 v226, 4, v226
	v_lshlrev_b32_e32 v228, 4, v228
	v_or_b32_e32 v185, v229, v226
	v_or_b32_e32 v184, v227, v226
	v_or_b32_e32 v183, v229, v228
	v_or_b32_e32 v182, v227, v228
	s_waitcnt vmcnt(0)
	s_barrier
	s_waitcnt vmcnt(11)
	ds_write_b128 v176, v[168:171]
	s_waitcnt vmcnt(10)
	ds_write_b128 v176, v[160:163] offset:4096
	s_waitcnt vmcnt(9)
	ds_write_b128 v176, v[152:155] offset:8192
	s_waitcnt vmcnt(8)
	ds_write_b128 v176, v[136:139] offset:12288
	s_waitcnt vmcnt(7)
	ds_write_b128 v176, v[132:135] offset:16384
	s_waitcnt vmcnt(6)
	ds_write_b128 v176, v[120:123] offset:20480
	s_waitcnt vmcnt(5)
	ds_write_b128 v176, v[108:111] offset:24576
	s_waitcnt vmcnt(4)
	ds_write_b128 v176, v[96:99] offset:28672
	s_waitcnt vmcnt(3)
	ds_write_b128 v176, v[148:151] offset:32768
	s_waitcnt vmcnt(2)
	ds_write_b128 v176, v[88:91] offset:36864
	s_waitcnt vmcnt(1)
	ds_write_b128 v176, v[72:75] offset:40960
	s_waitcnt vmcnt(0)
	ds_write_b128 v176, v[68:71] offset:45056
	s_waitcnt lgkmcnt(0)
	s_barrier
	ds_read_b128 v[68:71], v185
	ds_read_b128 v[72:75], v185 offset:2048
	ds_read_b128 v[88:91], v185 offset:4096
	ds_read_b128 v[96:99], v185 offset:6144
	ds_read_b128 v[108:111], v185 offset:8192
	ds_read_b128 v[120:123], v185 offset:10240
	ds_read_b128 v[132:135], v185 offset:12288
	ds_read_b128 v[136:139], v185 offset:14336
	ds_read_b128 v[148:151], v184 offset:32768
	ds_read_b128 v[152:155], v184 offset:34816
	ds_read_b128 v[160:163], v184 offset:36864
	ds_read_b128 v[168:171], v184 offset:38912
	s_waitcnt lgkmcnt(3)
	v_mfma_f32_16x16x32_bf16 v[172:175], v[148:151], v[68:71], v[172:175]
	s_waitcnt lgkmcnt(2)
	v_mfma_f32_16x16x32_bf16 v[164:167], v[152:155], v[68:71], v[164:167]
	s_waitcnt lgkmcnt(1)
	v_mfma_f32_16x16x32_bf16 v[156:159], v[160:163], v[68:71], v[156:159]
	s_waitcnt lgkmcnt(0)
	v_mfma_f32_16x16x32_bf16 v[68:71], v[168:171], v[68:71], v[144:147]
	v_mfma_f32_16x16x32_bf16 v[140:143], v[148:151], v[72:75], v[140:143]
	v_mfma_f32_16x16x32_bf16 v[128:131], v[152:155], v[72:75], v[128:131]
	v_mfma_f32_16x16x32_bf16 v[144:147], v[160:163], v[72:75], v[124:127]
	v_mfma_f32_16x16x32_bf16 v[72:75], v[168:171], v[72:75], v[116:119]
	v_mfma_f32_16x16x32_bf16 v[64:67], v[160:163], v[96:99], v[64:67]
	v_mfma_f32_16x16x32_bf16 v[60:63], v[168:171], v[96:99], v[60:63]
	v_mfma_f32_16x16x32_bf16 v[56:59], v[148:151], v[108:111], v[56:59]
	v_mfma_f32_16x16x32_bf16 v[52:55], v[152:155], v[108:111], v[52:55]
	v_mfma_f32_16x16x32_bf16 v[48:51], v[160:163], v[108:111], v[48:51]
	v_mfma_f32_16x16x32_bf16 v[44:47], v[168:171], v[108:111], v[44:47]
	v_mfma_f32_16x16x32_bf16 v[40:43], v[148:151], v[120:123], v[40:43]
	v_mfma_f32_16x16x32_bf16 v[36:39], v[152:155], v[120:123], v[36:39]
	v_mfma_f32_16x16x32_bf16 v[32:35], v[160:163], v[120:123], v[32:35]
	v_mfma_f32_16x16x32_bf16 v[28:31], v[168:171], v[120:123], v[28:31]
	v_mfma_f32_16x16x32_bf16 v[24:27], v[148:151], v[132:135], v[24:27]
	v_mfma_f32_16x16x32_bf16 v[20:23], v[152:155], v[132:135], v[20:23]
	v_mfma_f32_16x16x32_bf16 v[16:19], v[160:163], v[132:135], v[16:19]
	v_mfma_f32_16x16x32_bf16 v[12:15], v[168:171], v[132:135], v[12:15]
	v_mfma_f32_16x16x32_bf16 v[8:11], v[148:151], v[136:139], v[8:11]
	v_mfma_f32_16x16x32_bf16 v[4:7], v[152:155], v[136:139], v[4:7]
	v_mfma_f32_16x16x32_bf16 v[0:3], v[160:163], v[136:139], v[0:3]
	v_mfma_f32_16x16x32_bf16 v[178:181], v[148:151], v[88:91], v[104:107]
	v_mfma_f32_16x16x32_bf16 v[184:187], v[152:155], v[88:91], v[100:103]
	v_mfma_f32_16x16x32_bf16 v[190:193], v[160:163], v[88:91], v[92:95]
	v_mfma_f32_16x16x32_bf16 v[194:197], v[168:171], v[88:91], v[84:87]
	v_mfma_f32_16x16x32_bf16 v[198:201], v[148:151], v[96:99], v[80:83]
	v_mfma_f32_16x16x32_bf16 v[204:207], v[152:155], v[96:99], v[76:79]
	v_mfma_f32_16x16x32_bf16 v[148:151], v[168:171], v[136:139], v[112:115]
	s_nop 1
	ds_read_b128 v[76:79], v183
	ds_read_b128 v[80:83], v183 offset:2048
	ds_read_b128 v[132:135], v183 offset:4096
	ds_read_b128 v[136:139], v183 offset:6144
	ds_read_b128 v[152:155], v183 offset:8192
	ds_read_b128 v[160:163], v183 offset:10240
	ds_read_b128 v[168:171], v183 offset:12288
	ds_read_b128 v[208:211], v183 offset:14336
	ds_read_b128 v[212:215], v182 offset:32768
	ds_read_b128 v[216:219], v182 offset:34816
	ds_read_b128 v[220:223], v182 offset:36864
	ds_read_b128 v[224:227], v182 offset:38912
	s_waitcnt lgkmcnt(3)
	v_mfma_f32_16x16x32_bf16 v[124:127], v[212:215], v[76:79], v[172:175]
	s_movk_i32 s0, 0xfff
	s_waitcnt lgkmcnt(2)
	v_mfma_f32_16x16x32_bf16 v[120:123], v[216:219], v[76:79], v[164:167]
	s_waitcnt lgkmcnt(1)
	v_mfma_f32_16x16x32_bf16 v[116:119], v[220:223], v[76:79], v[156:159]
	s_waitcnt lgkmcnt(0)
	v_mfma_f32_16x16x32_bf16 v[112:115], v[224:227], v[76:79], v[68:71]
	v_mfma_f32_16x16x32_bf16 v[108:111], v[212:215], v[80:83], v[140:143]
	v_mfma_f32_16x16x32_bf16 v[104:107], v[216:219], v[80:83], v[128:131]
	v_mfma_f32_16x16x32_bf16 v[100:103], v[220:223], v[80:83], v[144:147]
	v_mfma_f32_16x16x32_bf16 v[96:99], v[224:227], v[80:83], v[72:75]
	v_mfma_f32_16x16x32_bf16 v[92:95], v[212:215], v[132:135], v[178:181]
	v_mfma_f32_16x16x32_bf16 v[88:91], v[216:219], v[132:135], v[184:187]
	v_mfma_f32_16x16x32_bf16 v[84:87], v[220:223], v[132:135], v[190:193]
	v_mfma_f32_16x16x32_bf16 v[80:83], v[224:227], v[132:135], v[194:197]
	v_mov_b32_e32 v132, v188
	v_mfma_f32_16x16x32_bf16 v[76:79], v[212:215], v[136:139], v[198:201]
	v_mfma_f32_16x16x32_bf16 v[72:75], v[216:219], v[136:139], v[204:207]
	v_mfma_f32_16x16x32_bf16 v[68:71], v[220:223], v[136:139], v[64:67]
	v_mfma_f32_16x16x32_bf16 v[64:67], v[224:227], v[136:139], v[60:63]
	v_mov_b32_e32 v137, v188
	v_mfma_f32_16x16x32_bf16 v[60:63], v[212:215], v[152:155], v[56:59]
	v_and_b32_e32 v143, 15, v137
	v_and_or_b32 v136, v132, 64, s8
	v_and_b32_e32 v176, 48, v137
	v_mfma_f32_16x16x32_bf16 v[56:59], v[216:219], v[152:155], v[52:55]
	v_mfma_f32_16x16x32_bf16 v[52:55], v[220:223], v[152:155], v[48:51]
	v_mfma_f32_16x16x32_bf16 v[48:51], v[224:227], v[152:155], v[44:47]
	v_mfma_f32_16x16x32_bf16 v[44:47], v[212:215], v[160:163], v[40:43]
	v_mfma_f32_16x16x32_bf16 v[40:43], v[216:219], v[160:163], v[36:39]
	v_mfma_f32_16x16x32_bf16 v[36:39], v[224:227], v[160:163], v[28:31]
	s_nop 2
	v_and_b32_e32 v28, 0xffffff80, v132
	v_add_u32_e32 v144, s9, v28
	v_or_b32_e32 v145, v144, v143
	v_mfma_f32_16x16x32_bf16 v[28:31], v[216:219], v[168:171], v[20:23]
	v_cmp_lt_i32_e32 vcc, s0, v144
	s_mov_b32 s0, 0x2aaaaaab
	v_and_b32_e32 v142, 0x380, v144
	v_lshlrev_b32_e32 v20, 3, v145
	v_ashrrev_i32_e32 v21, 31, v20
	v_lshl_add_u64 v[128:129], v[20:21], 2, s[4:5]
	global_load_dwordx2 v[138:139], v[128:129], off offset:16
	s_nop 0
	global_load_dwordx4 v[128:131], v[128:129], off
	v_mfma_f32_16x16x32_bf16 v[20:23], v[220:223], v[168:171], v[16:19]
	v_mfma_f32_16x16x32_bf16 v[16:19], v[224:227], v[168:171], v[12:15]
	s_nop 2
	v_mul_hi_i32 v12, v136, s0
	v_lshrrev_b32_e32 v13, 31, v12
	v_lshrrev_b32_e32 v12, 5, v12
	v_add_u32_e32 v132, v12, v13
	s_movk_i32 s0, 0xc0
	v_mfma_f32_16x16x32_bf16 v[12:15], v[216:219], v[208:211], v[4:7]
	s_nop 2
	v_mul_lo_u32 v4, v132, s0
	v_sub_u32_e32 v4, v136, v4
	v_cmp_eq_u32_e64 s[0:1], s19, v4
	s_and_b64 s[40:41], s[0:1], vcc
	v_readlane_b32 s0, v255, 45
	v_mfma_f32_16x16x32_bf16 v[32:35], v[220:223], v[160:163], v[32:35]
	v_readlane_b32 s1, v255, 46
	v_mfma_f32_16x16x32_bf16 v[24:27], v[212:215], v[168:171], v[24:27]
	s_nop 0
	v_lshl_add_u64 v[134:135], s[0:1], 0, v[176:177]
	v_readlane_b32 s0, v255, 47
	v_readlane_b32 s1, v255, 48
	v_mfma_f32_16x16x32_bf16 v[8:11], v[212:215], v[208:211], v[8:11]
	s_nop 0
	v_lshl_add_u64 v[132:133], s[0:1], 0, v[176:177]
	v_mfma_f32_16x16x32_bf16 v[0:3], v[220:223], v[208:211], v[0:3]
	v_mfma_f32_16x16x32_bf16 v[4:7], v[224:227], v[208:211], v[148:151]
	s_and_saveexec_b64 s[0:1], s[40:41]
	s_cbranch_execz .LBB0_403
	v_or_b32_e32 v140, v142, v143
	v_lshlrev_b32_e32 v176, 7, v140
	v_lshl_add_u64 v[154:155], v[134:135], 0, v[176:177]
	v_lshl_add_u64 v[156:157], v[132:133], 0, v[176:177]
	global_load_dwordx4 v[146:149], v[154:155], off
	global_load_dwordx4 v[150:153], v[156:157], off
	s_waitcnt vmcnt(0)
	v_pk_mul_f32 v[158:159], v[124:125], v[150:151]
	v_pk_mul_f32 v[140:141], v[116:117], v[150:151]
	v_mul_f32_e32 v150, v126, v148
	v_mul_f32_e32 v160, v118, v152
	v_mul_f32_e32 v162, v126, v152
	v_mul_f32_e32 v148, v118, v148
	v_mov_b32_e32 v118, v127
	v_mov_b32_e32 v152, v149
	v_mov_b32_e32 v126, v119
	v_pk_mul_f32 v[164:165], v[118:119], v[152:153]
	v_pk_mul_f32 v[118:119], v[126:127], v[152:153]
	v_mov_b32_e32 v151, v164
	v_mov_b32_e32 v161, v165
	v_mov_b32_e32 v149, v118
	v_mov_b32_e32 v163, v119
	v_pk_fma_f32 v[124:125], v[124:125], v[146:147], v[140:141] neg_lo:[0,0,1] neg_hi:[0,0,1]
	v_pk_add_f32 v[140:141], v[150:151], v[160:161] neg_lo:[0,1] neg_hi:[0,1]
	v_pk_fma_f32 v[116:117], v[116:117], v[146:147], v[158:159]
	v_pk_add_f32 v[118:119], v[148:149], v[162:163]
	global_load_dwordx4 v[146:149], v[154:155], off offset:64
	global_load_dwordx4 v[150:153], v[156:157], off offset:64
	s_waitcnt vmcnt(1)
	v_mul_f32_e32 v154, v122, v148
	s_waitcnt vmcnt(0)
	v_mul_f32_e32 v156, v114, v152
	v_mul_f32_e32 v158, v122, v152
	v_mul_f32_e32 v148, v114, v148
	v_mov_b32_e32 v114, v123
	v_mov_b32_e32 v152, v149
	v_pk_mul_f32 v[160:161], v[114:115], v[152:153]
	v_mov_b32_e32 v122, v115
	v_pk_mul_f32 v[126:127], v[120:121], v[150:151]
	v_pk_mul_f32 v[150:151], v[112:113], v[150:151]
	v_mov_b32_e32 v155, v160
	v_mov_b32_e32 v157, v161
	v_pk_mul_f32 v[114:115], v[122:123], v[152:153]
	v_pk_fma_f32 v[120:121], v[120:121], v[146:147], v[150:151] neg_lo:[0,0,1] neg_hi:[0,0,1]
	v_pk_add_f32 v[150:151], v[154:155], v[156:157] neg_lo:[0,1] neg_hi:[0,1]
	v_mov_b32_e32 v149, v114
	v_mov_b32_e32 v159, v115
	v_pk_fma_f32 v[112:113], v[112:113], v[146:147], v[126:127]
	v_pk_add_f32 v[114:115], v[148:149], v[158:159]
	v_mov_b32_e32 v122, v150
	v_mov_b32_e32 v123, v151
	v_mov_b32_e32 v126, v140
	v_mov_b32_e32 v127, v141

.LBB0_424:
	s_waitcnt lgkmcnt(0)
	s_barrier
	ds_read_b128 v[224:227], v184
	ds_read_b128 v[228:231], v184 offset:1024
	ds_read_b128 v[232:235], v184 offset:2048
	ds_read_b128 v[236:239], v184 offset:3072
	ds_read_b128 v[190:193], v185
	ds_read_b128 v[194:197], v185 offset:1024
	ds_read_b128 v[198:201], v185 offset:2048
	ds_read_b128 v[204:207], v185 offset:3072
	ds_read_b128 v[208:211], v185 offset:4096
	ds_read_b128 v[212:215], v185 offset:5120
	ds_read_b128 v[216:219], v185 offset:6144
	ds_read_b128 v[220:223], v185 offset:7168
	s_movk_i32 vcc_lo, 0x6000
	s_cmp_eq_u32 m0, 2
	s_cselect_b32 vcc_lo, 0xffff4000, vcc_lo
	s_add_u32 m0, m0, 1
	s_cmp_eq_u32 m0, 3
	s_cselect_b32 m0, 0, m0
	v_add_u32_e32 v185, vcc_lo, v185
	v_add_u32_e32 v184, vcc_lo, v184
	v_xor_b32_e32 v185, 64, v185
	v_xor_b32_e32 v184, 64, v184
	s_waitcnt lgkmcnt(7)
	v_mfma_f32_16x16x32_bf16 v[172:175], v[190:193], v[224:227], v[172:175]
	v_mfma_f32_16x16x32_bf16 v[168:171], v[190:193], v[228:231], v[168:171]
	v_mfma_f32_16x16x32_bf16 v[164:167], v[190:193], v[232:235], v[164:167]
	v_mfma_f32_16x16x32_bf16 v[160:163], v[190:193], v[236:239], v[160:163]
	ds_read_b128 v[190:193], v185
	s_waitcnt lgkmcnt(7)
	v_mfma_f32_16x16x32_bf16 v[156:159], v[194:197], v[224:227], v[156:159]
	v_mfma_f32_16x16x32_bf16 v[152:155], v[194:197], v[228:231], v[152:155]
	v_mfma_f32_16x16x32_bf16 v[148:151], v[194:197], v[232:235], v[148:151]
	v_mfma_f32_16x16x32_bf16 v[144:147], v[194:197], v[236:239], v[144:147]
	ds_read_b128 v[194:197], v185 offset:1024
	s_waitcnt lgkmcnt(7)
	v_mfma_f32_16x16x32_bf16 v[136:139], v[198:201], v[224:227], v[136:139]
	v_mfma_f32_16x16x32_bf16 v[132:135], v[198:201], v[228:231], v[132:135]
	v_mfma_f32_16x16x32_bf16 v[128:131], v[198:201], v[232:235], v[128:131]
	v_mfma_f32_16x16x32_bf16 v[124:127], v[198:201], v[236:239], v[124:127]
	ds_read_b128 v[198:201], v185 offset:2048
	s_waitcnt lgkmcnt(7)
	v_mfma_f32_16x16x32_bf16 v[120:123], v[204:207], v[224:227], v[120:123]
	v_mfma_f32_16x16x32_bf16 v[108:111], v[204:207], v[228:231], v[108:111]
	v_mfma_f32_16x16x32_bf16 v[100:103], v[204:207], v[232:235], v[100:103]
	v_mfma_f32_16x16x32_bf16 v[96:99], v[204:207], v[236:239], v[96:99]
	ds_read_b128 v[204:207], v185 offset:3072
	s_waitcnt lgkmcnt(7)
	v_mfma_f32_16x16x32_bf16 v[88:91], v[208:211], v[224:227], v[88:91]
	v_mfma_f32_16x16x32_bf16 v[80:83], v[208:211], v[228:231], v[80:83]
	v_mfma_f32_16x16x32_bf16 v[76:79], v[208:211], v[232:235], v[76:79]
	v_mfma_f32_16x16x32_bf16 v[64:67], v[208:211], v[236:239], v[64:67]
	ds_read_b128 v[208:211], v185 offset:4096
	s_waitcnt lgkmcnt(7)
	v_mfma_f32_16x16x32_bf16 v[60:63], v[212:215], v[224:227], v[60:63]
	v_mfma_f32_16x16x32_bf16 v[52:55], v[212:215], v[228:231], v[52:55]
	v_mfma_f32_16x16x32_bf16 v[44:47], v[212:215], v[232:235], v[44:47]
	v_mfma_f32_16x16x32_bf16 v[36:39], v[212:215], v[236:239], v[36:39]
	ds_read_b128 v[212:215], v185 offset:5120
	s_waitcnt lgkmcnt(7)
	v_mfma_f32_16x16x32_bf16 v[32:35], v[216:219], v[224:227], v[32:35]
	v_mfma_f32_16x16x32_bf16 v[28:31], v[216:219], v[228:231], v[28:31]
	v_mfma_f32_16x16x32_bf16 v[16:19], v[216:219], v[232:235], v[16:19]
	v_mfma_f32_16x16x32_bf16 v[12:15], v[216:219], v[236:239], v[12:15]
	ds_read_b128 v[216:219], v185 offset:6144
	s_waitcnt lgkmcnt(7)
	v_mfma_f32_16x16x32_bf16 v[8:11], v[220:223], v[224:227], v[8:11]
	v_mfma_f32_16x16x32_bf16 v[4:7], v[220:223], v[228:231], v[4:7]
	v_mfma_f32_16x16x32_bf16 v[0:3], v[220:223], v[232:235], v[0:3]
	v_mfma_f32_16x16x32_bf16 v[140:143], v[220:223], v[236:239], v[140:143]
	ds_read_b128 v[220:223], v185 offset:7168
	ds_read_b128 v[224:227], v184
	ds_read_b128 v[228:231], v184 offset:1024
	ds_read_b128 v[232:235], v184 offset:2048
	ds_read_b128 v[236:239], v184 offset:3072
	s_movk_i32 vcc_lo, 0x6000
	s_cmp_eq_u32 m0, 2
	s_cselect_b32 vcc_lo, 0xffff4000, vcc_lo
	s_add_u32 m0, m0, 1
	s_cmp_eq_u32 m0, 3
	s_cselect_b32 m0, 0, m0
	v_add_u32_e32 v185, vcc_lo, v185
	v_add_u32_e32 v184, vcc_lo, v184
	v_xor_b32_e32 v185, 64, v185
	v_xor_b32_e32 v184, 64, v184
	s_sub_u32 vcc_lo, s30, s98
	v_add_u32_e32 v186, vcc_lo, v178
	v_add_u32_e32 v187, vcc_lo, v180
	s_barrier
	s_waitcnt lgkmcnt(0)
	v_mfma_f32_16x16x32_bf16 v[172:175], v[190:193], v[224:227], v[172:175]
	s_waitcnt vmcnt(11)
	v_mfma_f32_16x16x32_bf16 v[168:171], v[190:193], v[228:231], v[168:171]
	ds_write_b128 v183, v[116:119]
	v_add_u32_e32 v116, s15, v187
	v_mfma_f32_16x16x32_bf16 v[164:167], v[190:193], v[232:235], v[164:167]
	global_load_dwordx4 v[116:119], v116, s[98:99] offset:128
	v_mfma_f32_16x16x32_bf16 v[160:163], v[190:193], v[236:239], v[160:163]
	s_waitcnt vmcnt(11)
	ds_write_b128 v183, v[112:115] offset:2048
	v_mfma_f32_16x16x32_bf16 v[156:159], v[194:197], v[224:227], v[156:159]
	v_add_u32_e32 v112, s17, v187
	v_mfma_f32_16x16x32_bf16 v[152:155], v[194:197], v[228:231], v[152:155]
	global_load_dwordx4 v[112:115], v112, s[98:99] offset:128
	s_waitcnt vmcnt(11)
	v_mfma_f32_16x16x32_bf16 v[148:151], v[194:197], v[232:235], v[148:151]
	ds_write_b128 v183, v[104:107] offset:4096
	v_mfma_f32_16x16x32_bf16 v[144:147], v[194:197], v[236:239], v[144:147]
	v_add_u32_e32 v104, s52, v187
	global_load_dwordx4 v[104:107], v104, s[98:99] offset:128
	v_mfma_f32_16x16x32_bf16 v[136:139], v[198:201], v[224:227], v[136:139]
	s_waitcnt vmcnt(11)
	v_mfma_f32_16x16x32_bf16 v[132:135], v[198:201], v[228:231], v[132:135]
	ds_write_b128 v183, v[92:95] offset:6144
	v_add_u32_e32 v92, s53, v187
	v_mfma_f32_16x16x32_bf16 v[128:131], v[198:201], v[232:235], v[128:131]
	global_load_dwordx4 v[92:95], v92, s[98:99] offset:128
	v_mfma_f32_16x16x32_bf16 v[124:127], v[198:201], v[236:239], v[124:127]
	s_waitcnt vmcnt(11)
	ds_write_b128 v183, v[84:87] offset:8192
	v_mfma_f32_16x16x32_bf16 v[120:123], v[204:207], v[224:227], v[120:123]
	v_add_u32_e32 v84, s10, v187
	v_mfma_f32_16x16x32_bf16 v[108:111], v[204:207], v[228:231], v[108:111]
	global_load_dwordx4 v[84:87], v84, s[98:99] offset:128
	s_waitcnt vmcnt(11)
	v_mfma_f32_16x16x32_bf16 v[100:103], v[204:207], v[232:235], v[100:103]
	ds_write_b128 v183, v[72:75] offset:10240
	v_mfma_f32_16x16x32_bf16 v[96:99], v[204:207], v[236:239], v[96:99]
	v_add_u32_e32 v72, s11, v187
	global_load_dwordx4 v[72:75], v72, s[98:99] offset:128
	v_mfma_f32_16x16x32_bf16 v[88:91], v[208:211], v[224:227], v[88:91]
	s_waitcnt vmcnt(11)
	v_mfma_f32_16x16x32_bf16 v[80:83], v[208:211], v[228:231], v[80:83]
	ds_write_b128 v183, v[68:71] offset:12288
	v_add_u32_e32 v68, s12, v187
	v_mfma_f32_16x16x32_bf16 v[76:79], v[208:211], v[232:235], v[76:79]
	global_load_dwordx4 v[68:71], v68, s[98:99] offset:128
	v_mfma_f32_16x16x32_bf16 v[64:67], v[208:211], v[236:239], v[64:67]
	s_waitcnt vmcnt(11)
	ds_write_b128 v183, v[48:51] offset:14336
	v_mfma_f32_16x16x32_bf16 v[60:63], v[212:215], v[224:227], v[60:63]
	v_add_u32_e32 v48, s13, v187
	v_mfma_f32_16x16x32_bf16 v[52:55], v[212:215], v[228:231], v[52:55]
	global_load_dwordx4 v[48:51], v48, s[98:99] offset:128
	s_waitcnt vmcnt(11)
	v_mfma_f32_16x16x32_bf16 v[44:47], v[212:215], v[232:235], v[44:47]
	ds_write_b128 v183, v[56:59] offset:16384
	v_mfma_f32_16x16x32_bf16 v[36:39], v[212:215], v[236:239], v[36:39]
	v_mov_b32_e32 v56, v186
	global_load_dwordx4 v[56:59], v56, s[98:99] offset:128
	v_mfma_f32_16x16x32_bf16 v[32:35], v[216:219], v[224:227], v[32:35]
	s_waitcnt vmcnt(11)
	v_mfma_f32_16x16x32_bf16 v[28:31], v[216:219], v[228:231], v[28:31]
	ds_write_b128 v183, v[40:43] offset:18432
	v_add_u32_e32 v40, s16, v186
	v_mfma_f32_16x16x32_bf16 v[16:19], v[216:219], v[232:235], v[16:19]
	global_load_dwordx4 v[40:43], v40, s[98:99] offset:128
	v_mfma_f32_16x16x32_bf16 v[12:15], v[216:219], v[236:239], v[12:15]
	s_waitcnt vmcnt(11)
	ds_write_b128 v183, v[24:27] offset:20480
	v_mfma_f32_16x16x32_bf16 v[8:11], v[220:223], v[224:227], v[8:11]
	v_add_u32_e32 v24, s95, v186
	v_mfma_f32_16x16x32_bf16 v[4:7], v[220:223], v[228:231], v[4:7]
	global_load_dwordx4 v[24:27], v24, s[98:99] offset:128
	s_waitcnt vmcnt(11)
	v_mfma_f32_16x16x32_bf16 v[0:3], v[220:223], v[232:235], v[0:3]
	ds_write_b128 v183, v[20:23] offset:22528
	v_mfma_f32_16x16x32_bf16 v[140:143], v[220:223], v[236:239], v[140:143]
	v_add_u32_e32 v20, s28, v186
	global_load_dwordx4 v[20:23], v20, s[98:99] offset:128
	v_cmp_gt_u32_e32 vcc, 0x6000, v183
	v_add_u32_e32 v182, 0xc000, v183
	v_add_u32_e32 v183, 0xffffa000, v183
	s_nop 0
	v_cndmask_b32_e32 v183, v183, v182, vcc
	s_add_u32 s30, s30, 0x80
	s_addc_u32 s31, s31, 0
	s_cmpk_eq_i32 s30, 0x180
	s_cbranch_scc0 .LBB0_424
	s_waitcnt lgkmcnt(0)
	s_barrier
	ds_read_b128 v[224:227], v184
	ds_read_b128 v[228:231], v184 offset:1024
	ds_read_b128 v[232:235], v184 offset:2048
	ds_read_b128 v[236:239], v184 offset:3072
	ds_read_b128 v[190:193], v185
	ds_read_b128 v[194:197], v185 offset:1024
	ds_read_b128 v[198:201], v185 offset:2048
	ds_read_b128 v[204:207], v185 offset:3072
	ds_read_b128 v[208:211], v185 offset:4096
	ds_read_b128 v[212:215], v185 offset:5120
	ds_read_b128 v[216:219], v185 offset:6144
	ds_read_b128 v[220:223], v185 offset:7168
	s_movk_i32 vcc_lo, 0x6000
	s_cmp_eq_u32 m0, 2
	s_cselect_b32 vcc_lo, 0xffff4000, vcc_lo
	s_add_u32 m0, m0, 1
	s_cmp_eq_u32 m0, 3
	s_cselect_b32 m0, 0, m0
	v_add_u32_e32 v185, vcc_lo, v185
	v_add_u32_e32 v184, vcc_lo, v184
	v_xor_b32_e32 v185, 64, v185
	v_xor_b32_e32 v184, 64, v184
	s_waitcnt lgkmcnt(7)
	v_mfma_f32_16x16x32_bf16 v[172:175], v[190:193], v[224:227], v[172:175]
	v_mfma_f32_16x16x32_bf16 v[168:171], v[190:193], v[228:231], v[168:171]
	v_mfma_f32_16x16x32_bf16 v[164:167], v[190:193], v[232:235], v[164:167]
	v_mfma_f32_16x16x32_bf16 v[160:163], v[190:193], v[236:239], v[160:163]
	ds_read_b128 v[190:193], v185
	s_waitcnt lgkmcnt(7)
	v_mfma_f32_16x16x32_bf16 v[156:159], v[194:197], v[224:227], v[156:159]
	v_mfma_f32_16x16x32_bf16 v[152:155], v[194:197], v[228:231], v[152:155]
	v_mfma_f32_16x16x32_bf16 v[148:151], v[194:197], v[232:235], v[148:151]
	v_mfma_f32_16x16x32_bf16 v[144:147], v[194:197], v[236:239], v[144:147]
	ds_read_b128 v[194:197], v185 offset:1024
	s_waitcnt lgkmcnt(7)
	v_mfma_f32_16x16x32_bf16 v[136:139], v[198:201], v[224:227], v[136:139]
	v_mfma_f32_16x16x32_bf16 v[132:135], v[198:201], v[228:231], v[132:135]
	v_mfma_f32_16x16x32_bf16 v[128:131], v[198:201], v[232:235], v[128:131]
	v_mfma_f32_16x16x32_bf16 v[124:127], v[198:201], v[236:239], v[124:127]
	ds_read_b128 v[198:201], v185 offset:2048
	s_waitcnt lgkmcnt(7)
	v_mfma_f32_16x16x32_bf16 v[120:123], v[204:207], v[224:227], v[120:123]
	v_mfma_f32_16x16x32_bf16 v[108:111], v[204:207], v[228:231], v[108:111]
	v_mfma_f32_16x16x32_bf16 v[100:103], v[204:207], v[232:235], v[100:103]
	v_mfma_f32_16x16x32_bf16 v[96:99], v[204:207], v[236:239], v[96:99]
	ds_read_b128 v[204:207], v185 offset:3072
	s_waitcnt lgkmcnt(7)
	v_mfma_f32_16x16x32_bf16 v[88:91], v[208:211], v[224:227], v[88:91]
	v_mfma_f32_16x16x32_bf16 v[80:83], v[208:211], v[228:231], v[80:83]
	v_mfma_f32_16x16x32_bf16 v[76:79], v[208:211], v[232:235], v[76:79]
	v_mfma_f32_16x16x32_bf16 v[64:67], v[208:211], v[236:239], v[64:67]
	ds_read_b128 v[208:211], v185 offset:4096
	s_waitcnt lgkmcnt(7)
	v_mfma_f32_16x16x32_bf16 v[60:63], v[212:215], v[224:227], v[60:63]
	v_mfma_f32_16x16x32_bf16 v[52:55], v[212:215], v[228:231], v[52:55]
	v_mfma_f32_16x16x32_bf16 v[44:47], v[212:215], v[232:235], v[44:47]
	v_mfma_f32_16x16x32_bf16 v[36:39], v[212:215], v[236:239], v[36:39]
	ds_read_b128 v[212:215], v185 offset:5120
	s_waitcnt lgkmcnt(7)
	v_mfma_f32_16x16x32_bf16 v[32:35], v[216:219], v[224:227], v[32:35]
	v_mfma_f32_16x16x32_bf16 v[28:31], v[216:219], v[228:231], v[28:31]
	v_mfma_f32_16x16x32_bf16 v[16:19], v[216:219], v[232:235], v[16:19]
	v_mfma_f32_16x16x32_bf16 v[12:15], v[216:219], v[236:239], v[12:15]
	ds_read_b128 v[216:219], v185 offset:6144
	s_waitcnt lgkmcnt(7)
	v_mfma_f32_16x16x32_bf16 v[8:11], v[220:223], v[224:227], v[8:11]
	v_mfma_f32_16x16x32_bf16 v[4:7], v[220:223], v[228:231], v[4:7]
	v_mfma_f32_16x16x32_bf16 v[0:3], v[220:223], v[232:235], v[0:3]
	v_mfma_f32_16x16x32_bf16 v[140:143], v[220:223], v[236:239], v[140:143]
	ds_read_b128 v[220:223], v185 offset:7168
	ds_read_b128 v[224:227], v184
	ds_read_b128 v[228:231], v184 offset:1024
	ds_read_b128 v[232:235], v184 offset:2048
	ds_read_b128 v[236:239], v184 offset:3072
	s_movk_i32 vcc_lo, 0x6000
	s_cmp_eq_u32 m0, 2
	s_cselect_b32 vcc_lo, 0xffff4000, vcc_lo
	s_add_u32 m0, m0, 1
	s_cmp_eq_u32 m0, 3
	s_cselect_b32 m0, 0, m0
	v_add_u32_e32 v185, vcc_lo, v185
	v_add_u32_e32 v184, vcc_lo, v184
	v_xor_b32_e32 v185, 64, v185
	v_xor_b32_e32 v184, 64, v184
	s_waitcnt lgkmcnt(0)
	v_mfma_f32_16x16x32_bf16 v[172:175], v[190:193], v[224:227], v[172:175]
	v_mfma_f32_16x16x32_bf16 v[168:171], v[190:193], v[228:231], v[168:171]
	v_mfma_f32_16x16x32_bf16 v[164:167], v[190:193], v[232:235], v[164:167]
	v_mfma_f32_16x16x32_bf16 v[160:163], v[190:193], v[236:239], v[160:163]
	v_mfma_f32_16x16x32_bf16 v[156:159], v[194:197], v[224:227], v[156:159]
	v_mfma_f32_16x16x32_bf16 v[152:155], v[194:197], v[228:231], v[152:155]
	v_mfma_f32_16x16x32_bf16 v[148:151], v[194:197], v[232:235], v[148:151]
	v_mfma_f32_16x16x32_bf16 v[144:147], v[194:197], v[236:239], v[144:147]
	v_mfma_f32_16x16x32_bf16 v[136:139], v[198:201], v[224:227], v[136:139]
	v_mfma_f32_16x16x32_bf16 v[132:135], v[198:201], v[228:231], v[132:135]
	v_mfma_f32_16x16x32_bf16 v[128:131], v[198:201], v[232:235], v[128:131]
	v_mfma_f32_16x16x32_bf16 v[124:127], v[198:201], v[236:239], v[124:127]
	v_mfma_f32_16x16x32_bf16 v[120:123], v[204:207], v[224:227], v[120:123]
	v_mfma_f32_16x16x32_bf16 v[108:111], v[204:207], v[228:231], v[108:111]
	v_mfma_f32_16x16x32_bf16 v[100:103], v[204:207], v[232:235], v[100:103]
	v_mfma_f32_16x16x32_bf16 v[96:99], v[204:207], v[236:239], v[96:99]
	v_mfma_f32_16x16x32_bf16 v[88:91], v[208:211], v[224:227], v[88:91]
	v_mfma_f32_16x16x32_bf16 v[80:83], v[208:211], v[228:231], v[80:83]
	v_mfma_f32_16x16x32_bf16 v[76:79], v[208:211], v[232:235], v[76:79]
	v_mfma_f32_16x16x32_bf16 v[64:67], v[208:211], v[236:239], v[64:67]
	v_mfma_f32_16x16x32_bf16 v[60:63], v[212:215], v[224:227], v[60:63]
	v_mfma_f32_16x16x32_bf16 v[52:55], v[212:215], v[228:231], v[52:55]
	v_mfma_f32_16x16x32_bf16 v[44:47], v[212:215], v[232:235], v[44:47]
	v_mfma_f32_16x16x32_bf16 v[36:39], v[212:215], v[236:239], v[36:39]
	v_mfma_f32_16x16x32_bf16 v[32:35], v[216:219], v[224:227], v[32:35]
	v_mfma_f32_16x16x32_bf16 v[28:31], v[216:219], v[228:231], v[28:31]
	v_mfma_f32_16x16x32_bf16 v[16:19], v[216:219], v[232:235], v[16:19]
	v_mfma_f32_16x16x32_bf16 v[12:15], v[216:219], v[236:239], v[12:15]
	v_mfma_f32_16x16x32_bf16 v[8:11], v[220:223], v[224:227], v[8:11]
	v_mfma_f32_16x16x32_bf16 v[4:7], v[220:223], v[228:231], v[4:7]
	v_mfma_f32_16x16x32_bf16 v[0:3], v[220:223], v[232:235], v[0:3]
	v_mfma_f32_16x16x32_bf16 v[140:143], v[220:223], v[236:239], v[140:143]
	v_lshrrev_b32_e32 v224, 4, v188
	v_and_b32_e32 v225, 7, v188
	v_bitop3_b32 v226, v224, v225, 3 bitop3:0x6c
	v_lshlrev_b32_e32 v227, 7, v188
	v_bfe_u32 v228, v188, 4, 2
	v_and_b32_e32 v229, 0xffffc780, v227
	v_and_b32_e32 v227, 0x2780, v227
	v_bitop3_b32 v228, v228, v225, 4 bitop3:0x36
	v_lshlrev_b32_e32 v226, 4, v226
	v_lshlrev_b32_e32 v228, 4, v228
	v_or_b32_e32 v185, v229, v226
	v_or_b32_e32 v184, v227, v226
	v_or_b32_e32 v183, v229, v228
	v_or_b32_e32 v182, v227, v228
	s_waitcnt vmcnt(0)
	s_barrier
	s_waitcnt vmcnt(10)
	ds_write_b128 v176, v[116:119]
	s_waitcnt vmcnt(9)
	ds_write_b128 v176, v[112:115] offset:4096
	s_waitcnt vmcnt(8)
	ds_write_b128 v176, v[104:107] offset:8192
	s_waitcnt vmcnt(7)
	ds_write_b128 v176, v[92:95] offset:12288
	s_waitcnt vmcnt(6)
	ds_write_b128 v176, v[84:87] offset:16384
	s_waitcnt vmcnt(5)
	ds_write_b128 v176, v[72:75] offset:20480
	s_waitcnt vmcnt(4)
	ds_write_b128 v176, v[68:71] offset:24576
	s_waitcnt vmcnt(3)
	ds_write_b128 v176, v[48:51] offset:28672
	ds_write_b128 v176, v[56:59] offset:32768
	s_waitcnt vmcnt(2)
	ds_write_b128 v176, v[40:43] offset:36864
	s_waitcnt vmcnt(1)
	ds_write_b128 v176, v[24:27] offset:40960
	s_waitcnt vmcnt(0)
	ds_write_b128 v176, v[20:23] offset:45056
	s_waitcnt lgkmcnt(0)
	s_barrier
	ds_read_b128 v[20:23], v185
	ds_read_b128 v[24:27], v185 offset:2048
	ds_read_b128 v[40:43], v185 offset:4096
	ds_read_b128 v[48:51], v185 offset:6144
	ds_read_b128 v[56:59], v185 offset:8192
	ds_read_b128 v[68:71], v185 offset:10240
	ds_read_b128 v[72:75], v185 offset:12288
	ds_read_b128 v[84:87], v185 offset:14336
	ds_read_b128 v[92:95], v184 offset:32768
	ds_read_b128 v[104:107], v184 offset:34816
	ds_read_b128 v[112:115], v184 offset:36864
	ds_read_b128 v[116:119], v184 offset:38912
	s_waitcnt lgkmcnt(3)
	v_mfma_f32_16x16x32_bf16 v[172:175], v[20:23], v[92:95], v[172:175]
	s_waitcnt lgkmcnt(2)
	v_mfma_f32_16x16x32_bf16 v[168:171], v[20:23], v[104:107], v[168:171]
	s_waitcnt lgkmcnt(1)
	v_mfma_f32_16x16x32_bf16 v[164:167], v[20:23], v[112:115], v[164:167]
	s_waitcnt lgkmcnt(0)
	v_mfma_f32_16x16x32_bf16 v[20:23], v[20:23], v[116:119], v[160:163]
	v_mfma_f32_16x16x32_bf16 v[156:159], v[24:27], v[92:95], v[156:159]
	v_mfma_f32_16x16x32_bf16 v[152:155], v[24:27], v[104:107], v[152:155]
	v_mfma_f32_16x16x32_bf16 v[148:151], v[24:27], v[112:115], v[148:151]
	v_mfma_f32_16x16x32_bf16 v[24:27], v[24:27], v[116:119], v[144:147]
	v_mfma_f32_16x16x32_bf16 v[136:139], v[40:43], v[92:95], v[136:139]
	v_mfma_f32_16x16x32_bf16 v[132:135], v[40:43], v[104:107], v[132:135]
	v_mfma_f32_16x16x32_bf16 v[128:131], v[40:43], v[112:115], v[128:131]
	v_mfma_f32_16x16x32_bf16 v[40:43], v[40:43], v[116:119], v[124:127]
	v_mfma_f32_16x16x32_bf16 v[144:147], v[48:51], v[92:95], v[120:123]
	v_mfma_f32_16x16x32_bf16 v[160:163], v[48:51], v[104:107], v[108:111]
	v_mfma_f32_16x16x32_bf16 v[178:181], v[48:51], v[112:115], v[100:103]
	v_mfma_f32_16x16x32_bf16 v[48:51], v[48:51], v[116:119], v[96:99]
	v_mfma_f32_16x16x32_bf16 v[16:19], v[72:75], v[112:115], v[16:19]
	v_mfma_f32_16x16x32_bf16 v[12:15], v[72:75], v[116:119], v[12:15]
	v_mfma_f32_16x16x32_bf16 v[8:11], v[84:87], v[92:95], v[8:11]
	v_mfma_f32_16x16x32_bf16 v[4:7], v[84:87], v[104:107], v[4:7]
	v_mfma_f32_16x16x32_bf16 v[0:3], v[84:87], v[112:115], v[0:3]
	v_mfma_f32_16x16x32_bf16 v[184:187], v[56:59], v[92:95], v[88:91]
	v_mfma_f32_16x16x32_bf16 v[190:193], v[56:59], v[104:107], v[80:83]
	v_mfma_f32_16x16x32_bf16 v[194:197], v[56:59], v[112:115], v[76:79]
	v_mfma_f32_16x16x32_bf16 v[56:59], v[56:59], v[116:119], v[64:67]
	v_mfma_f32_16x16x32_bf16 v[198:201], v[68:71], v[92:95], v[60:63]
	v_mfma_f32_16x16x32_bf16 v[52:55], v[68:71], v[104:107], v[52:55]
	v_mfma_f32_16x16x32_bf16 v[204:207], v[68:71], v[112:115], v[44:47]
	v_mfma_f32_16x16x32_bf16 v[208:211], v[68:71], v[116:119], v[36:39]
	v_mfma_f32_16x16x32_bf16 v[212:215], v[72:75], v[92:95], v[32:35]
	v_mfma_f32_16x16x32_bf16 v[216:219], v[72:75], v[104:107], v[28:31]
	v_mfma_f32_16x16x32_bf16 v[140:143], v[84:87], v[116:119], v[140:143]
	s_nop 1
	ds_read_b128 v[28:31], v183
	ds_read_b128 v[32:35], v183 offset:2048
	ds_read_b128 v[36:39], v183 offset:4096
	ds_read_b128 v[44:47], v183 offset:6144
	ds_read_b128 v[220:223], v183 offset:8192
	ds_read_b128 v[224:227], v183 offset:10240
	ds_read_b128 v[228:231], v183 offset:12288
	ds_read_b128 v[232:235], v183 offset:14336
	ds_read_b128 v[236:239], v182 offset:32768
	ds_read_b128 v[240:243], v182 offset:34816
	ds_read_b128 v[244:247], v182 offset:36864
	ds_read_b128 v[248:251], v182 offset:38912
	s_waitcnt lgkmcnt(3)
	v_mfma_f32_16x16x32_bf16 v[124:127], v[28:31], v[236:239], v[172:175]
	v_readlane_b32 s16, v255, 27
	s_mov_b64 s[30:31], 0
	v_readlane_b32 s17, v255, 28
	s_waitcnt lgkmcnt(2)
	v_mfma_f32_16x16x32_bf16 v[120:123], v[28:31], v[240:243], v[168:171]
	v_readlane_b32 s11, v255, 16
	v_readlane_b32 s10, v255, 18
	s_waitcnt lgkmcnt(1)
	v_mfma_f32_16x16x32_bf16 v[116:119], v[28:31], v[244:247], v[164:167]
	s_waitcnt lgkmcnt(0)
	v_mfma_f32_16x16x32_bf16 v[112:115], v[28:31], v[248:251], v[20:23]
	v_mfma_f32_16x16x32_bf16 v[108:111], v[32:35], v[236:239], v[156:159]
	v_mfma_f32_16x16x32_bf16 v[104:107], v[32:35], v[240:243], v[152:155]
	v_mfma_f32_16x16x32_bf16 v[100:103], v[32:35], v[244:247], v[148:151]
	v_mfma_f32_16x16x32_bf16 v[96:99], v[32:35], v[248:251], v[24:27]
	v_mfma_f32_16x16x32_bf16 v[92:95], v[36:39], v[236:239], v[136:139]
	v_mfma_f32_16x16x32_bf16 v[88:91], v[36:39], v[240:243], v[132:135]
	v_mfma_f32_16x16x32_bf16 v[84:87], v[36:39], v[244:247], v[128:131]
	v_mfma_f32_16x16x32_bf16 v[80:83], v[36:39], v[248:251], v[40:43]
	v_mfma_f32_16x16x32_bf16 v[76:79], v[44:47], v[236:239], v[144:147]
	v_mfma_f32_16x16x32_bf16 v[72:75], v[44:47], v[240:243], v[160:163]
	v_mfma_f32_16x16x32_bf16 v[68:71], v[44:47], v[244:247], v[178:181]
	v_mfma_f32_16x16x32_bf16 v[64:67], v[44:47], v[248:251], v[48:51]
	v_mfma_f32_16x16x32_bf16 v[60:63], v[220:223], v[236:239], v[184:187]
	v_mfma_f32_16x16x32_bf16 v[156:159], v[220:223], v[240:243], v[190:193]
	v_mfma_f32_16x16x32_bf16 v[152:155], v[220:223], v[244:247], v[194:197]
	v_mfma_f32_16x16x32_bf16 v[48:51], v[220:223], v[248:251], v[56:59]
	v_mfma_f32_16x16x32_bf16 v[44:47], v[224:227], v[236:239], v[198:201]
	v_mfma_f32_16x16x32_bf16 v[40:43], v[224:227], v[240:243], v[52:55]
	v_mfma_f32_16x16x32_bf16 v[36:39], v[224:227], v[244:247], v[204:207]
	v_mfma_f32_16x16x32_bf16 v[32:35], v[224:227], v[248:251], v[208:211]
	v_mfma_f32_16x16x32_bf16 v[28:31], v[228:231], v[236:239], v[212:215]
	v_mfma_f32_16x16x32_bf16 v[24:27], v[228:231], v[240:243], v[216:219]
	v_mfma_f32_16x16x32_bf16 v[20:23], v[228:231], v[244:247], v[16:19]
	v_mfma_f32_16x16x32_bf16 v[16:19], v[228:231], v[248:251], v[12:15]
	v_mfma_f32_16x16x32_bf16 v[12:15], v[232:235], v[236:239], v[8:11]
	v_mfma_f32_16x16x32_bf16 v[8:11], v[232:235], v[240:243], v[4:7]
	v_xor_b32_e32 v240, 32, v203
	v_mfma_f32_16x16x32_bf16 v[0:3], v[232:235], v[244:247], v[0:3]
	v_mfma_f32_16x16x32_bf16 v[4:7], v[232:235], v[248:251], v[140:143]

.LBB0_428:
	s_waitcnt lgkmcnt(0)
	s_barrier
	ds_read_b128 v[224:227], v184
	ds_read_b128 v[228:231], v184 offset:1024
	ds_read_b128 v[232:235], v184 offset:2048
	ds_read_b128 v[236:239], v184 offset:3072
	ds_read_b128 v[190:193], v185
	ds_read_b128 v[194:197], v185 offset:1024
	ds_read_b128 v[198:201], v185 offset:2048
	ds_read_b128 v[204:207], v185 offset:3072
	ds_read_b128 v[208:211], v185 offset:4096
	ds_read_b128 v[212:215], v185 offset:5120
	ds_read_b128 v[216:219], v185 offset:6144
	ds_read_b128 v[220:223], v185 offset:7168
	s_movk_i32 vcc_lo, 0x6000
	s_cmp_eq_u32 m0, 2
	s_cselect_b32 vcc_lo, 0xffff4000, vcc_lo
	s_add_u32 m0, m0, 1
	s_cmp_eq_u32 m0, 3
	s_cselect_b32 m0, 0, m0
	v_add_u32_e32 v185, vcc_lo, v185
	v_add_u32_e32 v184, vcc_lo, v184
	v_xor_b32_e32 v185, 64, v185
	v_xor_b32_e32 v184, 64, v184
	s_waitcnt lgkmcnt(7)
	v_mfma_f32_16x16x32_bf16 v[172:175], v[224:227], v[190:193], v[172:175]
	v_mfma_f32_16x16x32_bf16 v[168:171], v[228:231], v[190:193], v[168:171]
	v_mfma_f32_16x16x32_bf16 v[164:167], v[232:235], v[190:193], v[164:167]
	v_mfma_f32_16x16x32_bf16 v[160:163], v[236:239], v[190:193], v[160:163]
	ds_read_b128 v[190:193], v185
	s_waitcnt lgkmcnt(7)
	v_mfma_f32_16x16x32_bf16 v[156:159], v[224:227], v[194:197], v[156:159]
	v_mfma_f32_16x16x32_bf16 v[152:155], v[228:231], v[194:197], v[152:155]
	v_mfma_f32_16x16x32_bf16 v[148:151], v[232:235], v[194:197], v[148:151]
	v_mfma_f32_16x16x32_bf16 v[144:147], v[236:239], v[194:197], v[144:147]
	ds_read_b128 v[194:197], v185 offset:1024
	s_waitcnt lgkmcnt(7)
	v_mfma_f32_16x16x32_bf16 v[136:139], v[224:227], v[198:201], v[136:139]
	v_mfma_f32_16x16x32_bf16 v[132:135], v[228:231], v[198:201], v[132:135]
	v_mfma_f32_16x16x32_bf16 v[128:131], v[232:235], v[198:201], v[128:131]
	v_mfma_f32_16x16x32_bf16 v[124:127], v[236:239], v[198:201], v[124:127]
	ds_read_b128 v[198:201], v185 offset:2048
	s_waitcnt lgkmcnt(7)
	v_mfma_f32_16x16x32_bf16 v[120:123], v[224:227], v[204:207], v[120:123]
	v_mfma_f32_16x16x32_bf16 v[108:111], v[228:231], v[204:207], v[108:111]
	v_mfma_f32_16x16x32_bf16 v[100:103], v[232:235], v[204:207], v[100:103]
	v_mfma_f32_16x16x32_bf16 v[96:99], v[236:239], v[204:207], v[96:99]
	ds_read_b128 v[204:207], v185 offset:3072
	s_waitcnt lgkmcnt(7)
	v_mfma_f32_16x16x32_bf16 v[88:91], v[224:227], v[208:211], v[88:91]
	v_mfma_f32_16x16x32_bf16 v[80:83], v[228:231], v[208:211], v[80:83]
	v_mfma_f32_16x16x32_bf16 v[76:79], v[232:235], v[208:211], v[76:79]
	v_mfma_f32_16x16x32_bf16 v[64:67], v[236:239], v[208:211], v[64:67]
	ds_read_b128 v[208:211], v185 offset:4096
	s_waitcnt lgkmcnt(7)
	v_mfma_f32_16x16x32_bf16 v[60:63], v[224:227], v[212:215], v[60:63]
	v_mfma_f32_16x16x32_bf16 v[52:55], v[228:231], v[212:215], v[52:55]
	v_mfma_f32_16x16x32_bf16 v[44:47], v[232:235], v[212:215], v[44:47]
	v_mfma_f32_16x16x32_bf16 v[36:39], v[236:239], v[212:215], v[36:39]
	ds_read_b128 v[212:215], v185 offset:5120
	s_waitcnt lgkmcnt(7)
	v_mfma_f32_16x16x32_bf16 v[32:35], v[224:227], v[216:219], v[32:35]
	v_mfma_f32_16x16x32_bf16 v[28:31], v[228:231], v[216:219], v[28:31]
	v_mfma_f32_16x16x32_bf16 v[16:19], v[232:235], v[216:219], v[16:19]
	v_mfma_f32_16x16x32_bf16 v[12:15], v[236:239], v[216:219], v[12:15]
	ds_read_b128 v[216:219], v185 offset:6144
	s_waitcnt lgkmcnt(7)
	v_mfma_f32_16x16x32_bf16 v[8:11], v[224:227], v[220:223], v[8:11]
	v_mfma_f32_16x16x32_bf16 v[4:7], v[228:231], v[220:223], v[4:7]
	v_mfma_f32_16x16x32_bf16 v[0:3], v[232:235], v[220:223], v[0:3]
	v_mfma_f32_16x16x32_bf16 v[140:143], v[236:239], v[220:223], v[140:143]
	ds_read_b128 v[220:223], v185 offset:7168
	ds_read_b128 v[224:227], v184
	ds_read_b128 v[228:231], v184 offset:1024
	ds_read_b128 v[232:235], v184 offset:2048
	ds_read_b128 v[236:239], v184 offset:3072
	s_movk_i32 vcc_lo, 0x6000
	s_cmp_eq_u32 m0, 2
	s_cselect_b32 vcc_lo, 0xffff4000, vcc_lo
	s_add_u32 m0, m0, 1
	s_cmp_eq_u32 m0, 3
	s_cselect_b32 m0, 0, m0
	v_add_u32_e32 v185, vcc_lo, v185
	v_add_u32_e32 v184, vcc_lo, v184
	v_xor_b32_e32 v185, 64, v185
	v_xor_b32_e32 v184, 64, v184
	s_sub_u32 vcc_lo, s30, s98
	v_add_u32_e32 v186, vcc_lo, v178
	v_add_u32_e32 v187, vcc_lo, v180
	s_barrier
	s_waitcnt lgkmcnt(0)
	v_mfma_f32_16x16x32_bf16 v[172:175], v[224:227], v[190:193], v[172:175]
	s_waitcnt vmcnt(11)
	v_mfma_f32_16x16x32_bf16 v[168:171], v[228:231], v[190:193], v[168:171]
	ds_write_b128 v183, v[116:119]
	v_add_u32_e32 v116, s14, v187
	v_mfma_f32_16x16x32_bf16 v[164:167], v[232:235], v[190:193], v[164:167]
	global_load_dwordx4 v[116:119], v116, s[98:99] offset:128
	v_mfma_f32_16x16x32_bf16 v[160:163], v[236:239], v[190:193], v[160:163]
	s_waitcnt vmcnt(11)
	ds_write_b128 v183, v[112:115] offset:2048
	v_mfma_f32_16x16x32_bf16 v[156:159], v[224:227], v[194:197], v[156:159]
	v_add_u32_e32 v112, s15, v187
	v_mfma_f32_16x16x32_bf16 v[152:155], v[228:231], v[194:197], v[152:155]
	global_load_dwordx4 v[112:115], v112, s[98:99] offset:128
	s_waitcnt vmcnt(11)
	v_mfma_f32_16x16x32_bf16 v[148:151], v[232:235], v[194:197], v[148:151]
	ds_write_b128 v183, v[104:107] offset:4096
	v_mfma_f32_16x16x32_bf16 v[144:147], v[236:239], v[194:197], v[144:147]
	v_add_u32_e32 v104, s16, v187
	global_load_dwordx4 v[104:107], v104, s[98:99] offset:128
	v_mfma_f32_16x16x32_bf16 v[136:139], v[224:227], v[198:201], v[136:139]
	s_waitcnt vmcnt(11)
	v_mfma_f32_16x16x32_bf16 v[132:135], v[228:231], v[198:201], v[132:135]
	ds_write_b128 v183, v[92:95] offset:6144
	v_add_u32_e32 v92, s17, v187
	v_mfma_f32_16x16x32_bf16 v[128:131], v[232:235], v[198:201], v[128:131]
	global_load_dwordx4 v[92:95], v92, s[98:99] offset:128
	v_mfma_f32_16x16x32_bf16 v[124:127], v[236:239], v[198:201], v[124:127]
	s_waitcnt vmcnt(11)
	ds_write_b128 v183, v[84:87] offset:8192
	v_mfma_f32_16x16x32_bf16 v[120:123], v[224:227], v[204:207], v[120:123]
	v_add_u32_e32 v84, s10, v187
	v_mfma_f32_16x16x32_bf16 v[108:111], v[228:231], v[204:207], v[108:111]
	global_load_dwordx4 v[84:87], v84, s[98:99] offset:128
	s_waitcnt vmcnt(11)
	v_mfma_f32_16x16x32_bf16 v[100:103], v[232:235], v[204:207], v[100:103]
	ds_write_b128 v183, v[72:75] offset:10240
	v_mfma_f32_16x16x32_bf16 v[96:99], v[236:239], v[204:207], v[96:99]
	v_add_u32_e32 v72, s11, v187
	global_load_dwordx4 v[72:75], v72, s[98:99] offset:128
	v_mfma_f32_16x16x32_bf16 v[88:91], v[224:227], v[208:211], v[88:91]
	s_waitcnt vmcnt(11)
	v_mfma_f32_16x16x32_bf16 v[80:83], v[228:231], v[208:211], v[80:83]
	ds_write_b128 v183, v[68:71] offset:12288
	v_add_u32_e32 v68, s12, v187
	v_mfma_f32_16x16x32_bf16 v[76:79], v[232:235], v[208:211], v[76:79]
	global_load_dwordx4 v[68:71], v68, s[98:99] offset:128
	v_mfma_f32_16x16x32_bf16 v[64:67], v[236:239], v[208:211], v[64:67]
	s_waitcnt vmcnt(11)
	ds_write_b128 v183, v[48:51] offset:14336
	v_mfma_f32_16x16x32_bf16 v[60:63], v[224:227], v[212:215], v[60:63]
	v_add_u32_e32 v48, s13, v187
	v_mfma_f32_16x16x32_bf16 v[52:55], v[228:231], v[212:215], v[52:55]
	global_load_dwordx4 v[48:51], v48, s[98:99] offset:128
	s_waitcnt vmcnt(11)
	v_mfma_f32_16x16x32_bf16 v[44:47], v[232:235], v[212:215], v[44:47]
	ds_write_b128 v183, v[56:59] offset:16384
	v_mfma_f32_16x16x32_bf16 v[36:39], v[236:239], v[212:215], v[36:39]
	v_mov_b32_e32 v56, v186
	global_load_dwordx4 v[56:59], v56, s[98:99] offset:128
	v_mfma_f32_16x16x32_bf16 v[32:35], v[224:227], v[216:219], v[32:35]
	s_waitcnt vmcnt(11)
	v_mfma_f32_16x16x32_bf16 v[28:31], v[228:231], v[216:219], v[28:31]
	ds_write_b128 v183, v[40:43] offset:18432
	v_add_u32_e32 v40, s43, v186
	v_mfma_f32_16x16x32_bf16 v[16:19], v[232:235], v[216:219], v[16:19]
	global_load_dwordx4 v[40:43], v40, s[98:99] offset:128
	v_mfma_f32_16x16x32_bf16 v[12:15], v[236:239], v[216:219], v[12:15]
	s_waitcnt vmcnt(11)
	ds_write_b128 v183, v[24:27] offset:20480
	v_mfma_f32_16x16x32_bf16 v[8:11], v[224:227], v[220:223], v[8:11]
	v_add_u32_e32 v24, s42, v186
	v_mfma_f32_16x16x32_bf16 v[4:7], v[228:231], v[220:223], v[4:7]
	global_load_dwordx4 v[24:27], v24, s[98:99] offset:128
	s_waitcnt vmcnt(11)
	v_mfma_f32_16x16x32_bf16 v[0:3], v[232:235], v[220:223], v[0:3]
	ds_write_b128 v183, v[20:23] offset:22528
	v_mfma_f32_16x16x32_bf16 v[140:143], v[236:239], v[220:223], v[140:143]
	v_add_u32_e32 v20, s28, v186
	global_load_dwordx4 v[20:23], v20, s[98:99] offset:128
	v_cmp_gt_u32_e32 vcc, 0x6000, v183
	v_add_u32_e32 v182, 0xc000, v183
	v_add_u32_e32 v183, 0xffffa000, v183
	s_nop 0
	v_cndmask_b32_e32 v183, v183, v182, vcc
	s_add_u32 s30, s30, 0x80
	s_addc_u32 s31, s31, 0
	s_cmpk_lg_i32 s30, 0x180
	s_cbranch_scc1 .LBB0_428
	s_waitcnt lgkmcnt(0)
	s_barrier
	ds_read_b128 v[224:227], v184
	ds_read_b128 v[228:231], v184 offset:1024
	ds_read_b128 v[232:235], v184 offset:2048
	ds_read_b128 v[236:239], v184 offset:3072
	ds_read_b128 v[190:193], v185
	ds_read_b128 v[194:197], v185 offset:1024
	ds_read_b128 v[198:201], v185 offset:2048
	ds_read_b128 v[204:207], v185 offset:3072
	ds_read_b128 v[208:211], v185 offset:4096
	ds_read_b128 v[212:215], v185 offset:5120
	ds_read_b128 v[216:219], v185 offset:6144
	ds_read_b128 v[220:223], v185 offset:7168
	s_movk_i32 vcc_lo, 0x6000
	s_cmp_eq_u32 m0, 2
	s_cselect_b32 vcc_lo, 0xffff4000, vcc_lo
	s_add_u32 m0, m0, 1
	s_cmp_eq_u32 m0, 3
	s_cselect_b32 m0, 0, m0
	v_add_u32_e32 v185, vcc_lo, v185
	v_add_u32_e32 v184, vcc_lo, v184
	v_xor_b32_e32 v185, 64, v185
	v_xor_b32_e32 v184, 64, v184
	s_waitcnt lgkmcnt(7)
	v_mfma_f32_16x16x32_bf16 v[172:175], v[224:227], v[190:193], v[172:175]
	v_mfma_f32_16x16x32_bf16 v[168:171], v[228:231], v[190:193], v[168:171]
	v_mfma_f32_16x16x32_bf16 v[164:167], v[232:235], v[190:193], v[164:167]
	v_mfma_f32_16x16x32_bf16 v[160:163], v[236:239], v[190:193], v[160:163]
	ds_read_b128 v[190:193], v185
	s_waitcnt lgkmcnt(7)
	v_mfma_f32_16x16x32_bf16 v[156:159], v[224:227], v[194:197], v[156:159]
	v_mfma_f32_16x16x32_bf16 v[152:155], v[228:231], v[194:197], v[152:155]
	v_mfma_f32_16x16x32_bf16 v[148:151], v[232:235], v[194:197], v[148:151]
	v_mfma_f32_16x16x32_bf16 v[144:147], v[236:239], v[194:197], v[144:147]
	ds_read_b128 v[194:197], v185 offset:1024
	s_waitcnt lgkmcnt(7)
	v_mfma_f32_16x16x32_bf16 v[136:139], v[224:227], v[198:201], v[136:139]
	v_mfma_f32_16x16x32_bf16 v[132:135], v[228:231], v[198:201], v[132:135]
	v_mfma_f32_16x16x32_bf16 v[128:131], v[232:235], v[198:201], v[128:131]
	v_mfma_f32_16x16x32_bf16 v[124:127], v[236:239], v[198:201], v[124:127]
	ds_read_b128 v[198:201], v185 offset:2048
	s_waitcnt lgkmcnt(7)
	v_mfma_f32_16x16x32_bf16 v[120:123], v[224:227], v[204:207], v[120:123]
	v_mfma_f32_16x16x32_bf16 v[108:111], v[228:231], v[204:207], v[108:111]
	v_mfma_f32_16x16x32_bf16 v[100:103], v[232:235], v[204:207], v[100:103]
	v_mfma_f32_16x16x32_bf16 v[96:99], v[236:239], v[204:207], v[96:99]
	ds_read_b128 v[204:207], v185 offset:3072
	s_waitcnt lgkmcnt(7)
	v_mfma_f32_16x16x32_bf16 v[88:91], v[224:227], v[208:211], v[88:91]
	v_mfma_f32_16x16x32_bf16 v[80:83], v[228:231], v[208:211], v[80:83]
	v_mfma_f32_16x16x32_bf16 v[76:79], v[232:235], v[208:211], v[76:79]
	v_mfma_f32_16x16x32_bf16 v[64:67], v[236:239], v[208:211], v[64:67]
	ds_read_b128 v[208:211], v185 offset:4096
	s_waitcnt lgkmcnt(7)
	v_mfma_f32_16x16x32_bf16 v[60:63], v[224:227], v[212:215], v[60:63]
	v_mfma_f32_16x16x32_bf16 v[52:55], v[228:231], v[212:215], v[52:55]
	v_mfma_f32_16x16x32_bf16 v[44:47], v[232:235], v[212:215], v[44:47]
	v_mfma_f32_16x16x32_bf16 v[36:39], v[236:239], v[212:215], v[36:39]
	ds_read_b128 v[212:215], v185 offset:5120
	s_waitcnt lgkmcnt(7)
	v_mfma_f32_16x16x32_bf16 v[32:35], v[224:227], v[216:219], v[32:35]
	v_mfma_f32_16x16x32_bf16 v[28:31], v[228:231], v[216:219], v[28:31]
	v_mfma_f32_16x16x32_bf16 v[16:19], v[232:235], v[216:219], v[16:19]
	v_mfma_f32_16x16x32_bf16 v[12:15], v[236:239], v[216:219], v[12:15]
	ds_read_b128 v[216:219], v185 offset:6144
	s_waitcnt lgkmcnt(7)
	v_mfma_f32_16x16x32_bf16 v[8:11], v[224:227], v[220:223], v[8:11]
	v_mfma_f32_16x16x32_bf16 v[4:7], v[228:231], v[220:223], v[4:7]
	v_mfma_f32_16x16x32_bf16 v[0:3], v[232:235], v[220:223], v[0:3]
	v_mfma_f32_16x16x32_bf16 v[140:143], v[236:239], v[220:223], v[140:143]
	ds_read_b128 v[220:223], v185 offset:7168
	ds_read_b128 v[224:227], v184
	ds_read_b128 v[228:231], v184 offset:1024
	ds_read_b128 v[232:235], v184 offset:2048
	ds_read_b128 v[236:239], v184 offset:3072
	s_movk_i32 vcc_lo, 0x6000
	s_cmp_eq_u32 m0, 2
	s_cselect_b32 vcc_lo, 0xffff4000, vcc_lo
	s_add_u32 m0, m0, 1
	s_cmp_eq_u32 m0, 3
	s_cselect_b32 m0, 0, m0
	v_add_u32_e32 v185, vcc_lo, v185
	v_add_u32_e32 v184, vcc_lo, v184
	v_xor_b32_e32 v185, 64, v185
	v_xor_b32_e32 v184, 64, v184
	s_waitcnt lgkmcnt(0)
	v_mfma_f32_16x16x32_bf16 v[172:175], v[224:227], v[190:193], v[172:175]
	v_mfma_f32_16x16x32_bf16 v[168:171], v[228:231], v[190:193], v[168:171]
	v_mfma_f32_16x16x32_bf16 v[164:167], v[232:235], v[190:193], v[164:167]
	v_mfma_f32_16x16x32_bf16 v[160:163], v[236:239], v[190:193], v[160:163]
	v_mfma_f32_16x16x32_bf16 v[156:159], v[224:227], v[194:197], v[156:159]
	v_mfma_f32_16x16x32_bf16 v[152:155], v[228:231], v[194:197], v[152:155]
	v_mfma_f32_16x16x32_bf16 v[148:151], v[232:235], v[194:197], v[148:151]
	v_mfma_f32_16x16x32_bf16 v[144:147], v[236:239], v[194:197], v[144:147]
	v_mfma_f32_16x16x32_bf16 v[136:139], v[224:227], v[198:201], v[136:139]
	v_mfma_f32_16x16x32_bf16 v[132:135], v[228:231], v[198:201], v[132:135]
	v_mfma_f32_16x16x32_bf16 v[128:131], v[232:235], v[198:201], v[128:131]
	v_mfma_f32_16x16x32_bf16 v[124:127], v[236:239], v[198:201], v[124:127]
	v_mfma_f32_16x16x32_bf16 v[120:123], v[224:227], v[204:207], v[120:123]
	v_mfma_f32_16x16x32_bf16 v[108:111], v[228:231], v[204:207], v[108:111]
	v_mfma_f32_16x16x32_bf16 v[100:103], v[232:235], v[204:207], v[100:103]
	v_mfma_f32_16x16x32_bf16 v[96:99], v[236:239], v[204:207], v[96:99]
	v_mfma_f32_16x16x32_bf16 v[88:91], v[224:227], v[208:211], v[88:91]
	v_mfma_f32_16x16x32_bf16 v[80:83], v[228:231], v[208:211], v[80:83]
	v_mfma_f32_16x16x32_bf16 v[76:79], v[232:235], v[208:211], v[76:79]
	v_mfma_f32_16x16x32_bf16 v[64:67], v[236:239], v[208:211], v[64:67]
	v_mfma_f32_16x16x32_bf16 v[60:63], v[224:227], v[212:215], v[60:63]
	v_mfma_f32_16x16x32_bf16 v[52:55], v[228:231], v[212:215], v[52:55]
	v_mfma_f32_16x16x32_bf16 v[44:47], v[232:235], v[212:215], v[44:47]
	v_mfma_f32_16x16x32_bf16 v[36:39], v[236:239], v[212:215], v[36:39]
	v_mfma_f32_16x16x32_bf16 v[32:35], v[224:227], v[216:219], v[32:35]
	v_mfma_f32_16x16x32_bf16 v[28:31], v[228:231], v[216:219], v[28:31]
	v_mfma_f32_16x16x32_bf16 v[16:19], v[232:235], v[216:219], v[16:19]
	v_mfma_f32_16x16x32_bf16 v[12:15], v[236:239], v[216:219], v[12:15]
	v_mfma_f32_16x16x32_bf16 v[8:11], v[224:227], v[220:223], v[8:11]
	v_mfma_f32_16x16x32_bf16 v[4:7], v[228:231], v[220:223], v[4:7]
	v_mfma_f32_16x16x32_bf16 v[0:3], v[232:235], v[220:223], v[0:3]
	v_mfma_f32_16x16x32_bf16 v[140:143], v[236:239], v[220:223], v[140:143]
	v_lshrrev_b32_e32 v224, 4, v188
	v_and_b32_e32 v225, 7, v188
	v_bitop3_b32 v226, v224, v225, 3 bitop3:0x6c
	v_lshlrev_b32_e32 v227, 7, v188
	v_bfe_u32 v228, v188, 4, 2
	v_and_b32_e32 v229, 0xffffc780, v227
	v_and_b32_e32 v227, 0x2780, v227
	v_bitop3_b32 v228, v228, v225, 4 bitop3:0x36
	v_lshlrev_b32_e32 v226, 4, v226
	v_lshlrev_b32_e32 v228, 4, v228
	v_or_b32_e32 v185, v229, v226
	v_or_b32_e32 v184, v227, v226
	v_or_b32_e32 v183, v229, v228
	v_or_b32_e32 v182, v227, v228
	s_waitcnt vmcnt(0)
	s_barrier
	s_waitcnt vmcnt(10)
	ds_write_b128 v176, v[116:119]
	s_waitcnt vmcnt(9)
	ds_write_b128 v176, v[112:115] offset:4096
	s_waitcnt vmcnt(8)
	ds_write_b128 v176, v[104:107] offset:8192
	s_waitcnt vmcnt(7)
	ds_write_b128 v176, v[92:95] offset:12288
	s_waitcnt vmcnt(6)
	ds_write_b128 v176, v[84:87] offset:16384
	s_waitcnt vmcnt(5)
	ds_write_b128 v176, v[72:75] offset:20480
	s_waitcnt vmcnt(4)
	ds_write_b128 v176, v[68:71] offset:24576
	s_waitcnt vmcnt(3)
	ds_write_b128 v176, v[48:51] offset:28672
	ds_write_b128 v176, v[56:59] offset:32768
	s_waitcnt vmcnt(2)
	ds_write_b128 v176, v[40:43] offset:36864
	s_waitcnt vmcnt(1)
	ds_write_b128 v176, v[24:27] offset:40960
	s_waitcnt vmcnt(0)
	ds_write_b128 v176, v[20:23] offset:45056
	s_waitcnt lgkmcnt(0)
	s_barrier
	ds_read_b128 v[20:23], v185
	ds_read_b128 v[24:27], v185 offset:2048
	ds_read_b128 v[40:43], v185 offset:4096
	ds_read_b128 v[48:51], v185 offset:6144
	ds_read_b128 v[56:59], v185 offset:8192
	ds_read_b128 v[68:71], v185 offset:10240
	ds_read_b128 v[72:75], v185 offset:12288
	ds_read_b128 v[84:87], v185 offset:14336
	ds_read_b128 v[92:95], v184 offset:32768
	ds_read_b128 v[104:107], v184 offset:34816
	ds_read_b128 v[112:115], v184 offset:36864
	ds_read_b128 v[116:119], v184 offset:38912
	s_waitcnt lgkmcnt(3)
	v_mfma_f32_16x16x32_bf16 v[172:175], v[92:95], v[20:23], v[172:175]
	s_waitcnt lgkmcnt(2)
	v_mfma_f32_16x16x32_bf16 v[168:171], v[104:107], v[20:23], v[168:171]
	s_waitcnt lgkmcnt(1)
	v_mfma_f32_16x16x32_bf16 v[164:167], v[112:115], v[20:23], v[164:167]
	s_waitcnt lgkmcnt(0)
	v_mfma_f32_16x16x32_bf16 v[20:23], v[116:119], v[20:23], v[160:163]
	v_mfma_f32_16x16x32_bf16 v[156:159], v[92:95], v[24:27], v[156:159]
	v_mfma_f32_16x16x32_bf16 v[152:155], v[104:107], v[24:27], v[152:155]
	v_mfma_f32_16x16x32_bf16 v[148:151], v[112:115], v[24:27], v[148:151]
	v_mfma_f32_16x16x32_bf16 v[24:27], v[116:119], v[24:27], v[144:147]
	v_mfma_f32_16x16x32_bf16 v[136:139], v[92:95], v[40:43], v[136:139]
	v_mfma_f32_16x16x32_bf16 v[132:135], v[104:107], v[40:43], v[132:135]
	v_mfma_f32_16x16x32_bf16 v[128:131], v[112:115], v[40:43], v[128:131]
	v_mfma_f32_16x16x32_bf16 v[40:43], v[116:119], v[40:43], v[124:127]
	v_mfma_f32_16x16x32_bf16 v[144:147], v[92:95], v[48:51], v[120:123]
	v_mfma_f32_16x16x32_bf16 v[160:163], v[104:107], v[48:51], v[108:111]
	v_mfma_f32_16x16x32_bf16 v[178:181], v[112:115], v[48:51], v[100:103]
	v_mfma_f32_16x16x32_bf16 v[48:51], v[116:119], v[48:51], v[96:99]
	v_mfma_f32_16x16x32_bf16 v[16:19], v[112:115], v[72:75], v[16:19]
	v_mfma_f32_16x16x32_bf16 v[12:15], v[116:119], v[72:75], v[12:15]
	v_mfma_f32_16x16x32_bf16 v[8:11], v[92:95], v[84:87], v[8:11]
	v_mfma_f32_16x16x32_bf16 v[4:7], v[104:107], v[84:87], v[4:7]
	v_mfma_f32_16x16x32_bf16 v[0:3], v[112:115], v[84:87], v[0:3]
	v_mfma_f32_16x16x32_bf16 v[184:187], v[92:95], v[56:59], v[88:91]
	v_mfma_f32_16x16x32_bf16 v[190:193], v[104:107], v[56:59], v[80:83]
	v_mfma_f32_16x16x32_bf16 v[194:197], v[112:115], v[56:59], v[76:79]
	v_mfma_f32_16x16x32_bf16 v[198:201], v[116:119], v[56:59], v[64:67]
	v_mfma_f32_16x16x32_bf16 v[204:207], v[92:95], v[68:71], v[60:63]
	v_mfma_f32_16x16x32_bf16 v[208:211], v[104:107], v[68:71], v[52:55]
	v_mfma_f32_16x16x32_bf16 v[212:215], v[112:115], v[68:71], v[44:47]
	v_mfma_f32_16x16x32_bf16 v[216:219], v[116:119], v[68:71], v[36:39]
	v_mfma_f32_16x16x32_bf16 v[220:223], v[92:95], v[72:75], v[32:35]
	v_mfma_f32_16x16x32_bf16 v[224:227], v[104:107], v[72:75], v[28:31]
	v_mfma_f32_16x16x32_bf16 v[140:143], v[116:119], v[84:87], v[140:143]
	s_nop 1
	ds_read_b128 v[28:31], v183
	ds_read_b128 v[32:35], v183 offset:2048
	ds_read_b128 v[36:39], v183 offset:4096
	ds_read_b128 v[44:47], v183 offset:6144
	ds_read_b128 v[228:231], v183 offset:8192
	ds_read_b128 v[232:235], v183 offset:10240
	ds_read_b128 v[236:239], v183 offset:12288
	ds_read_b128 v[240:243], v183 offset:14336
	ds_read_b128 v[244:247], v182 offset:32768
	ds_read_b128 v[248:251], v182 offset:34816
	ds_read_b128 v[52:55], v182 offset:36864
	ds_read_b128 v[56:59], v182 offset:38912
	s_waitcnt lgkmcnt(3)
	v_mfma_f32_16x16x32_bf16 v[124:127], v[244:247], v[28:31], v[172:175]
	v_readlane_b32 s16, v255, 27
	v_readlane_b32 s17, v255, 28
	v_readlane_b32 s11, v255, 16
	s_waitcnt lgkmcnt(2)
	v_mfma_f32_16x16x32_bf16 v[120:123], v[248:251], v[28:31], v[168:171]
	v_readlane_b32 s10, v255, 18
	s_waitcnt lgkmcnt(1)
	v_mfma_f32_16x16x32_bf16 v[116:119], v[52:55], v[28:31], v[164:167]
	s_waitcnt lgkmcnt(0)
	v_mfma_f32_16x16x32_bf16 v[112:115], v[56:59], v[28:31], v[20:23]
	v_mfma_f32_16x16x32_bf16 v[108:111], v[244:247], v[32:35], v[156:159]
	v_mfma_f32_16x16x32_bf16 v[104:107], v[248:251], v[32:35], v[152:155]
	v_mfma_f32_16x16x32_bf16 v[100:103], v[52:55], v[32:35], v[148:151]
	v_mfma_f32_16x16x32_bf16 v[96:99], v[56:59], v[32:35], v[24:27]
	v_mfma_f32_16x16x32_bf16 v[92:95], v[244:247], v[36:39], v[136:139]
	v_mfma_f32_16x16x32_bf16 v[88:91], v[248:251], v[36:39], v[132:135]
	v_mfma_f32_16x16x32_bf16 v[84:87], v[52:55], v[36:39], v[128:131]
	v_mfma_f32_16x16x32_bf16 v[80:83], v[56:59], v[36:39], v[40:43]
	v_mfma_f32_16x16x32_bf16 v[76:79], v[244:247], v[44:47], v[144:147]
	v_mfma_f32_16x16x32_bf16 v[72:75], v[248:251], v[44:47], v[160:163]
	v_mfma_f32_16x16x32_bf16 v[68:71], v[52:55], v[44:47], v[178:181]
	v_mfma_f32_16x16x32_bf16 v[64:67], v[56:59], v[44:47], v[48:51]
	v_mfma_f32_16x16x32_bf16 v[60:63], v[244:247], v[228:231], v[184:187]
	v_mfma_f32_16x16x32_bf16 v[156:159], v[248:251], v[228:231], v[190:193]
	v_mfma_f32_16x16x32_bf16 v[152:155], v[52:55], v[228:231], v[194:197]
	v_mfma_f32_16x16x32_bf16 v[48:51], v[56:59], v[228:231], v[198:201]
	v_mfma_f32_16x16x32_bf16 v[44:47], v[244:247], v[232:235], v[204:207]
	v_mfma_f32_16x16x32_bf16 v[40:43], v[248:251], v[232:235], v[208:211]
	v_mfma_f32_16x16x32_bf16 v[36:39], v[52:55], v[232:235], v[212:215]
	v_mfma_f32_16x16x32_bf16 v[32:35], v[56:59], v[232:235], v[216:219]
	v_mfma_f32_16x16x32_bf16 v[28:31], v[244:247], v[236:239], v[220:223]
	v_mfma_f32_16x16x32_bf16 v[24:27], v[248:251], v[236:239], v[224:227]
	v_mfma_f32_16x16x32_bf16 v[20:23], v[52:55], v[236:239], v[16:19]
	v_mfma_f32_16x16x32_bf16 v[16:19], v[56:59], v[236:239], v[12:15]
	v_mfma_f32_16x16x32_bf16 v[12:15], v[244:247], v[240:243], v[8:11]
	v_mfma_f32_16x16x32_bf16 v[8:11], v[248:251], v[240:243], v[4:7]
	v_mfma_f32_16x16x32_bf16 v[0:3], v[52:55], v[240:243], v[0:3]
	v_mfma_f32_16x16x32_bf16 v[4:7], v[56:59], v[240:243], v[140:143]
	v_xor_b32_e32 v240, 32, v203

.LBB0_487:
	s_waitcnt lgkmcnt(0)
	s_barrier
	ds_read_b128 v[224:227], v184
	ds_read_b128 v[228:231], v184 offset:1024
	ds_read_b128 v[232:235], v184 offset:2048
	ds_read_b128 v[236:239], v184 offset:3072
	ds_read_b128 v[190:193], v185
	ds_read_b128 v[194:197], v185 offset:1024
	ds_read_b128 v[198:201], v185 offset:2048
	ds_read_b128 v[204:207], v185 offset:3072
	ds_read_b128 v[208:211], v185 offset:4096
	ds_read_b128 v[212:215], v185 offset:5120
	ds_read_b128 v[216:219], v185 offset:6144
	ds_read_b128 v[220:223], v185 offset:7168
	s_movk_i32 vcc_lo, 0x6000
	s_cmp_eq_u32 m0, 2
	s_cselect_b32 vcc_lo, 0xffff4000, vcc_lo
	s_add_u32 m0, m0, 1
	s_cmp_eq_u32 m0, 3
	s_cselect_b32 m0, 0, m0
	v_add_u32_e32 v185, vcc_lo, v185
	v_add_u32_e32 v184, vcc_lo, v184
	v_xor_b32_e32 v185, 64, v185
	v_xor_b32_e32 v184, 64, v184
	s_waitcnt lgkmcnt(7)
	v_mfma_f32_16x16x32_bf16 v[172:175], v[224:227], v[190:193], v[172:175]
	v_mfma_f32_16x16x32_bf16 v[168:171], v[228:231], v[190:193], v[168:171]
	v_mfma_f32_16x16x32_bf16 v[164:167], v[232:235], v[190:193], v[164:167]
	v_mfma_f32_16x16x32_bf16 v[156:159], v[236:239], v[190:193], v[156:159]
	ds_read_b128 v[190:193], v185
	s_waitcnt lgkmcnt(7)
	v_mfma_f32_16x16x32_bf16 v[144:147], v[224:227], v[194:197], v[144:147]
	v_mfma_f32_16x16x32_bf16 v[136:139], v[228:231], v[194:197], v[136:139]
	v_mfma_f32_16x16x32_bf16 v[132:135], v[232:235], v[194:197], v[132:135]
	v_mfma_f32_16x16x32_bf16 v[120:123], v[236:239], v[194:197], v[120:123]
	ds_read_b128 v[194:197], v185 offset:1024
	s_waitcnt lgkmcnt(7)
	v_mfma_f32_16x16x32_bf16 v[112:115], v[224:227], v[198:201], v[112:115]
	v_mfma_f32_16x16x32_bf16 v[108:111], v[228:231], v[198:201], v[108:111]
	v_mfma_f32_16x16x32_bf16 v[96:99], v[232:235], v[198:201], v[96:99]
	v_mfma_f32_16x16x32_bf16 v[92:95], v[236:239], v[198:201], v[92:95]
	ds_read_b128 v[198:201], v185 offset:2048
	s_waitcnt lgkmcnt(7)
	v_mfma_f32_16x16x32_bf16 v[88:91], v[224:227], v[204:207], v[88:91]
	v_mfma_f32_16x16x32_bf16 v[80:83], v[228:231], v[204:207], v[80:83]
	v_mfma_f32_16x16x32_bf16 v[72:75], v[232:235], v[204:207], v[72:75]
	v_mfma_f32_16x16x32_bf16 v[68:71], v[236:239], v[204:207], v[68:71]
	ds_read_b128 v[204:207], v185 offset:3072
	s_waitcnt lgkmcnt(7)
	v_mfma_f32_16x16x32_bf16 v[60:63], v[224:227], v[208:211], v[60:63]
	v_mfma_f32_16x16x32_bf16 v[52:55], v[228:231], v[208:211], v[52:55]
	v_mfma_f32_16x16x32_bf16 v[48:51], v[232:235], v[208:211], v[48:51]
	v_mfma_f32_16x16x32_bf16 v[44:47], v[236:239], v[208:211], v[44:47]
	ds_read_b128 v[208:211], v185 offset:4096
	s_waitcnt lgkmcnt(7)
	v_mfma_f32_16x16x32_bf16 v[40:43], v[224:227], v[212:215], v[40:43]
	v_mfma_f32_16x16x32_bf16 v[36:39], v[228:231], v[212:215], v[36:39]
	v_mfma_f32_16x16x32_bf16 v[32:35], v[232:235], v[212:215], v[32:35]
	v_mfma_f32_16x16x32_bf16 v[28:31], v[236:239], v[212:215], v[28:31]
	ds_read_b128 v[212:215], v185 offset:5120
	s_waitcnt lgkmcnt(7)
	v_mfma_f32_16x16x32_bf16 v[24:27], v[224:227], v[216:219], v[24:27]
	v_mfma_f32_16x16x32_bf16 v[20:23], v[228:231], v[216:219], v[20:23]
	v_mfma_f32_16x16x32_bf16 v[16:19], v[232:235], v[216:219], v[16:19]
	v_mfma_f32_16x16x32_bf16 v[12:15], v[236:239], v[216:219], v[12:15]
	ds_read_b128 v[216:219], v185 offset:6144
	s_waitcnt lgkmcnt(7)
	v_mfma_f32_16x16x32_bf16 v[8:11], v[224:227], v[220:223], v[8:11]
	v_mfma_f32_16x16x32_bf16 v[4:7], v[228:231], v[220:223], v[4:7]
	v_mfma_f32_16x16x32_bf16 v[0:3], v[232:235], v[220:223], v[0:3]
	v_mfma_f32_16x16x32_bf16 v[116:119], v[236:239], v[220:223], v[116:119]
	ds_read_b128 v[220:223], v185 offset:7168
	ds_read_b128 v[224:227], v184
	ds_read_b128 v[228:231], v184 offset:1024
	ds_read_b128 v[232:235], v184 offset:2048
	ds_read_b128 v[236:239], v184 offset:3072
	s_movk_i32 vcc_lo, 0x6000
	s_cmp_eq_u32 m0, 2
	s_cselect_b32 vcc_lo, 0xffff4000, vcc_lo
	s_add_u32 m0, m0, 1
	s_cmp_eq_u32 m0, 3
	s_cselect_b32 m0, 0, m0
	v_add_u32_e32 v185, vcc_lo, v185
	v_add_u32_e32 v184, vcc_lo, v184
	v_xor_b32_e32 v185, 64, v185
	v_xor_b32_e32 v184, 64, v184
	s_sub_u32 vcc_lo, s30, s98
	v_add_u32_e32 v186, vcc_lo, v178
	v_add_u32_e32 v187, vcc_lo, v180
	s_barrier
	s_waitcnt lgkmcnt(0)
	v_mfma_f32_16x16x32_bf16 v[172:175], v[224:227], v[190:193], v[172:175]
	s_waitcnt vmcnt(11)
	v_mfma_f32_16x16x32_bf16 v[168:171], v[228:231], v[190:193], v[168:171]
	ds_write_b128 v183, v[160:163]
	v_add_u32_e32 v160, s26, v186
	v_mfma_f32_16x16x32_bf16 v[164:167], v[232:235], v[190:193], v[164:167]
	global_load_dwordx4 v[160:163], v160, s[98:99] offset:128
	v_mfma_f32_16x16x32_bf16 v[156:159], v[236:239], v[190:193], v[156:159]
	s_waitcnt vmcnt(11)
	ds_write_b128 v183, v[152:155] offset:2048
	v_mfma_f32_16x16x32_bf16 v[144:147], v[224:227], v[194:197], v[144:147]
	v_add_u32_e32 v152, s27, v186
	v_mfma_f32_16x16x32_bf16 v[136:139], v[228:231], v[194:197], v[136:139]
	global_load_dwordx4 v[152:155], v152, s[98:99] offset:128
	s_waitcnt vmcnt(11)
	v_mfma_f32_16x16x32_bf16 v[132:135], v[232:235], v[194:197], v[132:135]
	ds_write_b128 v183, v[148:151] offset:4096
	v_mfma_f32_16x16x32_bf16 v[120:123], v[236:239], v[194:197], v[120:123]
	v_add_u32_e32 v148, s20, v186
	global_load_dwordx4 v[148:151], v148, s[98:99] offset:128
	v_mfma_f32_16x16x32_bf16 v[112:115], v[224:227], v[198:201], v[112:115]
	s_waitcnt vmcnt(11)
	v_mfma_f32_16x16x32_bf16 v[108:111], v[228:231], v[198:201], v[108:111]
	ds_write_b128 v183, v[128:131] offset:6144
	v_add_u32_e32 v128, s21, v186
	v_mfma_f32_16x16x32_bf16 v[96:99], v[232:235], v[198:201], v[96:99]
	global_load_dwordx4 v[128:131], v128, s[98:99] offset:128
	v_mfma_f32_16x16x32_bf16 v[92:95], v[236:239], v[198:201], v[92:95]
	s_waitcnt vmcnt(11)
	ds_write_b128 v183, v[124:127] offset:8192
	v_mfma_f32_16x16x32_bf16 v[88:91], v[224:227], v[204:207], v[88:91]
	v_add_u32_e32 v124, s56, v186
	v_mfma_f32_16x16x32_bf16 v[80:83], v[228:231], v[204:207], v[80:83]
	global_load_dwordx4 v[124:127], v124, s[98:99] offset:128
	s_waitcnt vmcnt(11)
	v_mfma_f32_16x16x32_bf16 v[72:75], v[232:235], v[204:207], v[72:75]
	ds_write_b128 v183, v[104:107] offset:10240
	v_mfma_f32_16x16x32_bf16 v[68:71], v[236:239], v[204:207], v[68:71]
	v_add_u32_e32 v104, s57, v186
	global_load_dwordx4 v[104:107], v104, s[98:99] offset:128
	v_mfma_f32_16x16x32_bf16 v[60:63], v[224:227], v[208:211], v[60:63]
	s_waitcnt vmcnt(11)
	v_mfma_f32_16x16x32_bf16 v[52:55], v[228:231], v[208:211], v[52:55]
	ds_write_b128 v183, v[100:103] offset:12288
	v_add_u32_e32 v100, s24, v186
	v_mfma_f32_16x16x32_bf16 v[48:51], v[232:235], v[208:211], v[48:51]
	global_load_dwordx4 v[100:103], v100, s[98:99] offset:128
	v_mfma_f32_16x16x32_bf16 v[44:47], v[236:239], v[208:211], v[44:47]
	s_waitcnt vmcnt(11)
	ds_write_b128 v183, v[84:87] offset:14336
	v_mfma_f32_16x16x32_bf16 v[40:43], v[224:227], v[212:215], v[40:43]
	v_add_u32_e32 v84, s96, v186
	v_mfma_f32_16x16x32_bf16 v[36:39], v[228:231], v[212:215], v[36:39]
	global_load_dwordx4 v[84:87], v84, s[98:99] offset:128
	s_waitcnt vmcnt(11)
	v_mfma_f32_16x16x32_bf16 v[32:35], v[232:235], v[212:215], v[32:35]
	ds_write_b128 v183, v[140:143] offset:16384
	v_mfma_f32_16x16x32_bf16 v[28:31], v[236:239], v[212:215], v[28:31]
	v_add_u32_e32 v140, 0x1800000, v187
	global_load_dwordx4 v[140:143], v140, s[98:99] offset:128
	v_mfma_f32_16x16x32_bf16 v[24:27], v[224:227], v[216:219], v[24:27]
	s_waitcnt vmcnt(11)
	v_mfma_f32_16x16x32_bf16 v[20:23], v[228:231], v[216:219], v[20:23]
	ds_write_b128 v183, v[76:79] offset:18432
	v_add_u32_e32 v76, 0x1810000, v187
	v_mfma_f32_16x16x32_bf16 v[16:19], v[232:235], v[216:219], v[16:19]
	global_load_dwordx4 v[76:79], v76, s[98:99] offset:128
	v_mfma_f32_16x16x32_bf16 v[12:15], v[236:239], v[216:219], v[12:15]
	s_waitcnt vmcnt(11)
	ds_write_b128 v183, v[64:67] offset:20480
	v_mfma_f32_16x16x32_bf16 v[8:11], v[224:227], v[220:223], v[8:11]
	v_add_u32_e32 v64, 0x1820000, v187
	v_mfma_f32_16x16x32_bf16 v[4:7], v[228:231], v[220:223], v[4:7]
	global_load_dwordx4 v[64:67], v64, s[98:99] offset:128
	s_waitcnt vmcnt(11)
	v_mfma_f32_16x16x32_bf16 v[0:3], v[232:235], v[220:223], v[0:3]
	ds_write_b128 v183, v[56:59] offset:22528
	v_mfma_f32_16x16x32_bf16 v[116:119], v[236:239], v[220:223], v[116:119]
	v_add_u32_e32 v56, 0x1830000, v187
	global_load_dwordx4 v[56:59], v56, s[98:99] offset:128
	v_cmp_gt_u32_e32 vcc, 0x6000, v183
	v_add_u32_e32 v182, 0xc000, v183
	v_add_u32_e32 v183, 0xffffa000, v183
	s_nop 0
	v_cndmask_b32_e32 v183, v183, v182, vcc
	s_add_u32 s30, s30, 0x80
	s_addc_u32 s31, s31, 0
	s_cmpk_lg_i32 s30, 0x780
	s_cbranch_scc1 .LBB0_487
	s_waitcnt lgkmcnt(0)
	s_barrier
	ds_read_b128 v[224:227], v184
	ds_read_b128 v[228:231], v184 offset:1024
	ds_read_b128 v[232:235], v184 offset:2048
	ds_read_b128 v[236:239], v184 offset:3072
	ds_read_b128 v[190:193], v185
	ds_read_b128 v[194:197], v185 offset:1024
	ds_read_b128 v[198:201], v185 offset:2048
	ds_read_b128 v[204:207], v185 offset:3072
	ds_read_b128 v[208:211], v185 offset:4096
	ds_read_b128 v[212:215], v185 offset:5120
	ds_read_b128 v[216:219], v185 offset:6144
	ds_read_b128 v[220:223], v185 offset:7168
	s_movk_i32 vcc_lo, 0x6000
	s_cmp_eq_u32 m0, 2
	s_cselect_b32 vcc_lo, 0xffff4000, vcc_lo
	s_add_u32 m0, m0, 1
	s_cmp_eq_u32 m0, 3
	s_cselect_b32 m0, 0, m0
	v_add_u32_e32 v185, vcc_lo, v185
	v_add_u32_e32 v184, vcc_lo, v184
	v_xor_b32_e32 v185, 64, v185
	v_xor_b32_e32 v184, 64, v184
	s_waitcnt lgkmcnt(7)
	v_mfma_f32_16x16x32_bf16 v[172:175], v[224:227], v[190:193], v[172:175]
	v_mfma_f32_16x16x32_bf16 v[168:171], v[228:231], v[190:193], v[168:171]
	v_mfma_f32_16x16x32_bf16 v[164:167], v[232:235], v[190:193], v[164:167]
	v_mfma_f32_16x16x32_bf16 v[156:159], v[236:239], v[190:193], v[156:159]
	ds_read_b128 v[190:193], v185
	s_waitcnt lgkmcnt(7)
	v_mfma_f32_16x16x32_bf16 v[144:147], v[224:227], v[194:197], v[144:147]
	v_mfma_f32_16x16x32_bf16 v[136:139], v[228:231], v[194:197], v[136:139]
	v_mfma_f32_16x16x32_bf16 v[132:135], v[232:235], v[194:197], v[132:135]
	v_mfma_f32_16x16x32_bf16 v[120:123], v[236:239], v[194:197], v[120:123]
	ds_read_b128 v[194:197], v185 offset:1024
	s_waitcnt lgkmcnt(7)
	v_mfma_f32_16x16x32_bf16 v[112:115], v[224:227], v[198:201], v[112:115]
	v_mfma_f32_16x16x32_bf16 v[108:111], v[228:231], v[198:201], v[108:111]
	v_mfma_f32_16x16x32_bf16 v[96:99], v[232:235], v[198:201], v[96:99]
	v_mfma_f32_16x16x32_bf16 v[92:95], v[236:239], v[198:201], v[92:95]
	ds_read_b128 v[198:201], v185 offset:2048
	s_waitcnt lgkmcnt(7)
	v_mfma_f32_16x16x32_bf16 v[88:91], v[224:227], v[204:207], v[88:91]
	v_mfma_f32_16x16x32_bf16 v[80:83], v[228:231], v[204:207], v[80:83]
	v_mfma_f32_16x16x32_bf16 v[72:75], v[232:235], v[204:207], v[72:75]
	v_mfma_f32_16x16x32_bf16 v[68:71], v[236:239], v[204:207], v[68:71]
	ds_read_b128 v[204:207], v185 offset:3072
	s_waitcnt lgkmcnt(7)
	v_mfma_f32_16x16x32_bf16 v[60:63], v[224:227], v[208:211], v[60:63]
	v_mfma_f32_16x16x32_bf16 v[52:55], v[228:231], v[208:211], v[52:55]
	v_mfma_f32_16x16x32_bf16 v[48:51], v[232:235], v[208:211], v[48:51]
	v_mfma_f32_16x16x32_bf16 v[44:47], v[236:239], v[208:211], v[44:47]
	ds_read_b128 v[208:211], v185 offset:4096
	s_waitcnt lgkmcnt(7)
	v_mfma_f32_16x16x32_bf16 v[40:43], v[224:227], v[212:215], v[40:43]
	v_mfma_f32_16x16x32_bf16 v[36:39], v[228:231], v[212:215], v[36:39]
	v_mfma_f32_16x16x32_bf16 v[32:35], v[232:235], v[212:215], v[32:35]
	v_mfma_f32_16x16x32_bf16 v[28:31], v[236:239], v[212:215], v[28:31]
	ds_read_b128 v[212:215], v185 offset:5120
	s_waitcnt lgkmcnt(7)
	v_mfma_f32_16x16x32_bf16 v[24:27], v[224:227], v[216:219], v[24:27]
	v_mfma_f32_16x16x32_bf16 v[20:23], v[228:231], v[216:219], v[20:23]
	v_mfma_f32_16x16x32_bf16 v[16:19], v[232:235], v[216:219], v[16:19]
	v_mfma_f32_16x16x32_bf16 v[12:15], v[236:239], v[216:219], v[12:15]
	ds_read_b128 v[216:219], v185 offset:6144
	s_waitcnt lgkmcnt(7)
	v_mfma_f32_16x16x32_bf16 v[8:11], v[224:227], v[220:223], v[8:11]
	v_mfma_f32_16x16x32_bf16 v[4:7], v[228:231], v[220:223], v[4:7]
	v_mfma_f32_16x16x32_bf16 v[0:3], v[232:235], v[220:223], v[0:3]
	v_mfma_f32_16x16x32_bf16 v[116:119], v[236:239], v[220:223], v[116:119]
	ds_read_b128 v[220:223], v185 offset:7168
	ds_read_b128 v[224:227], v184
	ds_read_b128 v[228:231], v184 offset:1024
	ds_read_b128 v[232:235], v184 offset:2048
	ds_read_b128 v[236:239], v184 offset:3072
	s_movk_i32 vcc_lo, 0x6000
	s_cmp_eq_u32 m0, 2
	s_cselect_b32 vcc_lo, 0xffff4000, vcc_lo
	s_add_u32 m0, m0, 1
	s_cmp_eq_u32 m0, 3
	s_cselect_b32 m0, 0, m0
	v_add_u32_e32 v185, vcc_lo, v185
	v_add_u32_e32 v184, vcc_lo, v184
	v_xor_b32_e32 v185, 64, v185
	v_xor_b32_e32 v184, 64, v184
	s_waitcnt lgkmcnt(0)
	v_mfma_f32_16x16x32_bf16 v[172:175], v[224:227], v[190:193], v[172:175]
	v_mfma_f32_16x16x32_bf16 v[168:171], v[228:231], v[190:193], v[168:171]
	v_mfma_f32_16x16x32_bf16 v[164:167], v[232:235], v[190:193], v[164:167]
	v_mfma_f32_16x16x32_bf16 v[156:159], v[236:239], v[190:193], v[156:159]
	v_mfma_f32_16x16x32_bf16 v[144:147], v[224:227], v[194:197], v[144:147]
	v_mfma_f32_16x16x32_bf16 v[136:139], v[228:231], v[194:197], v[136:139]
	v_mfma_f32_16x16x32_bf16 v[132:135], v[232:235], v[194:197], v[132:135]
	v_mfma_f32_16x16x32_bf16 v[120:123], v[236:239], v[194:197], v[120:123]
	v_mfma_f32_16x16x32_bf16 v[112:115], v[224:227], v[198:201], v[112:115]
	v_mfma_f32_16x16x32_bf16 v[108:111], v[228:231], v[198:201], v[108:111]
	v_mfma_f32_16x16x32_bf16 v[96:99], v[232:235], v[198:201], v[96:99]
	v_mfma_f32_16x16x32_bf16 v[92:95], v[236:239], v[198:201], v[92:95]
	v_mfma_f32_16x16x32_bf16 v[88:91], v[224:227], v[204:207], v[88:91]
	v_mfma_f32_16x16x32_bf16 v[80:83], v[228:231], v[204:207], v[80:83]
	v_mfma_f32_16x16x32_bf16 v[72:75], v[232:235], v[204:207], v[72:75]
	v_mfma_f32_16x16x32_bf16 v[68:71], v[236:239], v[204:207], v[68:71]
	v_mfma_f32_16x16x32_bf16 v[60:63], v[224:227], v[208:211], v[60:63]
	v_mfma_f32_16x16x32_bf16 v[52:55], v[228:231], v[208:211], v[52:55]
	v_mfma_f32_16x16x32_bf16 v[48:51], v[232:235], v[208:211], v[48:51]
	v_mfma_f32_16x16x32_bf16 v[44:47], v[236:239], v[208:211], v[44:47]
	v_mfma_f32_16x16x32_bf16 v[40:43], v[224:227], v[212:215], v[40:43]
	v_mfma_f32_16x16x32_bf16 v[36:39], v[228:231], v[212:215], v[36:39]
	v_mfma_f32_16x16x32_bf16 v[32:35], v[232:235], v[212:215], v[32:35]
	v_mfma_f32_16x16x32_bf16 v[28:31], v[236:239], v[212:215], v[28:31]
	v_mfma_f32_16x16x32_bf16 v[24:27], v[224:227], v[216:219], v[24:27]
	v_mfma_f32_16x16x32_bf16 v[20:23], v[228:231], v[216:219], v[20:23]
	v_mfma_f32_16x16x32_bf16 v[16:19], v[232:235], v[216:219], v[16:19]
	v_mfma_f32_16x16x32_bf16 v[12:15], v[236:239], v[216:219], v[12:15]
	v_mfma_f32_16x16x32_bf16 v[8:11], v[224:227], v[220:223], v[8:11]
	v_mfma_f32_16x16x32_bf16 v[4:7], v[228:231], v[220:223], v[4:7]
	v_mfma_f32_16x16x32_bf16 v[0:3], v[232:235], v[220:223], v[0:3]
	v_mfma_f32_16x16x32_bf16 v[116:119], v[236:239], v[220:223], v[116:119]
	v_lshrrev_b32_e32 v224, 4, v188
	v_and_b32_e32 v225, 7, v188
	v_bitop3_b32 v226, v224, v225, 3 bitop3:0x6c
	v_lshlrev_b32_e32 v227, 7, v188
	v_bfe_u32 v228, v188, 4, 2
	v_and_b32_e32 v229, 0xffffc780, v227
	v_and_b32_e32 v227, 0x2780, v227
	v_bitop3_b32 v228, v228, v225, 4 bitop3:0x36
	v_lshlrev_b32_e32 v226, 4, v226
	v_lshlrev_b32_e32 v228, 4, v228
	v_or_b32_e32 v185, v229, v226
	v_or_b32_e32 v184, v227, v226
	v_or_b32_e32 v183, v229, v228
	v_or_b32_e32 v182, v227, v228
	s_waitcnt vmcnt(0)
	s_barrier
	s_waitcnt vmcnt(11)
	ds_write_b128 v176, v[160:163]
	s_waitcnt vmcnt(10)
	ds_write_b128 v176, v[152:155] offset:4096
	s_waitcnt vmcnt(9)
	ds_write_b128 v176, v[148:151] offset:8192
	s_waitcnt vmcnt(8)
	ds_write_b128 v176, v[128:131] offset:12288
	s_waitcnt vmcnt(7)
	ds_write_b128 v176, v[124:127] offset:16384
	s_waitcnt vmcnt(6)
	ds_write_b128 v176, v[104:107] offset:20480
	s_waitcnt vmcnt(5)
	ds_write_b128 v176, v[100:103] offset:24576
	s_waitcnt vmcnt(4)
	ds_write_b128 v176, v[84:87] offset:28672
	s_waitcnt vmcnt(3)
	ds_write_b128 v176, v[140:143] offset:32768
	s_waitcnt vmcnt(2)
	ds_write_b128 v176, v[76:79] offset:36864
	s_waitcnt vmcnt(1)
	ds_write_b128 v176, v[64:67] offset:40960
	s_waitcnt vmcnt(0)
	ds_write_b128 v176, v[56:59] offset:45056
	s_waitcnt lgkmcnt(0)
	s_barrier
	ds_read_b128 v[56:59], v185
	ds_read_b128 v[64:67], v185 offset:2048
	ds_read_b128 v[76:79], v185 offset:4096
	ds_read_b128 v[84:87], v185 offset:6144
	ds_read_b128 v[100:103], v185 offset:8192
	ds_read_b128 v[104:107], v185 offset:10240
	ds_read_b128 v[124:127], v185 offset:12288
	ds_read_b128 v[128:131], v185 offset:14336
	ds_read_b128 v[140:143], v184 offset:32768
	ds_read_b128 v[148:151], v184 offset:34816
	ds_read_b128 v[152:155], v184 offset:36864
	ds_read_b128 v[160:163], v184 offset:38912
	s_waitcnt lgkmcnt(3)
	v_mfma_f32_16x16x32_bf16 v[172:175], v[140:143], v[56:59], v[172:175]
	s_waitcnt lgkmcnt(2)
	v_mfma_f32_16x16x32_bf16 v[168:171], v[148:151], v[56:59], v[168:171]
	s_waitcnt lgkmcnt(1)
	v_mfma_f32_16x16x32_bf16 v[164:167], v[152:155], v[56:59], v[164:167]
	s_waitcnt lgkmcnt(0)
	v_mfma_f32_16x16x32_bf16 v[56:59], v[160:163], v[56:59], v[156:159]
	v_mfma_f32_16x16x32_bf16 v[144:147], v[140:143], v[64:67], v[144:147]
	v_mfma_f32_16x16x32_bf16 v[136:139], v[148:151], v[64:67], v[136:139]
	v_mfma_f32_16x16x32_bf16 v[132:135], v[152:155], v[64:67], v[132:135]
	v_mfma_f32_16x16x32_bf16 v[64:67], v[160:163], v[64:67], v[120:123]
	v_mfma_f32_16x16x32_bf16 v[156:159], v[140:143], v[76:79], v[112:115]
	v_mfma_f32_16x16x32_bf16 v[178:181], v[148:151], v[76:79], v[108:111]
	v_mfma_f32_16x16x32_bf16 v[184:187], v[152:155], v[76:79], v[96:99]
	v_mfma_f32_16x16x32_bf16 v[76:79], v[160:163], v[76:79], v[92:95]
	v_mfma_f32_16x16x32_bf16 v[60:63], v[140:143], v[100:103], v[60:63]
	v_mfma_f32_16x16x32_bf16 v[52:55], v[148:151], v[100:103], v[52:55]
	v_mfma_f32_16x16x32_bf16 v[48:51], v[152:155], v[100:103], v[48:51]
	v_mfma_f32_16x16x32_bf16 v[44:47], v[160:163], v[100:103], v[44:47]
	v_mfma_f32_16x16x32_bf16 v[40:43], v[140:143], v[104:107], v[40:43]
	v_mfma_f32_16x16x32_bf16 v[36:39], v[148:151], v[104:107], v[36:39]
	v_mfma_f32_16x16x32_bf16 v[32:35], v[152:155], v[104:107], v[32:35]
	v_mfma_f32_16x16x32_bf16 v[28:31], v[160:163], v[104:107], v[28:31]
	v_mfma_f32_16x16x32_bf16 v[24:27], v[140:143], v[124:127], v[24:27]
	v_mfma_f32_16x16x32_bf16 v[20:23], v[148:151], v[124:127], v[20:23]
	v_mfma_f32_16x16x32_bf16 v[16:19], v[152:155], v[124:127], v[16:19]
	v_mfma_f32_16x16x32_bf16 v[12:15], v[160:163], v[124:127], v[12:15]
	v_mfma_f32_16x16x32_bf16 v[8:11], v[140:143], v[128:131], v[8:11]
	v_mfma_f32_16x16x32_bf16 v[4:7], v[148:151], v[128:131], v[4:7]
	v_mfma_f32_16x16x32_bf16 v[0:3], v[152:155], v[128:131], v[0:3]
	v_mfma_f32_16x16x32_bf16 v[190:193], v[140:143], v[84:87], v[88:91]
	v_mfma_f32_16x16x32_bf16 v[194:197], v[148:151], v[84:87], v[80:83]
	v_mfma_f32_16x16x32_bf16 v[198:201], v[152:155], v[84:87], v[72:75]
	v_mfma_f32_16x16x32_bf16 v[204:207], v[160:163], v[84:87], v[68:71]
	v_mfma_f32_16x16x32_bf16 v[140:143], v[160:163], v[128:131], v[116:119]
	s_nop 1
	ds_read_b128 v[68:71], v183
	ds_read_b128 v[72:75], v183 offset:2048
	ds_read_b128 v[80:83], v183 offset:4096
	ds_read_b128 v[128:131], v183 offset:6144
	ds_read_b128 v[148:151], v183 offset:8192
	ds_read_b128 v[152:155], v183 offset:10240
	ds_read_b128 v[160:163], v183 offset:12288
	ds_read_b128 v[208:211], v183 offset:14336
	ds_read_b128 v[212:215], v182 offset:32768
	ds_read_b128 v[216:219], v182 offset:34816
	ds_read_b128 v[220:223], v182 offset:36864
	ds_read_b128 v[224:227], v182 offset:38912
	s_waitcnt lgkmcnt(3)
	v_mfma_f32_16x16x32_bf16 v[124:127], v[212:215], v[68:71], v[172:175]
	s_movk_i32 s30, 0x6c0
	s_waitcnt lgkmcnt(2)
	v_mfma_f32_16x16x32_bf16 v[120:123], v[216:219], v[68:71], v[168:171]
	s_waitcnt lgkmcnt(1)
	v_mfma_f32_16x16x32_bf16 v[116:119], v[220:223], v[68:71], v[164:167]
	s_waitcnt lgkmcnt(0)
	v_mfma_f32_16x16x32_bf16 v[112:115], v[224:227], v[68:71], v[56:59]
	v_mfma_f32_16x16x32_bf16 v[108:111], v[212:215], v[72:75], v[144:147]
	v_mfma_f32_16x16x32_bf16 v[104:107], v[216:219], v[72:75], v[136:139]
	v_mfma_f32_16x16x32_bf16 v[100:103], v[220:223], v[72:75], v[132:135]
	v_mfma_f32_16x16x32_bf16 v[96:99], v[224:227], v[72:75], v[64:67]
	v_mfma_f32_16x16x32_bf16 v[92:95], v[212:215], v[80:83], v[156:159]
	v_mfma_f32_16x16x32_bf16 v[88:91], v[216:219], v[80:83], v[178:181]
	v_mfma_f32_16x16x32_bf16 v[84:87], v[220:223], v[80:83], v[184:187]
	v_mfma_f32_16x16x32_bf16 v[80:83], v[224:227], v[80:83], v[76:79]
	v_mfma_f32_16x16x32_bf16 v[76:79], v[212:215], v[128:131], v[190:193]
	v_mfma_f32_16x16x32_bf16 v[72:75], v[216:219], v[128:131], v[194:197]
	v_mfma_f32_16x16x32_bf16 v[68:71], v[220:223], v[128:131], v[198:201]
	v_mfma_f32_16x16x32_bf16 v[64:67], v[224:227], v[128:131], v[204:207]
	v_mov_b32_e32 v128, v188
	v_mov_b32_e32 v129, v188
	v_mfma_f32_16x16x32_bf16 v[60:63], v[212:215], v[148:151], v[60:63]
	s_nop 0
	v_and_or_b32 v134, v129, 64, s41
	v_mfma_f32_16x16x32_bf16 v[56:59], v[216:219], v[148:151], v[52:55]
	v_cmp_gt_i32_e32 vcc, s30, v134
	v_mfma_f32_16x16x32_bf16 v[52:55], v[220:223], v[148:151], v[48:51]
	v_mfma_f32_16x16x32_bf16 v[48:51], v[224:227], v[148:151], v[44:47]
	v_mfma_f32_16x16x32_bf16 v[44:47], v[212:215], v[152:155], v[40:43]
	v_mfma_f32_16x16x32_bf16 v[40:43], v[216:219], v[152:155], v[36:39]
	v_mfma_f32_16x16x32_bf16 v[36:39], v[220:223], v[152:155], v[32:35]
	v_mfma_f32_16x16x32_bf16 v[32:35], v[224:227], v[152:155], v[28:31]
	v_mfma_f32_16x16x32_bf16 v[28:31], v[212:215], v[160:163], v[24:27]
	v_mfma_f32_16x16x32_bf16 v[24:27], v[216:219], v[160:163], v[20:23]
	v_mfma_f32_16x16x32_bf16 v[20:23], v[220:223], v[160:163], v[16:19]
	v_mfma_f32_16x16x32_bf16 v[16:19], v[224:227], v[160:163], v[12:15]
	v_mfma_f32_16x16x32_bf16 v[12:15], v[212:215], v[208:211], v[8:11]
	v_mfma_f32_16x16x32_bf16 v[8:11], v[216:219], v[208:211], v[4:7]
	v_mfma_f32_16x16x32_bf16 v[4:7], v[220:223], v[208:211], v[0:3]
	v_mfma_f32_16x16x32_bf16 v[0:3], v[224:227], v[208:211], v[140:143]
	s_and_saveexec_b64 s[92:93], vcc
	s_cbranch_execz .LBB0_485
	v_and_b32_e32 v130, 0xffffff80, v129
	v_add_u32_e32 v183, s40, v130
	s_movk_i32 s30, 0xfff
	v_cmp_lt_i32_e64 s[48:49], s30, v183
	s_movk_i32 s30, 0x1000
	v_cmp_gt_i32_e64 s[44:45], s30, v183
	v_add_u32_e32 v130, 0xfffff000, v183
	v_bfe_u32 v141, v128, 4, 2
	s_movk_i32 s30, 0x27f
	v_ashrrev_i32_e32 v135, 10, v130
	v_ashrrev_i32_e32 v132, 8, v183
	v_cmp_lt_i32_e64 s[52:53], s30, v134
	s_movk_i32 s30, 0x280
	v_lshlrev_b32_e32 v130, 4, v141
	v_mov_b32_e32 v131, v177
	v_and_b32_e32 v140, 0x80, v129
	v_cmp_ne_u32_e64 s[50:51], s30, v134
	v_lshl_add_u64 v[138:139], s[84:85], 0, v[130:131]
	v_lshl_add_u64 v[136:137], s[82:83], 0, v[130:131]
	v_lshlrev_b32_e32 v130, 9, v132
	v_readlane_b32 s30, v255, 49
	v_and_b32_e32 v182, 15, v128
	v_and_b32_e32 v181, 0x380, v183
	v_or3_b32 v178, v130, s30, v140
	v_lshlrev_b32_e32 v130, 3, v132
	v_ashrrev_i32_e32 v131, 31, v130
	v_lshlrev_b64 v[132:133], 8, v[130:131]
	v_lshlrev_b32_e32 v130, 3, v135
	s_movk_i32 s30, 0x500
	v_bfe_u32 v129, v128, 4, 1
	v_lshrrev_b32_e32 v128, 2, v128
	v_mad_i64_i32 v[130:131], s[30:31], v130, s30, 0
	v_mov_b32_e32 v176, v134
	v_cmp_eq_u32_e64 s[40:41], 0, v129
	v_lshlrev_b32_e32 v180, 4, v129
	v_and_b32_e32 v179, 8, v128
	v_lshlrev_b32_e32 v128, 2, v141
	v_mov_b32_e32 v129, v177
	v_or_b32_e32 v132, v132, v140
	v_or_b32_e32 v130, v130, v181
	v_cmp_lt_i32_e64 s[46:47], s97, v134
	v_cmp_eq_u32_e64 s[42:43], 0, v141
	v_or_b32_e32 v140, v183, v182
	s_and_saveexec_b64 s[30:31], s[52:53]
	s_xor_b64 s[94:95], exec, s[30:31]
	s_cbranch_execz .LBB0_513
	s_and_saveexec_b64 s[30:31], s[50:51]
	s_xor_b64 s[30:31], exec, s[30:31]
	s_cbranch_execz .LBB0_492
	v_mul_f32_e32 v142, 0xbfb8aa3b, v124
	v_mul_f32_e32 v144, 0xbfb8aa3b, v120
	v_mul_f32_e32 v145, 0xbfb8aa3b, v125
	v_exp_f32_e32 v142, v142
	v_exp_f32_e32 v144, v144
	v_exp_f32_e32 v145, v145
	v_mul_f32_e32 v146, 0xbfb8aa3b, v121
	v_add_f32_e32 v142, 1.0, v142
	v_add_f32_e32 v144, 1.0, v144
	v_add_f32_e32 v145, 1.0, v145
	v_rcp_f32_e32 v142, v142
	v_rcp_f32_e32 v144, v144
	v_rcp_f32_e32 v145, v145
	v_exp_f32_e32 v146, v146
	v_mul_f32_e32 v142, v124, v142
	v_mul_f32_e32 v144, v120, v144
	v_mul_f32_e32 v145, v125, v145
	v_add_f32_e32 v120, 1.0, v146
	v_mul_f32_e32 v124, 0xbfb8aa3b, v126
	v_mul_f32_e32 v125, 0xbfb8aa3b, v122
	v_rcp_f32_e32 v120, v120
	v_exp_f32_e32 v124, v124
	v_exp_f32_e32 v125, v125
	v_ashrrev_i32_e32 v141, 31, v140
	v_mul_f32_e32 v146, v121, v120
	v_add_f32_e32 v120, 1.0, v124
	v_add_f32_e32 v121, 1.0, v125
	v_mul_f32_e32 v124, 0xbfb8aa3b, v127
	v_mul_f32_e32 v125, 0xbfb8aa3b, v123
	v_exp_f32_e32 v124, v124
	v_exp_f32_e32 v125, v125
	v_rcp_f32_e32 v120, v120
	v_rcp_f32_e32 v121, v121
	v_add_f32_e32 v124, 1.0, v124
	v_add_f32_e32 v125, 1.0, v125
	v_rcp_f32_e32 v124, v124
	v_rcp_f32_e32 v125, v125
	v_lshlrev_b64 v[140:141], 11, v[140:141]
	v_cmp_lt_i32_e32 vcc, v189, v202
	v_mul_f32_e32 v126, v126, v120
	v_mul_f32_e32 v122, v122, v121
	v_cndmask_b32_e32 v143, v203, v189, vcc
	v_mul_f32_e32 v127, v127, v124
	v_mul_f32_e32 v123, v123, v125
	v_lshl_add_u64 v[120:121], s[34:35], 0, v[140:141]
	v_lshlrev_b32_e32 v143, 2, v143
	v_lshl_add_u64 v[124:125], v[176:177], 1, v[120:121]
	v_cndmask_b32_e64 v120, v142, v144, s[40:41]
	v_cndmask_b32_e64 v121, v145, v146, s[40:41]
	v_cndmask_b32_e64 v140, v126, v122, s[40:41]
	v_cndmask_b32_e64 v141, v127, v123, s[40:41]
	ds_bpermute_b32 v120, v143, v120
	ds_bpermute_b32 v121, v143, v121
	ds_bpermute_b32 v140, v143, v140
	ds_bpermute_b32 v141, v143, v141
	s_mov_b32 s58, 0x96ff000
	s_waitcnt lgkmcnt(3)
	v_cndmask_b32_e64 v142, v120, v142, s[40:41]
	v_cndmask_b32_e64 v144, v144, v120, s[40:41]
	s_waitcnt lgkmcnt(2)
	v_cndmask_b32_e64 v120, v121, v145, s[40:41]
	v_cndmask_b32_e64 v145, v146, v121, s[40:41]
	s_waitcnt lgkmcnt(1)
	v_cndmask_b32_e64 v121, v140, v126, s[40:41]
	v_cndmask_b32_e64 v126, v122, v140, s[40:41]
	s_waitcnt lgkmcnt(0)
	v_cndmask_b32_e64 v123, v123, v141, s[40:41]
	v_cndmask_b32_e64 v122, v141, v127, s[40:41]
	v_cvt_pk_bf16_f32 v123, v126, v123
	v_lshlrev_b32_e32 v126, 1, v180
	v_mov_b32_e32 v127, v177
	v_lshlrev_b32_e32 v140, 1, v179
	v_mov_b32_e32 v141, v177
	v_lshl_add_u64 v[124:125], v[124:125], 0, v[126:127]
	v_lshl_add_u64 v[124:125], v[124:125], 0, v[140:141]
	v_add_co_u32_e32 v124, vcc, s58, v124
	v_cvt_pk_bf16_f32 v120, v142, v120
	v_cvt_pk_bf16_f32 v121, v121, v122
	v_cvt_pk_bf16_f32 v122, v144, v145
	v_addc_co_u32_e32 v125, vcc, 0, v125, vcc
	v_mul_f32_e32 v126, 0xbfb8aa3b, v116
	global_store_dwordx4 v[124:125], v[120:123], off offset:2688
	v_exp_f32_e32 v126, v126
	s_nop 0
	v_mul_f32_e32 v121, 0xbfb8aa3b, v112
	v_mul_f32_e32 v122, 0xbfb8aa3b, v117
	v_exp_f32_e32 v121, v121
	v_exp_f32_e32 v122, v122
	v_add_f32_e32 v120, 1.0, v126
	v_mul_f32_e32 v123, 0xbfb8aa3b, v113
	v_add_f32_e32 v121, 1.0, v121
	v_add_f32_e32 v122, 1.0, v122
	v_rcp_f32_e32 v120, v120
	v_rcp_f32_e32 v121, v121
	v_rcp_f32_e32 v122, v122
	v_exp_f32_e32 v123, v123
	v_mul_f32_e32 v116, v116, v120
	v_mul_f32_e32 v112, v112, v121
	v_mul_f32_e32 v117, v117, v122
	v_add_f32_e32 v120, 1.0, v123
	v_mul_f32_e32 v121, 0xbfb8aa3b, v118
	v_mul_f32_e32 v122, 0xbfb8aa3b, v114
	v_rcp_f32_e32 v120, v120
	v_exp_f32_e32 v121, v121
	v_exp_f32_e32 v122, v122
	v_mul_f32_e32 v123, 0xbfb8aa3b, v115
	v_mul_f32_e32 v113, v113, v120
	v_add_f32_e32 v120, 1.0, v121
	v_add_f32_e32 v121, 1.0, v122
	v_mul_f32_e32 v122, 0xbfb8aa3b, v119
	v_exp_f32_e32 v122, v122
	v_exp_f32_e32 v123, v123
	v_rcp_f32_e32 v120, v120
	v_rcp_f32_e32 v121, v121
	v_add_f32_e32 v122, 1.0, v122
	v_add_f32_e32 v123, 1.0, v123
	v_rcp_f32_e32 v122, v122
	v_rcp_f32_e32 v123, v123
	v_mul_f32_e32 v118, v118, v120
	v_mul_f32_e32 v114, v114, v121
	v_mul_f32_e32 v119, v119, v122
	v_mul_f32_e32 v115, v115, v123
	v_cndmask_b32_e64 v120, v116, v112, s[40:41]
	v_cndmask_b32_e64 v121, v117, v113, s[40:41]
	v_cndmask_b32_e64 v122, v118, v114, s[40:41]
	v_cndmask_b32_e64 v123, v119, v115, s[40:41]
	ds_bpermute_b32 v120, v143, v120
	ds_bpermute_b32 v121, v143, v121
	ds_bpermute_b32 v122, v143, v122
	ds_bpermute_b32 v123, v143, v123
	s_waitcnt lgkmcnt(3)
	v_cndmask_b32_e64 v116, v120, v116, s[40:41]
	v_cndmask_b32_e64 v120, v112, v120, s[40:41]
	s_waitcnt lgkmcnt(2)
	v_cndmask_b32_e64 v112, v121, v117, s[40:41]
	v_cndmask_b32_e64 v117, v113, v121, s[40:41]
	s_waitcnt lgkmcnt(1)
	v_cndmask_b32_e64 v113, v122, v118, s[40:41]
	v_cndmask_b32_e64 v118, v114, v122, s[40:41]
	s_waitcnt lgkmcnt(0)
	v_cndmask_b32_e64 v114, v123, v119, s[40:41]
	v_cndmask_b32_e64 v115, v115, v123, s[40:41]
	v_cvt_pk_bf16_f32 v112, v116, v112
	v_cvt_pk_bf16_f32 v113, v113, v114
	v_cvt_pk_bf16_f32 v114, v120, v117
	v_cvt_pk_bf16_f32 v115, v118, v115
	global_store_dwordx4 v[124:125], v[112:115], off offset:2752

.LBB0_802:
	s_waitcnt lgkmcnt(0)
	s_barrier
	ds_read_b128 v[224:227], v184
	ds_read_b128 v[228:231], v184 offset:1024
	ds_read_b128 v[232:235], v184 offset:2048
	ds_read_b128 v[236:239], v184 offset:3072
	ds_read_b128 v[190:193], v185
	ds_read_b128 v[194:197], v185 offset:1024
	ds_read_b128 v[198:201], v185 offset:2048
	ds_read_b128 v[204:207], v185 offset:3072
	ds_read_b128 v[208:211], v185 offset:4096
	ds_read_b128 v[212:215], v185 offset:5120
	ds_read_b128 v[216:219], v185 offset:6144
	ds_read_b128 v[220:223], v185 offset:7168
	s_movk_i32 vcc_lo, 0x6000
	s_cmp_eq_u32 m0, 2
	s_cselect_b32 vcc_lo, 0xffff4000, vcc_lo
	s_add_u32 m0, m0, 1
	s_cmp_eq_u32 m0, 3
	s_cselect_b32 m0, 0, m0
	v_add_u32_e32 v185, vcc_lo, v185
	v_add_u32_e32 v184, vcc_lo, v184
	v_xor_b32_e32 v185, 64, v185
	v_xor_b32_e32 v184, 64, v184
	s_waitcnt lgkmcnt(7)
	v_mfma_f32_16x16x32_bf16 v[172:175], v[224:227], v[190:193], v[172:175]
	v_mfma_f32_16x16x32_bf16 v[168:171], v[228:231], v[190:193], v[168:171]
	v_mfma_f32_16x16x32_bf16 v[164:167], v[232:235], v[190:193], v[164:167]
	v_mfma_f32_16x16x32_bf16 v[160:163], v[236:239], v[190:193], v[160:163]
	ds_read_b128 v[190:193], v185
	s_waitcnt lgkmcnt(7)
	v_mfma_f32_16x16x32_bf16 v[156:159], v[224:227], v[194:197], v[156:159]
	v_mfma_f32_16x16x32_bf16 v[152:155], v[228:231], v[194:197], v[152:155]
	v_mfma_f32_16x16x32_bf16 v[148:151], v[232:235], v[194:197], v[148:151]
	v_mfma_f32_16x16x32_bf16 v[144:147], v[236:239], v[194:197], v[144:147]
	ds_read_b128 v[194:197], v185 offset:1024
	s_waitcnt lgkmcnt(7)
	v_mfma_f32_16x16x32_bf16 v[136:139], v[224:227], v[198:201], v[136:139]
	v_mfma_f32_16x16x32_bf16 v[132:135], v[228:231], v[198:201], v[132:135]
	v_mfma_f32_16x16x32_bf16 v[128:131], v[232:235], v[198:201], v[128:131]
	v_mfma_f32_16x16x32_bf16 v[124:127], v[236:239], v[198:201], v[124:127]
	ds_read_b128 v[198:201], v185 offset:2048
	s_waitcnt lgkmcnt(7)
	v_mfma_f32_16x16x32_bf16 v[120:123], v[224:227], v[204:207], v[120:123]
	v_mfma_f32_16x16x32_bf16 v[108:111], v[228:231], v[204:207], v[108:111]
	v_mfma_f32_16x16x32_bf16 v[100:103], v[232:235], v[204:207], v[100:103]
	v_mfma_f32_16x16x32_bf16 v[96:99], v[236:239], v[204:207], v[96:99]
	ds_read_b128 v[204:207], v185 offset:3072
	s_waitcnt lgkmcnt(7)
	v_mfma_f32_16x16x32_bf16 v[92:95], v[224:227], v[208:211], v[92:95]
	v_mfma_f32_16x16x32_bf16 v[84:87], v[228:231], v[208:211], v[84:87]
	v_mfma_f32_16x16x32_bf16 v[76:79], v[232:235], v[208:211], v[76:79]
	v_mfma_f32_16x16x32_bf16 v[72:75], v[236:239], v[208:211], v[72:75]
	ds_read_b128 v[208:211], v185 offset:4096
	s_waitcnt lgkmcnt(7)
	v_mfma_f32_16x16x32_bf16 v[64:67], v[224:227], v[212:215], v[64:67]
	v_mfma_f32_16x16x32_bf16 v[52:55], v[228:231], v[212:215], v[52:55]
	v_mfma_f32_16x16x32_bf16 v[48:51], v[232:235], v[212:215], v[48:51]
	v_mfma_f32_16x16x32_bf16 v[44:47], v[236:239], v[212:215], v[44:47]
	ds_read_b128 v[212:215], v185 offset:5120
	s_waitcnt lgkmcnt(7)
	v_mfma_f32_16x16x32_bf16 v[36:39], v[224:227], v[216:219], v[36:39]
	v_mfma_f32_16x16x32_bf16 v[28:31], v[228:231], v[216:219], v[28:31]
	v_mfma_f32_16x16x32_bf16 v[24:27], v[232:235], v[216:219], v[24:27]
	v_mfma_f32_16x16x32_bf16 v[20:23], v[236:239], v[216:219], v[20:23]
	ds_read_b128 v[216:219], v185 offset:6144
	s_waitcnt lgkmcnt(7)
	v_mfma_f32_16x16x32_bf16 v[12:15], v[224:227], v[220:223], v[12:15]
	v_mfma_f32_16x16x32_bf16 v[4:7], v[228:231], v[220:223], v[4:7]
	v_mfma_f32_16x16x32_bf16 v[0:3], v[232:235], v[220:223], v[0:3]
	v_mfma_f32_16x16x32_bf16 v[140:143], v[236:239], v[220:223], v[140:143]
	ds_read_b128 v[220:223], v185 offset:7168
	ds_read_b128 v[224:227], v184
	ds_read_b128 v[228:231], v184 offset:1024
	ds_read_b128 v[232:235], v184 offset:2048
	ds_read_b128 v[236:239], v184 offset:3072
	s_movk_i32 vcc_lo, 0x6000
	s_cmp_eq_u32 m0, 2
	s_cselect_b32 vcc_lo, 0xffff4000, vcc_lo
	s_add_u32 m0, m0, 1
	s_cmp_eq_u32 m0, 3
	s_cselect_b32 m0, 0, m0
	v_add_u32_e32 v185, vcc_lo, v185
	v_add_u32_e32 v184, vcc_lo, v184
	v_xor_b32_e32 v185, 64, v185
	v_xor_b32_e32 v184, 64, v184
	s_sub_u32 vcc_lo, s6, s98
	v_add_u32_e32 v186, vcc_lo, v178
	v_add_u32_e32 v187, vcc_lo, v180
	s_barrier
	s_waitcnt lgkmcnt(0)
	v_mfma_f32_16x16x32_bf16 v[172:175], v[224:227], v[190:193], v[172:175]
	s_waitcnt vmcnt(11)
	v_mfma_f32_16x16x32_bf16 v[168:171], v[228:231], v[190:193], v[168:171]
	ds_write_b128 v183, v[116:119]
	v_add_u32_e32 v116, s26, v187
	v_mfma_f32_16x16x32_bf16 v[164:167], v[232:235], v[190:193], v[164:167]
	global_load_dwordx4 v[116:119], v116, s[98:99] offset:128
	v_mfma_f32_16x16x32_bf16 v[160:163], v[236:239], v[190:193], v[160:163]
	s_waitcnt vmcnt(11)
	ds_write_b128 v183, v[112:115] offset:2048
	v_mfma_f32_16x16x32_bf16 v[156:159], v[224:227], v[194:197], v[156:159]
	v_add_u32_e32 v112, s27, v187
	v_mfma_f32_16x16x32_bf16 v[152:155], v[228:231], v[194:197], v[152:155]
	global_load_dwordx4 v[112:115], v112, s[98:99] offset:128
	s_waitcnt vmcnt(11)
	v_mfma_f32_16x16x32_bf16 v[148:151], v[232:235], v[194:197], v[148:151]
	ds_write_b128 v183, v[104:107] offset:4096
	v_mfma_f32_16x16x32_bf16 v[144:147], v[236:239], v[194:197], v[144:147]
	v_add_u32_e32 v104, s20, v187
	global_load_dwordx4 v[104:107], v104, s[98:99] offset:128
	v_mfma_f32_16x16x32_bf16 v[136:139], v[224:227], v[198:201], v[136:139]
	s_waitcnt vmcnt(11)
	v_mfma_f32_16x16x32_bf16 v[132:135], v[228:231], v[198:201], v[132:135]
	ds_write_b128 v183, v[88:91] offset:6144
	v_add_u32_e32 v88, s21, v187
	v_mfma_f32_16x16x32_bf16 v[128:131], v[232:235], v[198:201], v[128:131]
	global_load_dwordx4 v[88:91], v88, s[98:99] offset:128
	v_mfma_f32_16x16x32_bf16 v[124:127], v[236:239], v[198:201], v[124:127]
	s_waitcnt vmcnt(11)
	ds_write_b128 v183, v[80:83] offset:8192
	v_mfma_f32_16x16x32_bf16 v[120:123], v[224:227], v[204:207], v[120:123]
	v_add_u32_e32 v80, s56, v187
	v_mfma_f32_16x16x32_bf16 v[108:111], v[228:231], v[204:207], v[108:111]
	global_load_dwordx4 v[80:83], v80, s[98:99] offset:128
	s_waitcnt vmcnt(11)
	v_mfma_f32_16x16x32_bf16 v[100:103], v[232:235], v[204:207], v[100:103]
	ds_write_b128 v183, v[68:71] offset:10240
	v_mfma_f32_16x16x32_bf16 v[96:99], v[236:239], v[204:207], v[96:99]
	v_add_u32_e32 v68, s57, v187
	global_load_dwordx4 v[68:71], v68, s[98:99] offset:128
	v_mfma_f32_16x16x32_bf16 v[92:95], v[224:227], v[208:211], v[92:95]
	s_waitcnt vmcnt(11)
	v_mfma_f32_16x16x32_bf16 v[84:87], v[228:231], v[208:211], v[84:87]
	ds_write_b128 v183, v[60:63] offset:12288
	v_add_u32_e32 v60, s24, v187
	v_mfma_f32_16x16x32_bf16 v[76:79], v[232:235], v[208:211], v[76:79]
	global_load_dwordx4 v[60:63], v60, s[98:99] offset:128
	v_mfma_f32_16x16x32_bf16 v[72:75], v[236:239], v[208:211], v[72:75]
	s_waitcnt vmcnt(11)
	ds_write_b128 v183, v[40:43] offset:14336
	v_mfma_f32_16x16x32_bf16 v[64:67], v[224:227], v[212:215], v[64:67]
	v_add_u32_e32 v40, s96, v187
	v_mfma_f32_16x16x32_bf16 v[52:55], v[228:231], v[212:215], v[52:55]
	global_load_dwordx4 v[40:43], v40, s[98:99] offset:128
	s_waitcnt vmcnt(11)
	v_mfma_f32_16x16x32_bf16 v[48:51], v[232:235], v[212:215], v[48:51]
	ds_write_b128 v183, v[56:59] offset:16384
	v_mfma_f32_16x16x32_bf16 v[44:47], v[236:239], v[212:215], v[44:47]
	v_mov_b32_e32 v56, v186
	global_load_dwordx4 v[56:59], v56, s[98:99] offset:128
	v_mfma_f32_16x16x32_bf16 v[36:39], v[224:227], v[216:219], v[36:39]
	s_waitcnt vmcnt(11)
	v_mfma_f32_16x16x32_bf16 v[28:31], v[228:231], v[216:219], v[28:31]
	ds_write_b128 v183, v[32:35] offset:18432
	v_add_u32_e32 v32, s13, v186
	v_mfma_f32_16x16x32_bf16 v[24:27], v[232:235], v[216:219], v[24:27]
	global_load_dwordx4 v[32:35], v32, s[98:99] offset:128
	v_mfma_f32_16x16x32_bf16 v[20:23], v[236:239], v[216:219], v[20:23]
	s_waitcnt vmcnt(11)
	ds_write_b128 v183, v[16:19] offset:20480
	v_mfma_f32_16x16x32_bf16 v[12:15], v[224:227], v[220:223], v[12:15]
	v_add_u32_e32 v16, s12, v186
	v_mfma_f32_16x16x32_bf16 v[4:7], v[228:231], v[220:223], v[4:7]
	global_load_dwordx4 v[16:19], v16, s[98:99] offset:128
	s_waitcnt vmcnt(11)
	v_mfma_f32_16x16x32_bf16 v[0:3], v[232:235], v[220:223], v[0:3]
	ds_write_b128 v183, v[8:11] offset:22528
	v_mfma_f32_16x16x32_bf16 v[140:143], v[236:239], v[220:223], v[140:143]
	v_add_u32_e32 v8, s11, v186
	global_load_dwordx4 v[8:11], v8, s[98:99] offset:128
	v_cmp_gt_u32_e32 vcc, 0x6000, v183
	v_add_u32_e32 v182, 0xc000, v183
	v_add_u32_e32 v183, 0xffffa000, v183
	s_nop 0
	v_cndmask_b32_e32 v183, v183, v182, vcc
	s_add_u32 s6, s6, 0x80
	s_addc_u32 s7, s7, 0
	s_cmpk_lg_i32 s6, 0x780
	s_cbranch_scc1 .LBB0_802
	s_waitcnt lgkmcnt(0)
	s_barrier
	ds_read_b128 v[224:227], v184
	ds_read_b128 v[228:231], v184 offset:1024
	ds_read_b128 v[232:235], v184 offset:2048
	ds_read_b128 v[236:239], v184 offset:3072
	ds_read_b128 v[190:193], v185
	ds_read_b128 v[194:197], v185 offset:1024
	ds_read_b128 v[198:201], v185 offset:2048
	ds_read_b128 v[204:207], v185 offset:3072
	ds_read_b128 v[208:211], v185 offset:4096
	ds_read_b128 v[212:215], v185 offset:5120
	ds_read_b128 v[216:219], v185 offset:6144
	ds_read_b128 v[220:223], v185 offset:7168
	s_movk_i32 vcc_lo, 0x6000
	s_cmp_eq_u32 m0, 2
	s_cselect_b32 vcc_lo, 0xffff4000, vcc_lo
	s_add_u32 m0, m0, 1
	s_cmp_eq_u32 m0, 3
	s_cselect_b32 m0, 0, m0
	v_add_u32_e32 v185, vcc_lo, v185
	v_add_u32_e32 v184, vcc_lo, v184
	v_xor_b32_e32 v185, 64, v185
	v_xor_b32_e32 v184, 64, v184
	s_waitcnt lgkmcnt(7)
	v_mfma_f32_16x16x32_bf16 v[172:175], v[224:227], v[190:193], v[172:175]
	v_mfma_f32_16x16x32_bf16 v[168:171], v[228:231], v[190:193], v[168:171]
	v_mfma_f32_16x16x32_bf16 v[164:167], v[232:235], v[190:193], v[164:167]
	v_mfma_f32_16x16x32_bf16 v[160:163], v[236:239], v[190:193], v[160:163]
	ds_read_b128 v[190:193], v185
	s_waitcnt lgkmcnt(7)
	v_mfma_f32_16x16x32_bf16 v[156:159], v[224:227], v[194:197], v[156:159]
	v_mfma_f32_16x16x32_bf16 v[152:155], v[228:231], v[194:197], v[152:155]
	v_mfma_f32_16x16x32_bf16 v[148:151], v[232:235], v[194:197], v[148:151]
	v_mfma_f32_16x16x32_bf16 v[144:147], v[236:239], v[194:197], v[144:147]
	ds_read_b128 v[194:197], v185 offset:1024
	s_waitcnt lgkmcnt(7)
	v_mfma_f32_16x16x32_bf16 v[136:139], v[224:227], v[198:201], v[136:139]
	v_mfma_f32_16x16x32_bf16 v[132:135], v[228:231], v[198:201], v[132:135]
	v_mfma_f32_16x16x32_bf16 v[128:131], v[232:235], v[198:201], v[128:131]
	v_mfma_f32_16x16x32_bf16 v[124:127], v[236:239], v[198:201], v[124:127]
	ds_read_b128 v[198:201], v185 offset:2048
	s_waitcnt lgkmcnt(7)
	v_mfma_f32_16x16x32_bf16 v[120:123], v[224:227], v[204:207], v[120:123]
	v_mfma_f32_16x16x32_bf16 v[108:111], v[228:231], v[204:207], v[108:111]
	v_mfma_f32_16x16x32_bf16 v[100:103], v[232:235], v[204:207], v[100:103]
	v_mfma_f32_16x16x32_bf16 v[96:99], v[236:239], v[204:207], v[96:99]
	ds_read_b128 v[204:207], v185 offset:3072
	s_waitcnt lgkmcnt(7)
	v_mfma_f32_16x16x32_bf16 v[92:95], v[224:227], v[208:211], v[92:95]
	v_mfma_f32_16x16x32_bf16 v[84:87], v[228:231], v[208:211], v[84:87]
	v_mfma_f32_16x16x32_bf16 v[76:79], v[232:235], v[208:211], v[76:79]
	v_mfma_f32_16x16x32_bf16 v[72:75], v[236:239], v[208:211], v[72:75]
	ds_read_b128 v[208:211], v185 offset:4096
	s_waitcnt lgkmcnt(7)
	v_mfma_f32_16x16x32_bf16 v[64:67], v[224:227], v[212:215], v[64:67]
	v_mfma_f32_16x16x32_bf16 v[52:55], v[228:231], v[212:215], v[52:55]
	v_mfma_f32_16x16x32_bf16 v[48:51], v[232:235], v[212:215], v[48:51]
	v_mfma_f32_16x16x32_bf16 v[44:47], v[236:239], v[212:215], v[44:47]
	ds_read_b128 v[212:215], v185 offset:5120
	s_waitcnt lgkmcnt(7)
	v_mfma_f32_16x16x32_bf16 v[36:39], v[224:227], v[216:219], v[36:39]
	v_mfma_f32_16x16x32_bf16 v[28:31], v[228:231], v[216:219], v[28:31]
	v_mfma_f32_16x16x32_bf16 v[24:27], v[232:235], v[216:219], v[24:27]
	v_mfma_f32_16x16x32_bf16 v[20:23], v[236:239], v[216:219], v[20:23]
	ds_read_b128 v[216:219], v185 offset:6144
	s_waitcnt lgkmcnt(7)
	v_mfma_f32_16x16x32_bf16 v[12:15], v[224:227], v[220:223], v[12:15]
	v_mfma_f32_16x16x32_bf16 v[4:7], v[228:231], v[220:223], v[4:7]
	v_mfma_f32_16x16x32_bf16 v[0:3], v[232:235], v[220:223], v[0:3]
	v_mfma_f32_16x16x32_bf16 v[140:143], v[236:239], v[220:223], v[140:143]
	ds_read_b128 v[220:223], v185 offset:7168
	ds_read_b128 v[224:227], v184
	ds_read_b128 v[228:231], v184 offset:1024
	ds_read_b128 v[232:235], v184 offset:2048
	ds_read_b128 v[236:239], v184 offset:3072
	s_movk_i32 vcc_lo, 0x6000
	s_cmp_eq_u32 m0, 2
	s_cselect_b32 vcc_lo, 0xffff4000, vcc_lo
	s_add_u32 m0, m0, 1
	s_cmp_eq_u32 m0, 3
	s_cselect_b32 m0, 0, m0
	v_add_u32_e32 v185, vcc_lo, v185
	v_add_u32_e32 v184, vcc_lo, v184
	v_xor_b32_e32 v185, 64, v185
	v_xor_b32_e32 v184, 64, v184
	s_waitcnt lgkmcnt(0)
	v_mfma_f32_16x16x32_bf16 v[172:175], v[224:227], v[190:193], v[172:175]
	v_mfma_f32_16x16x32_bf16 v[168:171], v[228:231], v[190:193], v[168:171]
	v_mfma_f32_16x16x32_bf16 v[164:167], v[232:235], v[190:193], v[164:167]
	v_mfma_f32_16x16x32_bf16 v[160:163], v[236:239], v[190:193], v[160:163]
	v_mfma_f32_16x16x32_bf16 v[156:159], v[224:227], v[194:197], v[156:159]
	v_mfma_f32_16x16x32_bf16 v[152:155], v[228:231], v[194:197], v[152:155]
	v_mfma_f32_16x16x32_bf16 v[148:151], v[232:235], v[194:197], v[148:151]
	v_mfma_f32_16x16x32_bf16 v[144:147], v[236:239], v[194:197], v[144:147]
	v_mfma_f32_16x16x32_bf16 v[136:139], v[224:227], v[198:201], v[136:139]
	v_mfma_f32_16x16x32_bf16 v[132:135], v[228:231], v[198:201], v[132:135]
	v_mfma_f32_16x16x32_bf16 v[128:131], v[232:235], v[198:201], v[128:131]
	v_mfma_f32_16x16x32_bf16 v[124:127], v[236:239], v[198:201], v[124:127]
	v_mfma_f32_16x16x32_bf16 v[120:123], v[224:227], v[204:207], v[120:123]
	v_mfma_f32_16x16x32_bf16 v[108:111], v[228:231], v[204:207], v[108:111]
	v_mfma_f32_16x16x32_bf16 v[100:103], v[232:235], v[204:207], v[100:103]
	v_mfma_f32_16x16x32_bf16 v[96:99], v[236:239], v[204:207], v[96:99]
	v_mfma_f32_16x16x32_bf16 v[92:95], v[224:227], v[208:211], v[92:95]
	v_mfma_f32_16x16x32_bf16 v[84:87], v[228:231], v[208:211], v[84:87]
	v_mfma_f32_16x16x32_bf16 v[76:79], v[232:235], v[208:211], v[76:79]
	v_mfma_f32_16x16x32_bf16 v[72:75], v[236:239], v[208:211], v[72:75]
	v_mfma_f32_16x16x32_bf16 v[64:67], v[224:227], v[212:215], v[64:67]
	v_mfma_f32_16x16x32_bf16 v[52:55], v[228:231], v[212:215], v[52:55]
	v_mfma_f32_16x16x32_bf16 v[48:51], v[232:235], v[212:215], v[48:51]
	v_mfma_f32_16x16x32_bf16 v[44:47], v[236:239], v[212:215], v[44:47]
	v_mfma_f32_16x16x32_bf16 v[36:39], v[224:227], v[216:219], v[36:39]
	v_mfma_f32_16x16x32_bf16 v[28:31], v[228:231], v[216:219], v[28:31]
	v_mfma_f32_16x16x32_bf16 v[24:27], v[232:235], v[216:219], v[24:27]
	v_mfma_f32_16x16x32_bf16 v[20:23], v[236:239], v[216:219], v[20:23]
	v_mfma_f32_16x16x32_bf16 v[12:15], v[224:227], v[220:223], v[12:15]
	v_mfma_f32_16x16x32_bf16 v[4:7], v[228:231], v[220:223], v[4:7]
	v_mfma_f32_16x16x32_bf16 v[0:3], v[232:235], v[220:223], v[0:3]
	v_mfma_f32_16x16x32_bf16 v[140:143], v[236:239], v[220:223], v[140:143]
	v_lshrrev_b32_e32 v224, 4, v188
	v_and_b32_e32 v225, 7, v188
	v_bitop3_b32 v226, v224, v225, 3 bitop3:0x6c
	v_lshlrev_b32_e32 v227, 7, v188
	v_bfe_u32 v228, v188, 4, 2
	v_and_b32_e32 v229, 0xffffc780, v227
	v_and_b32_e32 v227, 0x2780, v227
	v_bitop3_b32 v228, v228, v225, 4 bitop3:0x36
	v_lshlrev_b32_e32 v226, 4, v226
	v_lshlrev_b32_e32 v228, 4, v228
	v_or_b32_e32 v185, v229, v226
	v_or_b32_e32 v184, v227, v226
	v_or_b32_e32 v183, v229, v228
	v_or_b32_e32 v182, v227, v228
	s_waitcnt vmcnt(0)
	s_barrier
	s_waitcnt vmcnt(10)
	ds_write_b128 v176, v[116:119]
	s_waitcnt vmcnt(9)
	ds_write_b128 v176, v[112:115] offset:4096
	s_waitcnt vmcnt(8)
	ds_write_b128 v176, v[104:107] offset:8192
	s_waitcnt vmcnt(7)
	ds_write_b128 v176, v[88:91] offset:12288
	s_waitcnt vmcnt(6)
	ds_write_b128 v176, v[80:83] offset:16384
	s_waitcnt vmcnt(5)
	ds_write_b128 v176, v[68:71] offset:20480
	s_waitcnt vmcnt(4)
	ds_write_b128 v176, v[60:63] offset:24576
	s_waitcnt vmcnt(3)
	ds_write_b128 v176, v[40:43] offset:28672
	ds_write_b128 v176, v[56:59] offset:32768
	s_waitcnt vmcnt(2)
	ds_write_b128 v176, v[32:35] offset:36864
	s_waitcnt vmcnt(1)
	ds_write_b128 v176, v[16:19] offset:40960
	s_waitcnt vmcnt(0)
	ds_write_b128 v176, v[8:11] offset:45056
	s_waitcnt lgkmcnt(0)
	s_barrier
	ds_read_b128 v[8:11], v185
	ds_read_b128 v[16:19], v185 offset:2048
	ds_read_b128 v[32:35], v185 offset:4096
	ds_read_b128 v[40:43], v185 offset:6144
	ds_read_b128 v[56:59], v185 offset:8192
	ds_read_b128 v[60:63], v185 offset:10240
	ds_read_b128 v[68:71], v185 offset:12288
	ds_read_b128 v[80:83], v185 offset:14336
	ds_read_b128 v[88:91], v184 offset:32768
	ds_read_b128 v[104:107], v184 offset:34816
	ds_read_b128 v[112:115], v184 offset:36864
	ds_read_b128 v[116:119], v184 offset:38912
	s_waitcnt lgkmcnt(3)
	v_mfma_f32_16x16x32_bf16 v[172:175], v[88:91], v[8:11], v[172:175]
	s_waitcnt lgkmcnt(2)
	v_mfma_f32_16x16x32_bf16 v[168:171], v[104:107], v[8:11], v[168:171]
	s_waitcnt lgkmcnt(1)
	v_mfma_f32_16x16x32_bf16 v[164:167], v[112:115], v[8:11], v[164:167]
	s_waitcnt lgkmcnt(0)
	v_mfma_f32_16x16x32_bf16 v[8:11], v[116:119], v[8:11], v[160:163]
	v_mfma_f32_16x16x32_bf16 v[156:159], v[88:91], v[16:19], v[156:159]
	v_mfma_f32_16x16x32_bf16 v[152:155], v[104:107], v[16:19], v[152:155]
	v_mfma_f32_16x16x32_bf16 v[148:151], v[112:115], v[16:19], v[148:151]
	v_mfma_f32_16x16x32_bf16 v[16:19], v[116:119], v[16:19], v[144:147]
	v_mfma_f32_16x16x32_bf16 v[136:139], v[88:91], v[32:35], v[136:139]
	v_mfma_f32_16x16x32_bf16 v[132:135], v[104:107], v[32:35], v[132:135]
	v_mfma_f32_16x16x32_bf16 v[128:131], v[112:115], v[32:35], v[128:131]
	v_mfma_f32_16x16x32_bf16 v[32:35], v[116:119], v[32:35], v[124:127]
	v_mfma_f32_16x16x32_bf16 v[120:123], v[88:91], v[40:43], v[120:123]
	v_mfma_f32_16x16x32_bf16 v[108:111], v[104:107], v[40:43], v[108:111]
	v_mfma_f32_16x16x32_bf16 v[100:103], v[112:115], v[40:43], v[100:103]
	v_mfma_f32_16x16x32_bf16 v[40:43], v[116:119], v[40:43], v[96:99]
	v_mfma_f32_16x16x32_bf16 v[92:95], v[88:91], v[56:59], v[92:95]
	v_mfma_f32_16x16x32_bf16 v[84:87], v[104:107], v[56:59], v[84:87]
	v_mfma_f32_16x16x32_bf16 v[76:79], v[112:115], v[56:59], v[76:79]
	v_mfma_f32_16x16x32_bf16 v[56:59], v[116:119], v[56:59], v[72:75]
	v_mfma_f32_16x16x32_bf16 v[64:67], v[88:91], v[60:63], v[64:67]
	v_mfma_f32_16x16x32_bf16 v[52:55], v[104:107], v[60:63], v[52:55]
	v_mfma_f32_16x16x32_bf16 v[72:75], v[112:115], v[60:63], v[48:51]
	v_mfma_f32_16x16x32_bf16 v[60:63], v[116:119], v[60:63], v[44:47]
	v_mfma_f32_16x16x32_bf16 v[96:99], v[88:91], v[68:71], v[36:39]
	v_mfma_f32_16x16x32_bf16 v[28:31], v[104:107], v[68:71], v[28:31]
	v_mfma_f32_16x16x32_bf16 v[124:127], v[112:115], v[68:71], v[24:27]
	v_mfma_f32_16x16x32_bf16 v[20:23], v[116:119], v[68:71], v[20:23]
	v_mfma_f32_16x16x32_bf16 v[12:15], v[88:91], v[80:83], v[12:15]
	v_mfma_f32_16x16x32_bf16 v[4:7], v[104:107], v[80:83], v[4:7]
	v_mfma_f32_16x16x32_bf16 v[0:3], v[112:115], v[80:83], v[0:3]
	v_mfma_f32_16x16x32_bf16 v[68:71], v[116:119], v[80:83], v[140:143]
	ds_read_b128 v[24:27], v183
	ds_read_b128 v[36:39], v183 offset:2048
	ds_read_b128 v[44:47], v183 offset:4096
	ds_read_b128 v[80:83], v183 offset:6144
	ds_read_b128 v[88:91], v183 offset:8192
	ds_read_b128 v[104:107], v183 offset:10240
	ds_read_b128 v[112:115], v183 offset:12288
	ds_read_b128 v[116:119], v183 offset:14336
	ds_read_b128 v[140:143], v182 offset:32768
	ds_read_b128 v[144:147], v182 offset:34816
	ds_read_b128 v[160:163], v182 offset:36864
	ds_read_b128 v[178:181], v182 offset:38912
	s_waitcnt lgkmcnt(3)
	v_mfma_f32_16x16x32_bf16 v[172:175], v[140:143], v[24:27], v[172:175]
	v_mov_b32_e32 v49, v188
	v_cmp_lt_i32_e32 vcc, v189, v202
	s_waitcnt lgkmcnt(2)
	v_mfma_f32_16x16x32_bf16 v[168:171], v[144:147], v[24:27], v[168:171]
	v_mov_b32_e32 v48, v188
	v_readlane_b32 s6, v253, 24
	s_waitcnt lgkmcnt(1)
	v_mfma_f32_16x16x32_bf16 v[164:167], v[160:163], v[24:27], v[164:167]
	v_and_b32_e32 v50, 0xffffff80, v48
	v_add_u32_e32 v51, s9, v50
	v_and_or_b32 v50, v48, 64, s10
	s_waitcnt lgkmcnt(0)
	v_mfma_f32_16x16x32_bf16 v[8:11], v[178:181], v[24:27], v[8:11]
	v_bfe_u32 v26, v49, 4, 1
	v_cndmask_b32_e32 v24, v203, v189, vcc
	v_cmp_eq_u32_e32 vcc, 0, v26
	v_lshlrev_b32_e32 v186, 2, v24
	v_mfma_f32_16x16x32_bf16 v[182:185], v[178:181], v[36:39], v[16:19]
	v_and_or_b32 v48, v49, 15, v51
	v_ashrrev_i32_e32 v51, 31, v50
	v_lshl_add_u64 v[50:51], v[50:51], 1, s[4:5]
	v_cndmask_b32_e32 v16, v172, v168, vcc
	v_cndmask_b32_e32 v17, v173, v169, vcc
	v_cndmask_b32_e32 v18, v174, v170, vcc
	v_cndmask_b32_e32 v19, v175, v171, vcc
	ds_bpermute_b32 v16, v186, v16
	ds_bpermute_b32 v17, v186, v17
	ds_bpermute_b32 v18, v186, v18
	ds_bpermute_b32 v19, v186, v19
	v_lshlrev_b32_e32 v176, 5, v26
	v_lshrrev_b32_e32 v27, 1, v49
	v_lshl_add_u64 v[24:25], v[50:51], 0, v[176:177]
	v_and_b32_e32 v176, 16, v27
	v_ashrrev_i32_e32 v49, 31, v48
	v_mfma_f32_16x16x32_bf16 v[156:159], v[140:143], v[36:39], v[156:159]
	v_lshl_add_u64 v[50:51], v[24:25], 0, v[176:177]
	v_lshlrev_b64 v[24:25], 11, v[48:49]
	s_waitcnt lgkmcnt(3)
	v_cndmask_b32_e32 v26, v16, v172, vcc
	v_mfma_f32_16x16x32_bf16 v[152:155], v[144:147], v[36:39], v[152:155]
	v_cndmask_b32_e32 v27, v168, v16, vcc
	s_waitcnt lgkmcnt(2)
	v_cndmask_b32_e32 v16, v17, v173, vcc
	v_lshl_add_u64 v[24:25], v[50:51], 0, v[24:25]
	v_mfma_f32_16x16x32_bf16 v[148:151], v[160:163], v[36:39], v[148:151]
	v_cndmask_b32_e32 v36, v169, v17, vcc
	s_waitcnt lgkmcnt(1)
	v_cndmask_b32_e32 v17, v18, v174, vcc
	v_cvt_pk_bf16_f32 v16, v26, v16
	v_mfma_f32_16x16x32_bf16 v[190:193], v[178:181], v[44:47], v[32:35]
	v_readlane_b32 s7, v253, 25
	s_nop 1
	v_cndmask_b32_e32 v32, v170, v18, vcc
	s_waitcnt lgkmcnt(0)
	v_cndmask_b32_e32 v18, v19, v175, vcc
	v_cndmask_b32_e32 v19, v171, v19, vcc
	v_cvt_pk_bf16_f32 v17, v17, v18
	v_cvt_pk_bf16_f32 v18, v27, v36
	v_cvt_pk_bf16_f32 v19, v32, v19
	global_store_dwordx4 v[24:25], v[16:19], off
	v_mfma_f32_16x16x32_bf16 v[120:123], v[140:143], v[80:83], v[120:123]
	s_nop 0
	v_cndmask_b32_e32 v16, v164, v8, vcc
	v_cndmask_b32_e32 v17, v165, v9, vcc
	v_cndmask_b32_e32 v18, v166, v10, vcc
	v_cndmask_b32_e32 v19, v167, v11, vcc
	ds_bpermute_b32 v16, v186, v16
	ds_bpermute_b32 v17, v186, v17
	ds_bpermute_b32 v18, v186, v18
	ds_bpermute_b32 v19, v186, v19
	v_mfma_f32_16x16x32_bf16 v[108:111], v[144:147], v[80:83], v[108:111]
	s_waitcnt lgkmcnt(3)
	v_cndmask_b32_e32 v26, v16, v164, vcc
	v_cndmask_b32_e32 v16, v8, v16, vcc
	s_waitcnt lgkmcnt(2)
	v_cndmask_b32_e32 v8, v17, v165, vcc
	v_cndmask_b32_e32 v17, v9, v17, vcc
	s_waitcnt lgkmcnt(1)
	v_cndmask_b32_e32 v9, v18, v166, vcc
	v_cndmask_b32_e32 v18, v10, v18, vcc
	s_waitcnt lgkmcnt(0)
	v_cndmask_b32_e32 v10, v19, v167, vcc
	v_cndmask_b32_e32 v11, v11, v19, vcc
	v_cvt_pk_bf16_f32 v8, v26, v8
	v_cvt_pk_bf16_f32 v9, v9, v10
	v_cvt_pk_bf16_f32 v10, v16, v17
	v_cvt_pk_bf16_f32 v11, v18, v11
	global_store_dwordx4 v[24:25], v[8:11], off offset:64
	v_mfma_f32_16x16x32_bf16 v[100:103], v[160:163], v[80:83], v[100:103]
	s_nop 0
	v_or_b32_e32 v8, 16, v48
	v_ashrrev_i32_e32 v9, 31, v8
	v_lshlrev_b64 v[8:9], 11, v[8:9]
	v_mfma_f32_16x16x32_bf16 v[80:83], v[178:181], v[80:83], v[40:43]
	v_cndmask_b32_e32 v10, v158, v154, vcc
	v_cndmask_b32_e32 v11, v159, v155, vcc
	ds_bpermute_b32 v10, v186, v10
	v_mfma_f32_16x16x32_bf16 v[40:43], v[140:143], v[104:107], v[64:67]
	ds_bpermute_b32 v11, v186, v11
	s_nop 1
	v_lshl_add_u64 v[64:65], v[50:51], 0, v[8:9]
	v_cndmask_b32_e32 v8, v156, v152, vcc
	v_cndmask_b32_e32 v9, v157, v153, vcc
	ds_bpermute_b32 v8, v186, v8
	ds_bpermute_b32 v9, v186, v9
	v_mfma_f32_16x16x32_bf16 v[136:139], v[140:143], v[44:47], v[136:139]
	s_waitcnt lgkmcnt(1)
	v_cndmask_b32_e32 v49, v8, v156, vcc
	v_mfma_f32_16x16x32_bf16 v[132:135], v[144:147], v[44:47], v[132:135]
	v_mfma_f32_16x16x32_bf16 v[128:131], v[160:163], v[44:47], v[128:131]
	v_mfma_f32_16x16x32_bf16 v[44:47], v[144:147], v[104:107], v[52:55]
	v_mfma_f32_16x16x32_bf16 v[36:39], v[178:181], v[104:107], v[60:63]
	s_nop 1
	v_cndmask_b32_e32 v54, v152, v8, vcc
	s_waitcnt lgkmcnt(0)
	v_cndmask_b32_e32 v8, v9, v157, vcc
	v_cndmask_b32_e32 v55, v153, v9, vcc
	v_cndmask_b32_e32 v53, v10, v158, vcc
	v_cndmask_b32_e32 v60, v154, v10, vcc
	v_cndmask_b32_e32 v61, v11, v159, vcc
	v_cndmask_b32_e32 v62, v155, v11, vcc
	v_cvt_pk_bf16_f32 v52, v49, v8
	v_cvt_pk_bf16_f32 v53, v53, v61
	v_cvt_pk_bf16_f32 v54, v54, v55
	v_cvt_pk_bf16_f32 v55, v60, v62
	v_mfma_f32_16x16x32_bf16 v[8:11], v[140:143], v[116:119], v[12:15]
	global_store_dwordx4 v[64:65], v[52:55], off
	v_cndmask_b32_e32 v49, v149, v183, vcc
	ds_bpermute_b32 v49, v186, v49
	v_mfma_f32_16x16x32_bf16 v[12:15], v[144:147], v[116:119], v[4:7]
	v_cndmask_b32_e32 v52, v150, v184, vcc
	v_cndmask_b32_e32 v53, v151, v185, vcc
	ds_bpermute_b32 v52, v186, v52
	v_cndmask_b32_e32 v4, v148, v182, vcc
	ds_bpermute_b32 v54, v186, v4
	ds_bpermute_b32 v53, v186, v53
	s_waitcnt lgkmcnt(3)
	v_cndmask_b32_e32 v60, v49, v149, vcc
	v_cndmask_b32_e32 v49, v183, v49, vcc
	s_waitcnt lgkmcnt(2)
	v_cndmask_b32_e32 v61, v52, v150, vcc
	s_waitcnt lgkmcnt(1)
	v_cndmask_b32_e32 v55, v54, v148, vcc
	v_cndmask_b32_e32 v54, v182, v54, vcc
	v_cndmask_b32_e32 v62, v184, v52, vcc
	s_waitcnt lgkmcnt(0)
	v_cndmask_b32_e32 v63, v53, v151, vcc
	v_cndmask_b32_e32 v66, v185, v53, vcc
	v_cvt_pk_bf16_f32 v52, v55, v60
	v_cvt_pk_bf16_f32 v53, v61, v63
	v_cvt_pk_bf16_f32 v54, v54, v49
	v_cvt_pk_bf16_f32 v55, v62, v66
	global_store_dwordx4 v[64:65], v[52:55], off offset:64
	v_cndmask_b32_e32 v49, v136, v132, vcc
	ds_bpermute_b32 v49, v186, v49
	v_or_b32_e32 v52, 32, v48
	v_ashrrev_i32_e32 v53, 31, v52
	v_lshlrev_b64 v[52:53], 11, v[52:53]
	v_lshl_add_u64 v[60:61], v[50:51], 0, v[52:53]
	v_cndmask_b32_e32 v52, v137, v133, vcc
	v_cndmask_b32_e32 v53, v138, v134, vcc
	v_cndmask_b32_e32 v54, v139, v135, vcc
	ds_bpermute_b32 v52, v186, v52
	ds_bpermute_b32 v53, v186, v53
	ds_bpermute_b32 v54, v186, v54
	s_waitcnt lgkmcnt(3)
	v_cndmask_b32_e32 v55, v49, v136, vcc
	v_cndmask_b32_e32 v49, v132, v49, vcc
	s_waitcnt lgkmcnt(2)
	v_cndmask_b32_e32 v62, v52, v137, vcc
	v_cndmask_b32_e32 v63, v133, v52, vcc
	s_waitcnt lgkmcnt(1)
	v_cndmask_b32_e32 v64, v53, v138, vcc
	v_cndmask_b32_e32 v65, v134, v53, vcc
	s_waitcnt lgkmcnt(0)
	v_cndmask_b32_e32 v53, v54, v139, vcc
	v_cndmask_b32_e32 v66, v135, v54, vcc
	v_cvt_pk_bf16_f32 v52, v55, v62
	v_cvt_pk_bf16_f32 v53, v64, v53
	v_cvt_pk_bf16_f32 v54, v49, v63
	v_cvt_pk_bf16_f32 v55, v65, v66
	global_store_dwordx4 v[60:61], v[52:55], off
	v_cndmask_b32_e32 v49, v128, v190, vcc
	ds_bpermute_b32 v49, v186, v49
	v_cndmask_b32_e32 v52, v129, v191, vcc
	v_cndmask_b32_e32 v53, v130, v192, vcc
	v_cndmask_b32_e32 v54, v131, v193, vcc
	ds_bpermute_b32 v52, v186, v52
	ds_bpermute_b32 v53, v186, v53
	ds_bpermute_b32 v54, v186, v54
	s_waitcnt lgkmcnt(3)
	v_cndmask_b32_e32 v55, v49, v128, vcc
	v_cndmask_b32_e32 v49, v190, v49, vcc
	s_waitcnt lgkmcnt(2)
	v_cndmask_b32_e32 v62, v52, v129, vcc
	v_cndmask_b32_e32 v63, v191, v52, vcc
	s_waitcnt lgkmcnt(1)
	v_cndmask_b32_e32 v64, v53, v130, vcc
	v_cndmask_b32_e32 v65, v192, v53, vcc
	s_waitcnt lgkmcnt(0)
	v_cndmask_b32_e32 v53, v54, v131, vcc
	v_cndmask_b32_e32 v66, v193, v54, vcc
	v_cvt_pk_bf16_f32 v52, v55, v62
	v_cvt_pk_bf16_f32 v53, v64, v53
	v_cvt_pk_bf16_f32 v54, v49, v63
	v_cvt_pk_bf16_f32 v55, v65, v66
	global_store_dwordx4 v[60:61], v[52:55], off offset:64
	v_cndmask_b32_e32 v49, v120, v108, vcc
	ds_bpermute_b32 v49, v186, v49
	v_or_b32_e32 v52, 48, v48
	v_ashrrev_i32_e32 v53, 31, v52
	v_lshlrev_b64 v[52:53], 11, v[52:53]
	v_lshl_add_u64 v[60:61], v[50:51], 0, v[52:53]
	v_cndmask_b32_e32 v52, v121, v109, vcc
	v_cndmask_b32_e32 v53, v122, v110, vcc
	v_cndmask_b32_e32 v54, v123, v111, vcc
	ds_bpermute_b32 v52, v186, v52
	ds_bpermute_b32 v53, v186, v53
	ds_bpermute_b32 v54, v186, v54
	s_waitcnt lgkmcnt(3)
	v_cndmask_b32_e32 v55, v49, v120, vcc
	v_cndmask_b32_e32 v49, v108, v49, vcc
	s_waitcnt lgkmcnt(2)
	v_cndmask_b32_e32 v62, v52, v121, vcc
	v_cndmask_b32_e32 v63, v109, v52, vcc
	s_waitcnt lgkmcnt(1)
	v_cndmask_b32_e32 v64, v53, v122, vcc
	v_cndmask_b32_e32 v65, v110, v53, vcc
	s_waitcnt lgkmcnt(0)
	v_cndmask_b32_e32 v53, v54, v123, vcc
	v_cndmask_b32_e32 v66, v111, v54, vcc
	v_cvt_pk_bf16_f32 v52, v55, v62
	v_cvt_pk_bf16_f32 v53, v64, v53
	v_cvt_pk_bf16_f32 v54, v49, v63
	v_cvt_pk_bf16_f32 v55, v65, v66
	global_store_dwordx4 v[60:61], v[52:55], off
	v_cndmask_b32_e32 v49, v100, v80, vcc
	ds_bpermute_b32 v49, v186, v49
	v_cndmask_b32_e32 v52, v101, v81, vcc
	v_cndmask_b32_e32 v53, v102, v82, vcc
	v_cndmask_b32_e32 v54, v103, v83, vcc
	ds_bpermute_b32 v52, v186, v52
	ds_bpermute_b32 v53, v186, v53
	ds_bpermute_b32 v54, v186, v54
	s_waitcnt lgkmcnt(3)
	v_cndmask_b32_e32 v55, v49, v100, vcc
	v_cndmask_b32_e32 v49, v80, v49, vcc
	s_waitcnt lgkmcnt(2)
	v_cndmask_b32_e32 v62, v52, v101, vcc
	v_cndmask_b32_e32 v63, v81, v52, vcc
	s_waitcnt lgkmcnt(1)
	v_cndmask_b32_e32 v64, v53, v102, vcc
	v_cndmask_b32_e32 v65, v82, v53, vcc
	s_waitcnt lgkmcnt(0)
	v_cndmask_b32_e32 v53, v54, v103, vcc
	v_cndmask_b32_e32 v66, v83, v54, vcc
	v_mfma_f32_16x16x32_bf16 v[92:95], v[140:143], v[88:91], v[92:95]
	v_cvt_pk_bf16_f32 v52, v55, v62
	v_cvt_pk_bf16_f32 v53, v64, v53
	v_cvt_pk_bf16_f32 v54, v49, v63
	v_mfma_f32_16x16x32_bf16 v[84:87], v[144:147], v[88:91], v[84:87]
	v_cvt_pk_bf16_f32 v55, v65, v66
	global_store_dwordx4 v[60:61], v[52:55], off offset:64
	v_mfma_f32_16x16x32_bf16 v[76:79], v[160:163], v[88:91], v[76:79]
	s_nop 0
	v_or_b32_e32 v52, 64, v48
	v_ashrrev_i32_e32 v53, 31, v52
	v_lshlrev_b64 v[52:53], 11, v[52:53]
	v_lshl_add_u64 v[60:61], v[50:51], 0, v[52:53]
	v_cndmask_b32_e32 v49, v92, v84, vcc
	v_cndmask_b32_e32 v52, v93, v85, vcc
	v_cndmask_b32_e32 v53, v94, v86, vcc
	v_cndmask_b32_e32 v54, v95, v87, vcc
	ds_bpermute_b32 v49, v186, v49
	ds_bpermute_b32 v52, v186, v52
	ds_bpermute_b32 v53, v186, v53
	ds_bpermute_b32 v54, v186, v54
	v_mfma_f32_16x16x32_bf16 v[56:59], v[178:181], v[88:91], v[56:59]
	s_waitcnt lgkmcnt(3)
	v_cndmask_b32_e32 v55, v49, v92, vcc
	v_cndmask_b32_e32 v49, v84, v49, vcc
	s_waitcnt lgkmcnt(2)
	v_cndmask_b32_e32 v62, v52, v93, vcc
	v_cndmask_b32_e32 v63, v85, v52, vcc
	s_waitcnt lgkmcnt(1)
	v_cndmask_b32_e32 v64, v53, v94, vcc
	v_cndmask_b32_e32 v65, v86, v53, vcc
	s_waitcnt lgkmcnt(0)
	v_cndmask_b32_e32 v53, v54, v95, vcc
	v_cndmask_b32_e32 v66, v87, v54, vcc
	v_cvt_pk_bf16_f32 v52, v55, v62
	v_cvt_pk_bf16_f32 v53, v64, v53
	v_cvt_pk_bf16_f32 v54, v49, v63
	v_cvt_pk_bf16_f32 v55, v65, v66
	global_store_dwordx4 v[60:61], v[52:55], off
	v_cndmask_b32_e32 v49, v76, v56, vcc
	ds_bpermute_b32 v49, v186, v49
	v_cndmask_b32_e32 v52, v77, v57, vcc
	v_cndmask_b32_e32 v53, v78, v58, vcc
	v_cndmask_b32_e32 v54, v79, v59, vcc
	ds_bpermute_b32 v52, v186, v52
	ds_bpermute_b32 v53, v186, v53
	ds_bpermute_b32 v54, v186, v54
	s_waitcnt lgkmcnt(3)
	v_cndmask_b32_e32 v55, v49, v76, vcc
	v_cndmask_b32_e32 v49, v56, v49, vcc
	s_waitcnt lgkmcnt(2)
	v_cndmask_b32_e32 v56, v52, v77, vcc
	v_cndmask_b32_e32 v57, v57, v52, vcc
	s_waitcnt lgkmcnt(1)
	v_cndmask_b32_e32 v62, v53, v78, vcc
	v_cndmask_b32_e32 v58, v58, v53, vcc
	s_waitcnt lgkmcnt(0)
	v_cndmask_b32_e32 v53, v54, v79, vcc
	v_cndmask_b32_e32 v59, v59, v54, vcc
	v_cvt_pk_bf16_f32 v52, v55, v56
	v_cvt_pk_bf16_f32 v53, v62, v53
	v_cvt_pk_bf16_f32 v54, v49, v57
	v_cvt_pk_bf16_f32 v55, v58, v59
	global_store_dwordx4 v[60:61], v[52:55], off offset:64
	v_cndmask_b32_e32 v49, v40, v44, vcc
	v_cndmask_b32_e32 v56, v43, v47, vcc
	v_cndmask_b32_e32 v54, v41, v45, vcc
	v_cndmask_b32_e32 v55, v42, v46, vcc
	ds_bpermute_b32 v49, v186, v49
	ds_bpermute_b32 v54, v186, v54
	ds_bpermute_b32 v55, v186, v55
	ds_bpermute_b32 v56, v186, v56
	v_mfma_f32_16x16x32_bf16 v[32:35], v[160:163], v[104:107], v[72:75]
	v_or_b32_e32 v52, 0x50, v48
	v_ashrrev_i32_e32 v53, 31, v52
	v_lshlrev_b64 v[52:53], 11, v[52:53]
	s_waitcnt lgkmcnt(3)
	v_cndmask_b32_e32 v40, v49, v40, vcc
	v_cndmask_b32_e32 v44, v44, v49, vcc
	s_waitcnt lgkmcnt(2)
	v_cndmask_b32_e32 v41, v54, v41, vcc
	v_cndmask_b32_e32 v45, v45, v54, vcc
	s_waitcnt lgkmcnt(1)
	v_cndmask_b32_e32 v42, v55, v42, vcc
	v_cndmask_b32_e32 v46, v46, v55, vcc
	s_waitcnt lgkmcnt(0)
	v_cndmask_b32_e32 v43, v56, v43, vcc
	v_cndmask_b32_e32 v47, v47, v56, vcc
	v_lshl_add_u64 v[52:53], v[50:51], 0, v[52:53]
	v_cvt_pk_bf16_f32 v40, v40, v41
	v_cvt_pk_bf16_f32 v41, v42, v43
	v_cvt_pk_bf16_f32 v42, v44, v45
	v_cvt_pk_bf16_f32 v43, v46, v47
	global_store_dwordx4 v[52:53], v[40:43], off
	v_mfma_f32_16x16x32_bf16 v[24:27], v[140:143], v[112:115], v[96:99]
	s_nop 0
	v_cndmask_b32_e32 v40, v32, v36, vcc
	v_cndmask_b32_e32 v41, v33, v37, vcc
	v_cndmask_b32_e32 v42, v34, v38, vcc
	v_cndmask_b32_e32 v43, v35, v39, vcc
	ds_bpermute_b32 v40, v186, v40
	ds_bpermute_b32 v41, v186, v41
	ds_bpermute_b32 v42, v186, v42
	ds_bpermute_b32 v43, v186, v43
	v_mfma_f32_16x16x32_bf16 v[28:31], v[144:147], v[112:115], v[28:31]
	s_waitcnt lgkmcnt(3)
	v_cndmask_b32_e32 v32, v40, v32, vcc
	v_cndmask_b32_e32 v36, v36, v40, vcc
	s_waitcnt lgkmcnt(2)
	v_cndmask_b32_e32 v33, v41, v33, vcc
	v_cndmask_b32_e32 v37, v37, v41, vcc
	s_waitcnt lgkmcnt(1)
	v_cndmask_b32_e32 v34, v42, v34, vcc
	v_cndmask_b32_e32 v38, v38, v42, vcc
	s_waitcnt lgkmcnt(0)
	v_cndmask_b32_e32 v35, v43, v35, vcc
	v_cndmask_b32_e32 v39, v39, v43, vcc
	v_cvt_pk_bf16_f32 v32, v32, v33
	v_cvt_pk_bf16_f32 v33, v34, v35
	v_cvt_pk_bf16_f32 v34, v36, v37
	v_cvt_pk_bf16_f32 v35, v38, v39
	global_store_dwordx4 v[52:53], v[32:35], off offset:64
	v_cndmask_b32_e32 v36, v26, v30, vcc
	v_cndmask_b32_e32 v37, v27, v31, vcc
	v_cndmask_b32_e32 v34, v24, v28, vcc
	v_cndmask_b32_e32 v35, v25, v29, vcc
	ds_bpermute_b32 v34, v186, v34
	ds_bpermute_b32 v35, v186, v35
	ds_bpermute_b32 v36, v186, v36
	ds_bpermute_b32 v37, v186, v37
	v_mfma_f32_16x16x32_bf16 v[16:19], v[160:163], v[112:115], v[124:127]
	v_or_b32_e32 v32, 0x60, v48
	v_ashrrev_i32_e32 v33, 31, v32
	v_lshlrev_b64 v[32:33], 11, v[32:33]
	v_mfma_f32_16x16x32_bf16 v[20:23], v[178:181], v[112:115], v[20:23]
	s_waitcnt lgkmcnt(3)
	v_cndmask_b32_e32 v24, v34, v24, vcc
	v_cndmask_b32_e32 v28, v28, v34, vcc
	s_waitcnt lgkmcnt(2)
	v_cndmask_b32_e32 v25, v35, v25, vcc
	v_cndmask_b32_e32 v29, v29, v35, vcc
	s_waitcnt lgkmcnt(1)
	v_cndmask_b32_e32 v26, v36, v26, vcc
	v_cndmask_b32_e32 v30, v30, v36, vcc
	s_waitcnt lgkmcnt(0)
	v_cndmask_b32_e32 v27, v37, v27, vcc
	v_cndmask_b32_e32 v31, v31, v37, vcc
	v_lshl_add_u64 v[32:33], v[50:51], 0, v[32:33]
	v_cvt_pk_bf16_f32 v24, v24, v25
	v_cvt_pk_bf16_f32 v25, v26, v27
	v_cvt_pk_bf16_f32 v26, v28, v29
	v_cvt_pk_bf16_f32 v27, v30, v31
	global_store_dwordx4 v[32:33], v[24:27], off
	v_mfma_f32_16x16x32_bf16 v[0:3], v[160:163], v[116:119], v[0:3]
	s_nop 0
	v_cndmask_b32_e32 v24, v16, v20, vcc
	v_cndmask_b32_e32 v25, v17, v21, vcc
	v_cndmask_b32_e32 v26, v18, v22, vcc
	v_cndmask_b32_e32 v27, v19, v23, vcc
	ds_bpermute_b32 v24, v186, v24
	ds_bpermute_b32 v25, v186, v25
	ds_bpermute_b32 v26, v186, v26
	ds_bpermute_b32 v27, v186, v27
	v_mfma_f32_16x16x32_bf16 v[4:7], v[178:181], v[116:119], v[68:71]
	s_waitcnt lgkmcnt(3)
	v_cndmask_b32_e32 v16, v24, v16, vcc
	v_cndmask_b32_e32 v20, v20, v24, vcc
	s_waitcnt lgkmcnt(2)
	v_cndmask_b32_e32 v17, v25, v17, vcc
	v_cndmask_b32_e32 v21, v21, v25, vcc
	s_waitcnt lgkmcnt(1)
	v_cndmask_b32_e32 v18, v26, v18, vcc
	v_cndmask_b32_e32 v22, v22, v26, vcc
	s_waitcnt lgkmcnt(0)
	v_cndmask_b32_e32 v19, v27, v19, vcc
	v_cndmask_b32_e32 v23, v23, v27, vcc
	v_cvt_pk_bf16_f32 v16, v16, v17
	v_cvt_pk_bf16_f32 v17, v18, v19
	v_cvt_pk_bf16_f32 v18, v20, v21
	v_cvt_pk_bf16_f32 v19, v22, v23
	global_store_dwordx4 v[32:33], v[16:19], off offset:64
	v_cndmask_b32_e32 v20, v10, v14, vcc
	v_cndmask_b32_e32 v21, v11, v15, vcc
	v_cndmask_b32_e32 v18, v8, v12, vcc
	v_cndmask_b32_e32 v19, v9, v13, vcc
	ds_bpermute_b32 v18, v186, v18
	ds_bpermute_b32 v19, v186, v19
	ds_bpermute_b32 v20, v186, v20
	ds_bpermute_b32 v21, v186, v21
	v_or_b32_e32 v16, 0x70, v48
	v_ashrrev_i32_e32 v17, 31, v16
	v_lshlrev_b64 v[16:17], 11, v[16:17]
	s_waitcnt lgkmcnt(3)
	v_cndmask_b32_e32 v8, v18, v8, vcc
	v_cndmask_b32_e32 v12, v12, v18, vcc
	s_waitcnt lgkmcnt(2)
	v_cndmask_b32_e32 v9, v19, v9, vcc
	v_cndmask_b32_e32 v13, v13, v19, vcc
	s_waitcnt lgkmcnt(1)
	v_cndmask_b32_e32 v10, v20, v10, vcc
	v_cndmask_b32_e32 v14, v14, v20, vcc
	s_waitcnt lgkmcnt(0)
	v_cndmask_b32_e32 v11, v21, v11, vcc
	v_cndmask_b32_e32 v15, v15, v21, vcc
	v_lshl_add_u64 v[16:17], v[50:51], 0, v[16:17]
	v_cvt_pk_bf16_f32 v8, v8, v9
	v_cvt_pk_bf16_f32 v9, v10, v11
	v_cvt_pk_bf16_f32 v10, v12, v13
	v_cvt_pk_bf16_f32 v11, v14, v15
	global_store_dwordx4 v[16:17], v[8:11], off
	s_nop 1
	v_cndmask_b32_e32 v8, v0, v4, vcc
	v_cndmask_b32_e32 v9, v1, v5, vcc
	v_cndmask_b32_e32 v10, v2, v6, vcc
	v_cndmask_b32_e32 v11, v3, v7, vcc
	ds_bpermute_b32 v8, v186, v8
	ds_bpermute_b32 v9, v186, v9
	ds_bpermute_b32 v10, v186, v10
	ds_bpermute_b32 v11, v186, v11
	s_waitcnt lgkmcnt(3)
	v_cndmask_b32_e32 v0, v8, v0, vcc
	v_cndmask_b32_e32 v4, v4, v8, vcc
	s_waitcnt lgkmcnt(2)
	v_cndmask_b32_e32 v1, v9, v1, vcc
	v_cndmask_b32_e32 v5, v5, v9, vcc
	s_waitcnt lgkmcnt(1)
	v_cndmask_b32_e32 v2, v10, v2, vcc
	v_cndmask_b32_e32 v6, v6, v10, vcc
	s_waitcnt lgkmcnt(0)
	v_cndmask_b32_e32 v3, v11, v3, vcc
	v_cndmask_b32_e32 v7, v7, v11, vcc
	v_cvt_pk_bf16_f32 v0, v0, v1
	v_cvt_pk_bf16_f32 v1, v2, v3
	v_cvt_pk_bf16_f32 v2, v4, v5
	v_cvt_pk_bf16_f32 v3, v6, v7
	global_store_dwordx4 v[16:17], v[0:3], off offset:64
	s_load_dword s6, s[6:7], 0x0
	s_waitcnt lgkmcnt(0)
	s_add_i32 s8, s6, s8
	s_cmpk_gt_i32 s8, 0xff
	s_cbranch_scc0 .LBB0_801

.LBB0_1066:
	s_waitcnt lgkmcnt(0)
	s_barrier
	ds_read_b128 v[236:239], v184
	ds_read_b128 v[240:243], v184 offset:1024
	ds_read_b128 v[244:247], v184 offset:2048
	ds_read_b128 v[248:251], v184 offset:3072
	ds_read_b128 v[204:207], v185
	ds_read_b128 v[208:211], v185 offset:1024
	ds_read_b128 v[212:215], v185 offset:2048
	ds_read_b128 v[216:219], v185 offset:3072
	ds_read_b128 v[220:223], v185 offset:4096
	ds_read_b128 v[224:227], v185 offset:5120
	ds_read_b128 v[228:231], v185 offset:6144
	ds_read_b128 v[232:235], v185 offset:7168
	s_movk_i32 vcc_lo, 0x6000
	s_cmp_eq_u32 m0, 2
	s_cselect_b32 vcc_lo, 0xffff4000, vcc_lo
	s_add_u32 m0, m0, 1
	s_cmp_eq_u32 m0, 3
	s_cselect_b32 m0, 0, m0
	v_add_u32_e32 v185, vcc_lo, v185
	v_add_u32_e32 v184, vcc_lo, v184
	v_xor_b32_e32 v185, 64, v185
	v_xor_b32_e32 v184, 64, v184
	s_waitcnt lgkmcnt(7)
	v_mfma_f32_16x16x32_bf16 v[172:175], v[236:239], v[204:207], v[172:175]
	v_mfma_f32_16x16x32_bf16 v[168:171], v[240:243], v[204:207], v[168:171]
	v_mfma_f32_16x16x32_bf16 v[164:167], v[244:247], v[204:207], v[164:167]
	v_mfma_f32_16x16x32_bf16 v[160:163], v[248:251], v[204:207], v[160:163]
	ds_read_b128 v[204:207], v185
	s_waitcnt lgkmcnt(7)
	v_mfma_f32_16x16x32_bf16 v[156:159], v[236:239], v[208:211], v[156:159]
	v_mfma_f32_16x16x32_bf16 v[152:155], v[240:243], v[208:211], v[152:155]
	v_mfma_f32_16x16x32_bf16 v[148:151], v[244:247], v[208:211], v[148:151]
	v_mfma_f32_16x16x32_bf16 v[144:147], v[248:251], v[208:211], v[144:147]
	ds_read_b128 v[208:211], v185 offset:1024
	s_waitcnt lgkmcnt(7)
	v_mfma_f32_16x16x32_bf16 v[136:139], v[236:239], v[212:215], v[136:139]
	v_mfma_f32_16x16x32_bf16 v[132:135], v[240:243], v[212:215], v[132:135]
	v_mfma_f32_16x16x32_bf16 v[128:131], v[244:247], v[212:215], v[128:131]
	v_mfma_f32_16x16x32_bf16 v[124:127], v[248:251], v[212:215], v[124:127]
	ds_read_b128 v[212:215], v185 offset:2048
	s_waitcnt lgkmcnt(7)
	v_mfma_f32_16x16x32_bf16 v[120:123], v[236:239], v[216:219], v[120:123]
	v_mfma_f32_16x16x32_bf16 v[108:111], v[240:243], v[216:219], v[108:111]
	v_mfma_f32_16x16x32_bf16 v[96:99], v[244:247], v[216:219], v[96:99]
	v_mfma_f32_16x16x32_bf16 v[92:95], v[248:251], v[216:219], v[92:95]
	ds_read_b128 v[216:219], v185 offset:3072
	s_waitcnt lgkmcnt(7)
	v_mfma_f32_16x16x32_bf16 v[84:87], v[236:239], v[220:223], v[84:87]
	v_mfma_f32_16x16x32_bf16 v[76:79], v[240:243], v[220:223], v[76:79]
	v_mfma_f32_16x16x32_bf16 v[72:75], v[244:247], v[220:223], v[72:75]
	v_mfma_f32_16x16x32_bf16 v[64:67], v[248:251], v[220:223], v[64:67]
	ds_read_b128 v[220:223], v185 offset:4096
	s_waitcnt lgkmcnt(7)
	v_mfma_f32_16x16x32_bf16 v[56:59], v[236:239], v[224:227], v[56:59]
	v_mfma_f32_16x16x32_bf16 v[52:55], v[240:243], v[224:227], v[52:55]
	v_mfma_f32_16x16x32_bf16 v[44:47], v[244:247], v[224:227], v[44:47]
	v_mfma_f32_16x16x32_bf16 v[36:39], v[248:251], v[224:227], v[36:39]
	ds_read_b128 v[224:227], v185 offset:5120
	s_waitcnt lgkmcnt(7)
	v_mfma_f32_16x16x32_bf16 v[32:35], v[236:239], v[228:231], v[32:35]
	v_mfma_f32_16x16x32_bf16 v[28:31], v[240:243], v[228:231], v[28:31]
	v_mfma_f32_16x16x32_bf16 v[16:19], v[244:247], v[228:231], v[16:19]
	v_mfma_f32_16x16x32_bf16 v[12:15], v[248:251], v[228:231], v[12:15]
	ds_read_b128 v[228:231], v185 offset:6144
	s_waitcnt lgkmcnt(7)
	v_mfma_f32_16x16x32_bf16 v[8:11], v[236:239], v[232:235], v[8:11]
	v_mfma_f32_16x16x32_bf16 v[4:7], v[240:243], v[232:235], v[4:7]
	v_mfma_f32_16x16x32_bf16 v[0:3], v[244:247], v[232:235], v[0:3]
	v_mfma_f32_16x16x32_bf16 v[140:143], v[248:251], v[232:235], v[140:143]
	ds_read_b128 v[232:235], v185 offset:7168
	ds_read_b128 v[236:239], v184
	ds_read_b128 v[240:243], v184 offset:1024
	ds_read_b128 v[244:247], v184 offset:2048
	ds_read_b128 v[248:251], v184 offset:3072
	s_movk_i32 vcc_lo, 0x6000
	s_cmp_eq_u32 m0, 2
	s_cselect_b32 vcc_lo, 0xffff4000, vcc_lo
	s_add_u32 m0, m0, 1
	s_cmp_eq_u32 m0, 3
	s_cselect_b32 m0, 0, m0
	v_add_u32_e32 v185, vcc_lo, v185
	v_add_u32_e32 v184, vcc_lo, v184
	v_xor_b32_e32 v185, 64, v185
	v_xor_b32_e32 v184, 64, v184
	s_sub_u32 vcc_lo, s30, s98
	v_add_u32_e32 v186, vcc_lo, v178
	v_add_u32_e32 v187, vcc_lo, v180
	s_barrier
	s_waitcnt lgkmcnt(0)
	v_mfma_f32_16x16x32_bf16 v[172:175], v[236:239], v[204:207], v[172:175]
	s_waitcnt vmcnt(11)
	v_mfma_f32_16x16x32_bf16 v[168:171], v[240:243], v[204:207], v[168:171]
	ds_write_b128 v183, v[116:119]
	v_add_u32_e32 v116, s26, v186
	v_mfma_f32_16x16x32_bf16 v[164:167], v[244:247], v[204:207], v[164:167]
	global_load_dwordx4 v[116:119], v116, s[98:99] offset:128
	v_mfma_f32_16x16x32_bf16 v[160:163], v[248:251], v[204:207], v[160:163]
	s_waitcnt vmcnt(11)
	ds_write_b128 v183, v[112:115] offset:2048
	v_mfma_f32_16x16x32_bf16 v[156:159], v[236:239], v[208:211], v[156:159]
	v_add_u32_e32 v112, s27, v186
	v_mfma_f32_16x16x32_bf16 v[152:155], v[240:243], v[208:211], v[152:155]
	global_load_dwordx4 v[112:115], v112, s[98:99] offset:128
	s_waitcnt vmcnt(11)
	v_mfma_f32_16x16x32_bf16 v[148:151], v[244:247], v[208:211], v[148:151]
	ds_write_b128 v183, v[104:107] offset:4096
	v_mfma_f32_16x16x32_bf16 v[144:147], v[248:251], v[208:211], v[144:147]
	v_add_u32_e32 v104, s20, v186
	global_load_dwordx4 v[104:107], v104, s[98:99] offset:128
	v_mfma_f32_16x16x32_bf16 v[136:139], v[236:239], v[212:215], v[136:139]
	s_waitcnt vmcnt(11)
	v_mfma_f32_16x16x32_bf16 v[132:135], v[240:243], v[212:215], v[132:135]
	ds_write_b128 v183, v[88:91] offset:6144
	v_add_u32_e32 v88, s21, v186
	v_mfma_f32_16x16x32_bf16 v[128:131], v[244:247], v[212:215], v[128:131]
	global_load_dwordx4 v[88:91], v88, s[98:99] offset:128
	v_mfma_f32_16x16x32_bf16 v[124:127], v[248:251], v[212:215], v[124:127]
	s_waitcnt vmcnt(11)
	ds_write_b128 v183, v[80:83] offset:8192
	v_mfma_f32_16x16x32_bf16 v[120:123], v[236:239], v[216:219], v[120:123]
	v_add_u32_e32 v80, s56, v186
	v_mfma_f32_16x16x32_bf16 v[108:111], v[240:243], v[216:219], v[108:111]
	global_load_dwordx4 v[80:83], v80, s[98:99] offset:128
	s_waitcnt vmcnt(11)
	v_mfma_f32_16x16x32_bf16 v[96:99], v[244:247], v[216:219], v[96:99]
	ds_write_b128 v183, v[68:71] offset:10240
	v_mfma_f32_16x16x32_bf16 v[92:95], v[248:251], v[216:219], v[92:95]
	v_add_u32_e32 v68, s57, v186
	global_load_dwordx4 v[68:71], v68, s[98:99] offset:128
	v_mfma_f32_16x16x32_bf16 v[84:87], v[236:239], v[220:223], v[84:87]
	s_waitcnt vmcnt(11)
	v_mfma_f32_16x16x32_bf16 v[76:79], v[240:243], v[220:223], v[76:79]
	ds_write_b128 v183, v[60:63] offset:12288
	v_add_u32_e32 v60, s24, v186
	v_mfma_f32_16x16x32_bf16 v[72:75], v[244:247], v[220:223], v[72:75]
	global_load_dwordx4 v[60:63], v60, s[98:99] offset:128
	v_mfma_f32_16x16x32_bf16 v[64:67], v[248:251], v[220:223], v[64:67]
	s_waitcnt vmcnt(11)
	ds_write_b128 v183, v[48:51] offset:14336
	v_mfma_f32_16x16x32_bf16 v[56:59], v[236:239], v[224:227], v[56:59]
	v_add_u32_e32 v48, s96, v186
	v_mfma_f32_16x16x32_bf16 v[52:55], v[240:243], v[224:227], v[52:55]
	global_load_dwordx4 v[48:51], v48, s[98:99] offset:128
	s_waitcnt vmcnt(11)
	v_mfma_f32_16x16x32_bf16 v[44:47], v[244:247], v[224:227], v[44:47]
	ds_write_b128 v183, v[100:103] offset:16384
	v_mfma_f32_16x16x32_bf16 v[36:39], v[248:251], v[224:227], v[36:39]
	v_add_u32_e32 v100, s25, v187
	global_load_dwordx4 v[100:103], v100, s[98:99] offset:128
	v_mfma_f32_16x16x32_bf16 v[32:35], v[236:239], v[228:231], v[32:35]
	s_waitcnt vmcnt(11)
	v_mfma_f32_16x16x32_bf16 v[28:31], v[240:243], v[228:231], v[28:31]
	ds_write_b128 v183, v[40:43] offset:18432
	v_add_u32_e32 v40, s33, v187
	v_mfma_f32_16x16x32_bf16 v[16:19], v[244:247], v[228:231], v[16:19]
	global_load_dwordx4 v[40:43], v40, s[98:99] offset:128
	v_mfma_f32_16x16x32_bf16 v[12:15], v[248:251], v[228:231], v[12:15]
	s_waitcnt vmcnt(11)
	ds_write_b128 v183, v[24:27] offset:20480
	v_mfma_f32_16x16x32_bf16 v[8:11], v[236:239], v[232:235], v[8:11]
	v_add_u32_e32 v24, s40, v187
	v_mfma_f32_16x16x32_bf16 v[4:7], v[240:243], v[232:235], v[4:7]
	global_load_dwordx4 v[24:27], v24, s[98:99] offset:128
	s_waitcnt vmcnt(11)
	v_mfma_f32_16x16x32_bf16 v[0:3], v[244:247], v[232:235], v[0:3]
	ds_write_b128 v183, v[20:23] offset:22528
	v_mfma_f32_16x16x32_bf16 v[140:143], v[248:251], v[232:235], v[140:143]
	v_add_u32_e32 v20, s41, v187
	global_load_dwordx4 v[20:23], v20, s[98:99] offset:128
	v_cmp_gt_u32_e32 vcc, 0x6000, v183
	v_add_u32_e32 v182, 0xc000, v183
	v_add_u32_e32 v183, 0xffffa000, v183
	s_nop 0
	v_cndmask_b32_e32 v183, v183, v182, vcc
	s_add_u32 s30, s30, 0x80
	s_addc_u32 s31, s31, 0
	s_cmpk_eq_i32 s30, 0x780
	s_cbranch_scc0 .LBB0_1066
	s_waitcnt lgkmcnt(0)
	s_barrier
	ds_read_b128 v[236:239], v184
	ds_read_b128 v[240:243], v184 offset:1024
	ds_read_b128 v[244:247], v184 offset:2048
	ds_read_b128 v[248:251], v184 offset:3072
	ds_read_b128 v[204:207], v185
	ds_read_b128 v[208:211], v185 offset:1024
	ds_read_b128 v[212:215], v185 offset:2048
	ds_read_b128 v[216:219], v185 offset:3072
	ds_read_b128 v[220:223], v185 offset:4096
	ds_read_b128 v[224:227], v185 offset:5120
	ds_read_b128 v[228:231], v185 offset:6144
	ds_read_b128 v[232:235], v185 offset:7168
	s_movk_i32 vcc_lo, 0x6000
	s_cmp_eq_u32 m0, 2
	s_cselect_b32 vcc_lo, 0xffff4000, vcc_lo
	s_add_u32 m0, m0, 1
	s_cmp_eq_u32 m0, 3
	s_cselect_b32 m0, 0, m0
	v_add_u32_e32 v185, vcc_lo, v185
	v_add_u32_e32 v184, vcc_lo, v184
	v_xor_b32_e32 v185, 64, v185
	v_xor_b32_e32 v184, 64, v184
	s_waitcnt lgkmcnt(7)
	v_mfma_f32_16x16x32_bf16 v[172:175], v[236:239], v[204:207], v[172:175]
	v_mfma_f32_16x16x32_bf16 v[168:171], v[240:243], v[204:207], v[168:171]
	v_mfma_f32_16x16x32_bf16 v[164:167], v[244:247], v[204:207], v[164:167]
	v_mfma_f32_16x16x32_bf16 v[160:163], v[248:251], v[204:207], v[160:163]
	ds_read_b128 v[204:207], v185
	s_waitcnt lgkmcnt(7)
	v_mfma_f32_16x16x32_bf16 v[156:159], v[236:239], v[208:211], v[156:159]
	v_mfma_f32_16x16x32_bf16 v[152:155], v[240:243], v[208:211], v[152:155]
	v_mfma_f32_16x16x32_bf16 v[148:151], v[244:247], v[208:211], v[148:151]
	v_mfma_f32_16x16x32_bf16 v[144:147], v[248:251], v[208:211], v[144:147]
	ds_read_b128 v[208:211], v185 offset:1024
	s_waitcnt lgkmcnt(7)
	v_mfma_f32_16x16x32_bf16 v[136:139], v[236:239], v[212:215], v[136:139]
	v_mfma_f32_16x16x32_bf16 v[132:135], v[240:243], v[212:215], v[132:135]
	v_mfma_f32_16x16x32_bf16 v[128:131], v[244:247], v[212:215], v[128:131]
	v_mfma_f32_16x16x32_bf16 v[124:127], v[248:251], v[212:215], v[124:127]
	ds_read_b128 v[212:215], v185 offset:2048
	s_waitcnt lgkmcnt(7)
	v_mfma_f32_16x16x32_bf16 v[120:123], v[236:239], v[216:219], v[120:123]
	v_mfma_f32_16x16x32_bf16 v[108:111], v[240:243], v[216:219], v[108:111]
	v_mfma_f32_16x16x32_bf16 v[96:99], v[244:247], v[216:219], v[96:99]
	v_mfma_f32_16x16x32_bf16 v[92:95], v[248:251], v[216:219], v[92:95]
	ds_read_b128 v[216:219], v185 offset:3072
	s_waitcnt lgkmcnt(7)
	v_mfma_f32_16x16x32_bf16 v[84:87], v[236:239], v[220:223], v[84:87]
	v_mfma_f32_16x16x32_bf16 v[76:79], v[240:243], v[220:223], v[76:79]
	v_mfma_f32_16x16x32_bf16 v[72:75], v[244:247], v[220:223], v[72:75]
	v_mfma_f32_16x16x32_bf16 v[64:67], v[248:251], v[220:223], v[64:67]
	ds_read_b128 v[220:223], v185 offset:4096
	s_waitcnt lgkmcnt(7)
	v_mfma_f32_16x16x32_bf16 v[56:59], v[236:239], v[224:227], v[56:59]
	v_mfma_f32_16x16x32_bf16 v[52:55], v[240:243], v[224:227], v[52:55]
	v_mfma_f32_16x16x32_bf16 v[44:47], v[244:247], v[224:227], v[44:47]
	v_mfma_f32_16x16x32_bf16 v[36:39], v[248:251], v[224:227], v[36:39]
	ds_read_b128 v[224:227], v185 offset:5120
	s_waitcnt lgkmcnt(7)
	v_mfma_f32_16x16x32_bf16 v[32:35], v[236:239], v[228:231], v[32:35]
	v_mfma_f32_16x16x32_bf16 v[28:31], v[240:243], v[228:231], v[28:31]
	v_mfma_f32_16x16x32_bf16 v[16:19], v[244:247], v[228:231], v[16:19]
	v_mfma_f32_16x16x32_bf16 v[12:15], v[248:251], v[228:231], v[12:15]
	ds_read_b128 v[228:231], v185 offset:6144
	s_waitcnt lgkmcnt(7)
	v_mfma_f32_16x16x32_bf16 v[8:11], v[236:239], v[232:235], v[8:11]
	v_mfma_f32_16x16x32_bf16 v[4:7], v[240:243], v[232:235], v[4:7]
	v_mfma_f32_16x16x32_bf16 v[0:3], v[244:247], v[232:235], v[0:3]
	v_mfma_f32_16x16x32_bf16 v[140:143], v[248:251], v[232:235], v[140:143]
	ds_read_b128 v[232:235], v185 offset:7168
	ds_read_b128 v[236:239], v184
	ds_read_b128 v[240:243], v184 offset:1024
	ds_read_b128 v[244:247], v184 offset:2048
	ds_read_b128 v[248:251], v184 offset:3072
	s_movk_i32 vcc_lo, 0x6000
	s_cmp_eq_u32 m0, 2
	s_cselect_b32 vcc_lo, 0xffff4000, vcc_lo
	s_add_u32 m0, m0, 1
	s_cmp_eq_u32 m0, 3
	s_cselect_b32 m0, 0, m0
	v_add_u32_e32 v185, vcc_lo, v185
	v_add_u32_e32 v184, vcc_lo, v184
	v_xor_b32_e32 v185, 64, v185
	v_xor_b32_e32 v184, 64, v184
	s_waitcnt lgkmcnt(0)
	v_mfma_f32_16x16x32_bf16 v[172:175], v[236:239], v[204:207], v[172:175]
	v_mfma_f32_16x16x32_bf16 v[168:171], v[240:243], v[204:207], v[168:171]
	v_mfma_f32_16x16x32_bf16 v[164:167], v[244:247], v[204:207], v[164:167]
	v_mfma_f32_16x16x32_bf16 v[160:163], v[248:251], v[204:207], v[160:163]
	v_mfma_f32_16x16x32_bf16 v[156:159], v[236:239], v[208:211], v[156:159]
	v_mfma_f32_16x16x32_bf16 v[152:155], v[240:243], v[208:211], v[152:155]
	v_mfma_f32_16x16x32_bf16 v[148:151], v[244:247], v[208:211], v[148:151]
	v_mfma_f32_16x16x32_bf16 v[144:147], v[248:251], v[208:211], v[144:147]
	v_mfma_f32_16x16x32_bf16 v[136:139], v[236:239], v[212:215], v[136:139]
	v_mfma_f32_16x16x32_bf16 v[132:135], v[240:243], v[212:215], v[132:135]
	v_mfma_f32_16x16x32_bf16 v[128:131], v[244:247], v[212:215], v[128:131]
	v_mfma_f32_16x16x32_bf16 v[124:127], v[248:251], v[212:215], v[124:127]
	v_mfma_f32_16x16x32_bf16 v[120:123], v[236:239], v[216:219], v[120:123]
	v_mfma_f32_16x16x32_bf16 v[108:111], v[240:243], v[216:219], v[108:111]
	v_mfma_f32_16x16x32_bf16 v[96:99], v[244:247], v[216:219], v[96:99]
	v_mfma_f32_16x16x32_bf16 v[92:95], v[248:251], v[216:219], v[92:95]
	v_mfma_f32_16x16x32_bf16 v[84:87], v[236:239], v[220:223], v[84:87]
	v_mfma_f32_16x16x32_bf16 v[76:79], v[240:243], v[220:223], v[76:79]
	v_mfma_f32_16x16x32_bf16 v[72:75], v[244:247], v[220:223], v[72:75]
	v_mfma_f32_16x16x32_bf16 v[64:67], v[248:251], v[220:223], v[64:67]
	v_mfma_f32_16x16x32_bf16 v[56:59], v[236:239], v[224:227], v[56:59]
	v_mfma_f32_16x16x32_bf16 v[52:55], v[240:243], v[224:227], v[52:55]
	v_mfma_f32_16x16x32_bf16 v[44:47], v[244:247], v[224:227], v[44:47]
	v_mfma_f32_16x16x32_bf16 v[36:39], v[248:251], v[224:227], v[36:39]
	v_mfma_f32_16x16x32_bf16 v[32:35], v[236:239], v[228:231], v[32:35]
	v_mfma_f32_16x16x32_bf16 v[28:31], v[240:243], v[228:231], v[28:31]
	v_mfma_f32_16x16x32_bf16 v[16:19], v[244:247], v[228:231], v[16:19]
	v_mfma_f32_16x16x32_bf16 v[12:15], v[248:251], v[228:231], v[12:15]
	v_mfma_f32_16x16x32_bf16 v[8:11], v[236:239], v[232:235], v[8:11]
	v_mfma_f32_16x16x32_bf16 v[4:7], v[240:243], v[232:235], v[4:7]
	v_mfma_f32_16x16x32_bf16 v[0:3], v[244:247], v[232:235], v[0:3]
	v_mfma_f32_16x16x32_bf16 v[140:143], v[248:251], v[232:235], v[140:143]
	v_lshrrev_b32_e32 v236, 4, v188
	v_and_b32_e32 v237, 7, v188
	v_bitop3_b32 v238, v236, v237, 3 bitop3:0x6c
	v_lshlrev_b32_e32 v239, 7, v188
	v_bfe_u32 v240, v188, 4, 2
	v_and_b32_e32 v241, 0xffffc780, v239
	v_and_b32_e32 v239, 0x2780, v239
	v_bitop3_b32 v240, v240, v237, 4 bitop3:0x36
	v_lshlrev_b32_e32 v238, 4, v238
	v_lshlrev_b32_e32 v240, 4, v240
	v_or_b32_e32 v185, v241, v238
	v_or_b32_e32 v184, v239, v238
	v_or_b32_e32 v183, v241, v240
	v_or_b32_e32 v182, v239, v240
	s_waitcnt vmcnt(0)
	s_barrier
	s_waitcnt vmcnt(11)
	ds_write_b128 v176, v[116:119]
	s_waitcnt vmcnt(10)
	ds_write_b128 v176, v[112:115] offset:4096
	s_waitcnt vmcnt(9)
	ds_write_b128 v176, v[104:107] offset:8192
	s_waitcnt vmcnt(8)
	ds_write_b128 v176, v[88:91] offset:12288
	s_waitcnt vmcnt(7)
	ds_write_b128 v176, v[80:83] offset:16384
	s_waitcnt vmcnt(6)
	ds_write_b128 v176, v[68:71] offset:20480
	s_waitcnt vmcnt(5)
	ds_write_b128 v176, v[60:63] offset:24576
	s_waitcnt vmcnt(4)
	ds_write_b128 v176, v[48:51] offset:28672
	s_waitcnt vmcnt(3)
	ds_write_b128 v176, v[100:103] offset:32768
	s_waitcnt vmcnt(2)
	ds_write_b128 v176, v[40:43] offset:36864
	s_waitcnt vmcnt(1)
	ds_write_b128 v176, v[24:27] offset:40960
	s_waitcnt vmcnt(0)
	ds_write_b128 v176, v[20:23] offset:45056
	s_waitcnt lgkmcnt(0)
	s_barrier
	ds_read_b128 v[20:23], v185
	ds_read_b128 v[24:27], v185 offset:2048
	ds_read_b128 v[40:43], v185 offset:4096
	ds_read_b128 v[48:51], v185 offset:6144
	ds_read_b128 v[60:63], v185 offset:8192
	ds_read_b128 v[68:71], v185 offset:10240
	ds_read_b128 v[80:83], v185 offset:12288
	ds_read_b128 v[88:91], v185 offset:14336
	ds_read_b128 v[100:103], v184 offset:32768
	ds_read_b128 v[104:107], v184 offset:34816
	ds_read_b128 v[112:115], v184 offset:36864
	ds_read_b128 v[116:119], v184 offset:38912
	s_waitcnt lgkmcnt(3)
	v_mfma_f32_16x16x32_bf16 v[172:175], v[100:103], v[20:23], v[172:175]
	s_waitcnt lgkmcnt(2)
	v_mfma_f32_16x16x32_bf16 v[168:171], v[104:107], v[20:23], v[168:171]
	s_waitcnt lgkmcnt(1)
	v_mfma_f32_16x16x32_bf16 v[164:167], v[112:115], v[20:23], v[164:167]
	s_waitcnt lgkmcnt(0)
	v_mfma_f32_16x16x32_bf16 v[20:23], v[116:119], v[20:23], v[160:163]
	v_mfma_f32_16x16x32_bf16 v[156:159], v[100:103], v[24:27], v[156:159]
	v_mfma_f32_16x16x32_bf16 v[152:155], v[104:107], v[24:27], v[152:155]
	v_mfma_f32_16x16x32_bf16 v[148:151], v[112:115], v[24:27], v[148:151]
	v_mfma_f32_16x16x32_bf16 v[24:27], v[116:119], v[24:27], v[144:147]
	v_mfma_f32_16x16x32_bf16 v[136:139], v[100:103], v[40:43], v[136:139]
	v_mfma_f32_16x16x32_bf16 v[132:135], v[104:107], v[40:43], v[132:135]
	v_mfma_f32_16x16x32_bf16 v[128:131], v[112:115], v[40:43], v[128:131]
	v_mfma_f32_16x16x32_bf16 v[40:43], v[116:119], v[40:43], v[124:127]
	v_mfma_f32_16x16x32_bf16 v[144:147], v[100:103], v[48:51], v[120:123]
	v_mfma_f32_16x16x32_bf16 v[160:163], v[104:107], v[48:51], v[108:111]
	v_mfma_f32_16x16x32_bf16 v[178:181], v[112:115], v[48:51], v[96:99]
	v_mfma_f32_16x16x32_bf16 v[48:51], v[116:119], v[48:51], v[92:95]
	v_mfma_f32_16x16x32_bf16 v[184:187], v[100:103], v[60:63], v[84:87]
	v_mfma_f32_16x16x32_bf16 v[16:19], v[112:115], v[80:83], v[16:19]
	v_mfma_f32_16x16x32_bf16 v[12:15], v[116:119], v[80:83], v[12:15]
	v_mfma_f32_16x16x32_bf16 v[8:11], v[100:103], v[88:91], v[8:11]
	v_mfma_f32_16x16x32_bf16 v[4:7], v[104:107], v[88:91], v[4:7]
	v_mfma_f32_16x16x32_bf16 v[0:3], v[112:115], v[88:91], v[0:3]
	v_mfma_f32_16x16x32_bf16 v[190:193], v[104:107], v[60:63], v[76:79]
	v_mfma_f32_16x16x32_bf16 v[194:197], v[112:115], v[60:63], v[72:75]
	v_mfma_f32_16x16x32_bf16 v[198:201], v[116:119], v[60:63], v[64:67]
	v_mfma_f32_16x16x32_bf16 v[56:59], v[100:103], v[68:71], v[56:59]
	v_mfma_f32_16x16x32_bf16 v[52:55], v[104:107], v[68:71], v[52:55]
	v_mfma_f32_16x16x32_bf16 v[204:207], v[112:115], v[68:71], v[44:47]
	v_mfma_f32_16x16x32_bf16 v[208:211], v[116:119], v[68:71], v[36:39]
	v_mfma_f32_16x16x32_bf16 v[212:215], v[100:103], v[80:83], v[32:35]
	v_mfma_f32_16x16x32_bf16 v[216:219], v[104:107], v[80:83], v[28:31]
	v_mfma_f32_16x16x32_bf16 v[140:143], v[116:119], v[88:91], v[140:143]
	s_nop 1
	ds_read_b128 v[28:31], v183
	ds_read_b128 v[32:35], v183 offset:2048
	ds_read_b128 v[36:39], v183 offset:4096
	ds_read_b128 v[44:47], v183 offset:6144
	ds_read_b128 v[220:223], v183 offset:8192
	ds_read_b128 v[224:227], v183 offset:10240
	ds_read_b128 v[228:231], v183 offset:12288
	ds_read_b128 v[232:235], v183 offset:14336
	ds_read_b128 v[236:239], v182 offset:32768
	ds_read_b128 v[240:243], v182 offset:34816
	ds_read_b128 v[244:247], v182 offset:36864
	ds_read_b128 v[248:251], v182 offset:38912
	s_waitcnt lgkmcnt(3)
	v_mfma_f32_16x16x32_bf16 v[124:127], v[236:239], v[28:31], v[172:175]
	s_mov_b64 s[30:31], 0
	s_waitcnt lgkmcnt(2)
	v_mfma_f32_16x16x32_bf16 v[120:123], v[240:243], v[28:31], v[168:171]
	s_waitcnt lgkmcnt(1)
	v_mfma_f32_16x16x32_bf16 v[116:119], v[244:247], v[28:31], v[164:167]
	s_waitcnt lgkmcnt(0)
	v_mfma_f32_16x16x32_bf16 v[112:115], v[248:251], v[28:31], v[20:23]
	v_mfma_f32_16x16x32_bf16 v[108:111], v[236:239], v[32:35], v[156:159]
	v_mfma_f32_16x16x32_bf16 v[104:107], v[240:243], v[32:35], v[152:155]
	v_mfma_f32_16x16x32_bf16 v[100:103], v[244:247], v[32:35], v[148:151]
	v_mfma_f32_16x16x32_bf16 v[96:99], v[248:251], v[32:35], v[24:27]
	v_mfma_f32_16x16x32_bf16 v[92:95], v[236:239], v[36:39], v[136:139]
	v_mfma_f32_16x16x32_bf16 v[88:91], v[240:243], v[36:39], v[132:135]
	v_mfma_f32_16x16x32_bf16 v[84:87], v[244:247], v[36:39], v[128:131]
	v_mfma_f32_16x16x32_bf16 v[80:83], v[248:251], v[36:39], v[40:43]
	v_mfma_f32_16x16x32_bf16 v[76:79], v[236:239], v[44:47], v[144:147]
	v_mfma_f32_16x16x32_bf16 v[72:75], v[240:243], v[44:47], v[160:163]
	v_mfma_f32_16x16x32_bf16 v[68:71], v[244:247], v[44:47], v[178:181]
	v_mfma_f32_16x16x32_bf16 v[64:67], v[248:251], v[44:47], v[48:51]
	v_mfma_f32_16x16x32_bf16 v[60:63], v[236:239], v[220:223], v[184:187]
	v_mfma_f32_16x16x32_bf16 v[184:187], v[240:243], v[220:223], v[190:193]
	v_mfma_f32_16x16x32_bf16 v[180:183], v[244:247], v[220:223], v[194:197]
	v_mfma_f32_16x16x32_bf16 v[48:51], v[248:251], v[220:223], v[198:201]
	v_mfma_f32_16x16x32_bf16 v[44:47], v[236:239], v[224:227], v[56:59]
	v_mfma_f32_16x16x32_bf16 v[40:43], v[240:243], v[224:227], v[52:55]
	v_mfma_f32_16x16x32_bf16 v[36:39], v[244:247], v[224:227], v[204:207]
	v_mfma_f32_16x16x32_bf16 v[32:35], v[248:251], v[224:227], v[208:211]
	v_mfma_f32_16x16x32_bf16 v[28:31], v[236:239], v[228:231], v[212:215]
	v_mfma_f32_16x16x32_bf16 v[24:27], v[240:243], v[228:231], v[216:219]
	v_mfma_f32_16x16x32_bf16 v[20:23], v[244:247], v[228:231], v[16:19]
	v_mfma_f32_16x16x32_bf16 v[16:19], v[248:251], v[228:231], v[12:15]
	v_mfma_f32_16x16x32_bf16 v[12:15], v[236:239], v[232:235], v[8:11]
	v_mfma_f32_16x16x32_bf16 v[8:11], v[240:243], v[232:235], v[4:7]
	v_xor_b32_e32 v240, 32, v203
	v_mfma_f32_16x16x32_bf16 v[4:7], v[244:247], v[232:235], v[0:3]
	v_mfma_f32_16x16x32_bf16 v[0:3], v[248:251], v[232:235], v[140:143]

.LBB0_1070:
	s_waitcnt lgkmcnt(0)
	s_barrier
	ds_read_b128 v[240:243], v184
	ds_read_b128 v[244:247], v184 offset:1024
	ds_read_b128 v[248:251], v184 offset:2048
	ds_read_b128 v[204:207], v184 offset:3072
	ds_read_b128 v[208:211], v185
	ds_read_b128 v[212:215], v185 offset:1024
	ds_read_b128 v[216:219], v185 offset:2048
	ds_read_b128 v[220:223], v185 offset:3072
	ds_read_b128 v[224:227], v185 offset:4096
	ds_read_b128 v[228:231], v185 offset:5120
	ds_read_b128 v[232:235], v185 offset:6144
	ds_read_b128 v[236:239], v185 offset:7168
	s_movk_i32 vcc_lo, 0x6000
	s_cmp_eq_u32 m0, 2
	s_cselect_b32 vcc_lo, 0xffff4000, vcc_lo
	s_add_u32 m0, m0, 1
	s_cmp_eq_u32 m0, 3
	s_cselect_b32 m0, 0, m0
	v_add_u32_e32 v185, vcc_lo, v185
	v_add_u32_e32 v184, vcc_lo, v184
	v_xor_b32_e32 v185, 64, v185
	v_xor_b32_e32 v184, 64, v184
	s_waitcnt lgkmcnt(7)
	v_mfma_f32_16x16x32_bf16 v[172:175], v[208:211], v[240:243], v[172:175]
	v_mfma_f32_16x16x32_bf16 v[168:171], v[208:211], v[244:247], v[168:171]
	v_mfma_f32_16x16x32_bf16 v[164:167], v[208:211], v[248:251], v[164:167]
	v_mfma_f32_16x16x32_bf16 v[160:163], v[208:211], v[204:207], v[160:163]
	ds_read_b128 v[208:211], v185
	s_waitcnt lgkmcnt(7)
	v_mfma_f32_16x16x32_bf16 v[156:159], v[212:215], v[240:243], v[156:159]
	v_mfma_f32_16x16x32_bf16 v[152:155], v[212:215], v[244:247], v[152:155]
	v_mfma_f32_16x16x32_bf16 v[148:151], v[212:215], v[248:251], v[148:151]
	v_mfma_f32_16x16x32_bf16 v[144:147], v[212:215], v[204:207], v[144:147]
	ds_read_b128 v[212:215], v185 offset:1024
	s_waitcnt lgkmcnt(7)
	v_mfma_f32_16x16x32_bf16 v[136:139], v[216:219], v[240:243], v[136:139]
	v_mfma_f32_16x16x32_bf16 v[132:135], v[216:219], v[244:247], v[132:135]
	v_mfma_f32_16x16x32_bf16 v[128:131], v[216:219], v[248:251], v[128:131]
	v_mfma_f32_16x16x32_bf16 v[124:127], v[216:219], v[204:207], v[124:127]
	ds_read_b128 v[216:219], v185 offset:2048
	s_waitcnt lgkmcnt(7)
	v_mfma_f32_16x16x32_bf16 v[120:123], v[220:223], v[240:243], v[120:123]
	v_mfma_f32_16x16x32_bf16 v[108:111], v[220:223], v[244:247], v[108:111]
	v_mfma_f32_16x16x32_bf16 v[96:99], v[220:223], v[248:251], v[96:99]
	v_mfma_f32_16x16x32_bf16 v[92:95], v[220:223], v[204:207], v[92:95]
	ds_read_b128 v[220:223], v185 offset:3072
	s_waitcnt lgkmcnt(7)
	v_mfma_f32_16x16x32_bf16 v[84:87], v[224:227], v[240:243], v[84:87]
	v_mfma_f32_16x16x32_bf16 v[76:79], v[224:227], v[244:247], v[76:79]
	v_mfma_f32_16x16x32_bf16 v[72:75], v[224:227], v[248:251], v[72:75]
	v_mfma_f32_16x16x32_bf16 v[64:67], v[224:227], v[204:207], v[64:67]
	ds_read_b128 v[224:227], v185 offset:4096
	s_waitcnt lgkmcnt(7)
	v_mfma_f32_16x16x32_bf16 v[56:59], v[228:231], v[240:243], v[56:59]
	v_mfma_f32_16x16x32_bf16 v[52:55], v[228:231], v[244:247], v[52:55]
	v_mfma_f32_16x16x32_bf16 v[44:47], v[228:231], v[248:251], v[44:47]
	v_mfma_f32_16x16x32_bf16 v[36:39], v[228:231], v[204:207], v[36:39]
	ds_read_b128 v[228:231], v185 offset:5120
	s_waitcnt lgkmcnt(7)
	v_mfma_f32_16x16x32_bf16 v[32:35], v[232:235], v[240:243], v[32:35]
	v_mfma_f32_16x16x32_bf16 v[28:31], v[232:235], v[244:247], v[28:31]
	v_mfma_f32_16x16x32_bf16 v[16:19], v[232:235], v[248:251], v[16:19]
	v_mfma_f32_16x16x32_bf16 v[12:15], v[232:235], v[204:207], v[12:15]
	ds_read_b128 v[232:235], v185 offset:6144
	s_waitcnt lgkmcnt(7)
	v_mfma_f32_16x16x32_bf16 v[8:11], v[236:239], v[240:243], v[8:11]
	v_mfma_f32_16x16x32_bf16 v[4:7], v[236:239], v[244:247], v[4:7]
	v_mfma_f32_16x16x32_bf16 v[0:3], v[236:239], v[248:251], v[0:3]
	v_mfma_f32_16x16x32_bf16 v[140:143], v[236:239], v[204:207], v[140:143]
	ds_read_b128 v[236:239], v185 offset:7168
	ds_read_b128 v[240:243], v184
	ds_read_b128 v[244:247], v184 offset:1024
	ds_read_b128 v[248:251], v184 offset:2048
	ds_read_b128 v[204:207], v184 offset:3072
	s_movk_i32 vcc_lo, 0x6000
	s_cmp_eq_u32 m0, 2
	s_cselect_b32 vcc_lo, 0xffff4000, vcc_lo
	s_add_u32 m0, m0, 1
	s_cmp_eq_u32 m0, 3
	s_cselect_b32 m0, 0, m0
	v_add_u32_e32 v185, vcc_lo, v185
	v_add_u32_e32 v184, vcc_lo, v184
	v_xor_b32_e32 v185, 64, v185
	v_xor_b32_e32 v184, 64, v184
	s_sub_u32 vcc_lo, s30, s98
	v_add_u32_e32 v186, vcc_lo, v178
	v_add_u32_e32 v187, vcc_lo, v180
	s_barrier
	s_waitcnt lgkmcnt(0)
	v_mfma_f32_16x16x32_bf16 v[172:175], v[208:211], v[240:243], v[172:175]
	s_waitcnt vmcnt(11)
	v_mfma_f32_16x16x32_bf16 v[168:171], v[208:211], v[244:247], v[168:171]
	ds_write_b128 v183, v[116:119]
	v_add_u32_e32 v116, s26, v186
	v_mfma_f32_16x16x32_bf16 v[164:167], v[208:211], v[248:251], v[164:167]
	global_load_dwordx4 v[116:119], v116, s[98:99] offset:128
	v_mfma_f32_16x16x32_bf16 v[160:163], v[208:211], v[204:207], v[160:163]
	s_waitcnt vmcnt(11)
	ds_write_b128 v183, v[112:115] offset:2048
	v_mfma_f32_16x16x32_bf16 v[156:159], v[212:215], v[240:243], v[156:159]
	v_add_u32_e32 v112, s27, v186
	v_mfma_f32_16x16x32_bf16 v[152:155], v[212:215], v[244:247], v[152:155]
	global_load_dwordx4 v[112:115], v112, s[98:99] offset:128
	s_waitcnt vmcnt(11)
	v_mfma_f32_16x16x32_bf16 v[148:151], v[212:215], v[248:251], v[148:151]
	ds_write_b128 v183, v[104:107] offset:4096
	v_mfma_f32_16x16x32_bf16 v[144:147], v[212:215], v[204:207], v[144:147]
	v_add_u32_e32 v104, s20, v186
	global_load_dwordx4 v[104:107], v104, s[98:99] offset:128
	v_mfma_f32_16x16x32_bf16 v[136:139], v[216:219], v[240:243], v[136:139]
	s_waitcnt vmcnt(11)
	v_mfma_f32_16x16x32_bf16 v[132:135], v[216:219], v[244:247], v[132:135]
	ds_write_b128 v183, v[88:91] offset:6144
	v_add_u32_e32 v88, s21, v186
	v_mfma_f32_16x16x32_bf16 v[128:131], v[216:219], v[248:251], v[128:131]
	global_load_dwordx4 v[88:91], v88, s[98:99] offset:128
	v_mfma_f32_16x16x32_bf16 v[124:127], v[216:219], v[204:207], v[124:127]
	s_waitcnt vmcnt(11)
	ds_write_b128 v183, v[80:83] offset:8192
	v_mfma_f32_16x16x32_bf16 v[120:123], v[220:223], v[240:243], v[120:123]
	v_add_u32_e32 v80, s56, v186
	v_mfma_f32_16x16x32_bf16 v[108:111], v[220:223], v[244:247], v[108:111]
	global_load_dwordx4 v[80:83], v80, s[98:99] offset:128
	s_waitcnt vmcnt(11)
	v_mfma_f32_16x16x32_bf16 v[96:99], v[220:223], v[248:251], v[96:99]
	ds_write_b128 v183, v[68:71] offset:10240
	v_mfma_f32_16x16x32_bf16 v[92:95], v[220:223], v[204:207], v[92:95]
	v_add_u32_e32 v68, s57, v186
	global_load_dwordx4 v[68:71], v68, s[98:99] offset:128
	v_mfma_f32_16x16x32_bf16 v[84:87], v[224:227], v[240:243], v[84:87]
	s_waitcnt vmcnt(11)
	v_mfma_f32_16x16x32_bf16 v[76:79], v[224:227], v[244:247], v[76:79]
	ds_write_b128 v183, v[60:63] offset:12288
	v_add_u32_e32 v60, s24, v186
	v_mfma_f32_16x16x32_bf16 v[72:75], v[224:227], v[248:251], v[72:75]
	global_load_dwordx4 v[60:63], v60, s[98:99] offset:128
	v_mfma_f32_16x16x32_bf16 v[64:67], v[224:227], v[204:207], v[64:67]
	s_waitcnt vmcnt(11)
	ds_write_b128 v183, v[48:51] offset:14336
	v_mfma_f32_16x16x32_bf16 v[56:59], v[228:231], v[240:243], v[56:59]
	v_add_u32_e32 v48, s96, v186
	v_mfma_f32_16x16x32_bf16 v[52:55], v[228:231], v[244:247], v[52:55]
	global_load_dwordx4 v[48:51], v48, s[98:99] offset:128
	s_waitcnt vmcnt(11)
	v_mfma_f32_16x16x32_bf16 v[44:47], v[228:231], v[248:251], v[44:47]
	ds_write_b128 v183, v[100:103] offset:16384
	v_mfma_f32_16x16x32_bf16 v[36:39], v[228:231], v[204:207], v[36:39]
	v_add_u32_e32 v100, s25, v187
	global_load_dwordx4 v[100:103], v100, s[98:99] offset:128
	v_mfma_f32_16x16x32_bf16 v[32:35], v[232:235], v[240:243], v[32:35]
	s_waitcnt vmcnt(11)
	v_mfma_f32_16x16x32_bf16 v[28:31], v[232:235], v[244:247], v[28:31]
	ds_write_b128 v183, v[40:43] offset:18432
	v_add_u32_e32 v40, s33, v187
	v_mfma_f32_16x16x32_bf16 v[16:19], v[232:235], v[248:251], v[16:19]
	global_load_dwordx4 v[40:43], v40, s[98:99] offset:128
	v_mfma_f32_16x16x32_bf16 v[12:15], v[232:235], v[204:207], v[12:15]
	s_waitcnt vmcnt(11)
	ds_write_b128 v183, v[24:27] offset:20480
	v_mfma_f32_16x16x32_bf16 v[8:11], v[236:239], v[240:243], v[8:11]
	v_add_u32_e32 v24, s39, v187
	v_mfma_f32_16x16x32_bf16 v[4:7], v[236:239], v[244:247], v[4:7]
	global_load_dwordx4 v[24:27], v24, s[98:99] offset:128
	s_waitcnt vmcnt(11)
	v_mfma_f32_16x16x32_bf16 v[0:3], v[236:239], v[248:251], v[0:3]
	ds_write_b128 v183, v[20:23] offset:22528
	v_mfma_f32_16x16x32_bf16 v[140:143], v[236:239], v[204:207], v[140:143]
	v_add_u32_e32 v20, s40, v187
	global_load_dwordx4 v[20:23], v20, s[98:99] offset:128
	v_cmp_gt_u32_e32 vcc, 0x6000, v183
	v_add_u32_e32 v182, 0xc000, v183
	v_add_u32_e32 v183, 0xffffa000, v183
	s_nop 0
	v_cndmask_b32_e32 v183, v183, v182, vcc
	s_add_u32 s30, s30, 0x80
	s_addc_u32 s31, s31, 0
	s_cmpk_eq_i32 s30, 0x780
	s_cbranch_scc0 .LBB0_1070
	s_waitcnt lgkmcnt(0)
	s_barrier
	ds_read_b128 v[240:243], v184
	ds_read_b128 v[244:247], v184 offset:1024
	ds_read_b128 v[248:251], v184 offset:2048
	ds_read_b128 v[204:207], v184 offset:3072
	ds_read_b128 v[208:211], v185
	ds_read_b128 v[212:215], v185 offset:1024
	ds_read_b128 v[216:219], v185 offset:2048
	ds_read_b128 v[220:223], v185 offset:3072
	ds_read_b128 v[224:227], v185 offset:4096
	ds_read_b128 v[228:231], v185 offset:5120
	ds_read_b128 v[232:235], v185 offset:6144
	ds_read_b128 v[236:239], v185 offset:7168
	s_movk_i32 vcc_lo, 0x6000
	s_cmp_eq_u32 m0, 2
	s_cselect_b32 vcc_lo, 0xffff4000, vcc_lo
	s_add_u32 m0, m0, 1
	s_cmp_eq_u32 m0, 3
	s_cselect_b32 m0, 0, m0
	v_add_u32_e32 v185, vcc_lo, v185
	v_add_u32_e32 v184, vcc_lo, v184
	v_xor_b32_e32 v185, 64, v185
	v_xor_b32_e32 v184, 64, v184
	s_waitcnt lgkmcnt(7)
	v_mfma_f32_16x16x32_bf16 v[172:175], v[208:211], v[240:243], v[172:175]
	v_mfma_f32_16x16x32_bf16 v[168:171], v[208:211], v[244:247], v[168:171]
	v_mfma_f32_16x16x32_bf16 v[164:167], v[208:211], v[248:251], v[164:167]
	v_mfma_f32_16x16x32_bf16 v[160:163], v[208:211], v[204:207], v[160:163]
	ds_read_b128 v[208:211], v185
	s_waitcnt lgkmcnt(7)
	v_mfma_f32_16x16x32_bf16 v[156:159], v[212:215], v[240:243], v[156:159]
	v_mfma_f32_16x16x32_bf16 v[152:155], v[212:215], v[244:247], v[152:155]
	v_mfma_f32_16x16x32_bf16 v[148:151], v[212:215], v[248:251], v[148:151]
	v_mfma_f32_16x16x32_bf16 v[144:147], v[212:215], v[204:207], v[144:147]
	ds_read_b128 v[212:215], v185 offset:1024
	s_waitcnt lgkmcnt(7)
	v_mfma_f32_16x16x32_bf16 v[136:139], v[216:219], v[240:243], v[136:139]
	v_mfma_f32_16x16x32_bf16 v[132:135], v[216:219], v[244:247], v[132:135]
	v_mfma_f32_16x16x32_bf16 v[128:131], v[216:219], v[248:251], v[128:131]
	v_mfma_f32_16x16x32_bf16 v[124:127], v[216:219], v[204:207], v[124:127]
	ds_read_b128 v[216:219], v185 offset:2048
	s_waitcnt lgkmcnt(7)
	v_mfma_f32_16x16x32_bf16 v[120:123], v[220:223], v[240:243], v[120:123]
	v_mfma_f32_16x16x32_bf16 v[108:111], v[220:223], v[244:247], v[108:111]
	v_mfma_f32_16x16x32_bf16 v[96:99], v[220:223], v[248:251], v[96:99]
	v_mfma_f32_16x16x32_bf16 v[92:95], v[220:223], v[204:207], v[92:95]
	ds_read_b128 v[220:223], v185 offset:3072
	s_waitcnt lgkmcnt(7)
	v_mfma_f32_16x16x32_bf16 v[84:87], v[224:227], v[240:243], v[84:87]
	v_mfma_f32_16x16x32_bf16 v[76:79], v[224:227], v[244:247], v[76:79]
	v_mfma_f32_16x16x32_bf16 v[72:75], v[224:227], v[248:251], v[72:75]
	v_mfma_f32_16x16x32_bf16 v[64:67], v[224:227], v[204:207], v[64:67]
	ds_read_b128 v[224:227], v185 offset:4096
	s_waitcnt lgkmcnt(7)
	v_mfma_f32_16x16x32_bf16 v[56:59], v[228:231], v[240:243], v[56:59]
	v_mfma_f32_16x16x32_bf16 v[52:55], v[228:231], v[244:247], v[52:55]
	v_mfma_f32_16x16x32_bf16 v[44:47], v[228:231], v[248:251], v[44:47]
	v_mfma_f32_16x16x32_bf16 v[36:39], v[228:231], v[204:207], v[36:39]
	ds_read_b128 v[228:231], v185 offset:5120
	s_waitcnt lgkmcnt(7)
	v_mfma_f32_16x16x32_bf16 v[32:35], v[232:235], v[240:243], v[32:35]
	v_mfma_f32_16x16x32_bf16 v[28:31], v[232:235], v[244:247], v[28:31]
	v_mfma_f32_16x16x32_bf16 v[16:19], v[232:235], v[248:251], v[16:19]
	v_mfma_f32_16x16x32_bf16 v[12:15], v[232:235], v[204:207], v[12:15]
	ds_read_b128 v[232:235], v185 offset:6144
	s_waitcnt lgkmcnt(7)
	v_mfma_f32_16x16x32_bf16 v[8:11], v[236:239], v[240:243], v[8:11]
	v_mfma_f32_16x16x32_bf16 v[4:7], v[236:239], v[244:247], v[4:7]
	v_mfma_f32_16x16x32_bf16 v[0:3], v[236:239], v[248:251], v[0:3]
	v_mfma_f32_16x16x32_bf16 v[140:143], v[236:239], v[204:207], v[140:143]
	ds_read_b128 v[236:239], v185 offset:7168
	ds_read_b128 v[240:243], v184
	ds_read_b128 v[244:247], v184 offset:1024
	ds_read_b128 v[248:251], v184 offset:2048
	ds_read_b128 v[204:207], v184 offset:3072
	s_movk_i32 vcc_lo, 0x6000
	s_cmp_eq_u32 m0, 2
	s_cselect_b32 vcc_lo, 0xffff4000, vcc_lo
	s_add_u32 m0, m0, 1
	s_cmp_eq_u32 m0, 3
	s_cselect_b32 m0, 0, m0
	v_add_u32_e32 v185, vcc_lo, v185
	v_add_u32_e32 v184, vcc_lo, v184
	v_xor_b32_e32 v185, 64, v185
	v_xor_b32_e32 v184, 64, v184
	s_waitcnt lgkmcnt(0)
	v_mfma_f32_16x16x32_bf16 v[172:175], v[208:211], v[240:243], v[172:175]
	v_mfma_f32_16x16x32_bf16 v[168:171], v[208:211], v[244:247], v[168:171]
	v_mfma_f32_16x16x32_bf16 v[164:167], v[208:211], v[248:251], v[164:167]
	v_mfma_f32_16x16x32_bf16 v[160:163], v[208:211], v[204:207], v[160:163]
	v_mfma_f32_16x16x32_bf16 v[156:159], v[212:215], v[240:243], v[156:159]
	v_mfma_f32_16x16x32_bf16 v[152:155], v[212:215], v[244:247], v[152:155]
	v_mfma_f32_16x16x32_bf16 v[148:151], v[212:215], v[248:251], v[148:151]
	v_mfma_f32_16x16x32_bf16 v[144:147], v[212:215], v[204:207], v[144:147]
	v_mfma_f32_16x16x32_bf16 v[136:139], v[216:219], v[240:243], v[136:139]
	v_mfma_f32_16x16x32_bf16 v[132:135], v[216:219], v[244:247], v[132:135]
	v_mfma_f32_16x16x32_bf16 v[128:131], v[216:219], v[248:251], v[128:131]
	v_mfma_f32_16x16x32_bf16 v[124:127], v[216:219], v[204:207], v[124:127]
	v_mfma_f32_16x16x32_bf16 v[120:123], v[220:223], v[240:243], v[120:123]
	v_mfma_f32_16x16x32_bf16 v[108:111], v[220:223], v[244:247], v[108:111]
	v_mfma_f32_16x16x32_bf16 v[96:99], v[220:223], v[248:251], v[96:99]
	v_mfma_f32_16x16x32_bf16 v[92:95], v[220:223], v[204:207], v[92:95]
	v_mfma_f32_16x16x32_bf16 v[84:87], v[224:227], v[240:243], v[84:87]
	v_mfma_f32_16x16x32_bf16 v[76:79], v[224:227], v[244:247], v[76:79]
	v_mfma_f32_16x16x32_bf16 v[72:75], v[224:227], v[248:251], v[72:75]
	v_mfma_f32_16x16x32_bf16 v[64:67], v[224:227], v[204:207], v[64:67]
	v_mfma_f32_16x16x32_bf16 v[56:59], v[228:231], v[240:243], v[56:59]
	v_mfma_f32_16x16x32_bf16 v[52:55], v[228:231], v[244:247], v[52:55]
	v_mfma_f32_16x16x32_bf16 v[44:47], v[228:231], v[248:251], v[44:47]
	v_mfma_f32_16x16x32_bf16 v[36:39], v[228:231], v[204:207], v[36:39]
	v_mfma_f32_16x16x32_bf16 v[32:35], v[232:235], v[240:243], v[32:35]
	v_mfma_f32_16x16x32_bf16 v[28:31], v[232:235], v[244:247], v[28:31]
	v_mfma_f32_16x16x32_bf16 v[16:19], v[232:235], v[248:251], v[16:19]
	v_mfma_f32_16x16x32_bf16 v[12:15], v[232:235], v[204:207], v[12:15]
	v_mfma_f32_16x16x32_bf16 v[8:11], v[236:239], v[240:243], v[8:11]
	v_mfma_f32_16x16x32_bf16 v[4:7], v[236:239], v[244:247], v[4:7]
	v_mfma_f32_16x16x32_bf16 v[0:3], v[236:239], v[248:251], v[0:3]
	v_mfma_f32_16x16x32_bf16 v[140:143], v[236:239], v[204:207], v[140:143]
	v_lshrrev_b32_e32 v240, 4, v188
	v_and_b32_e32 v241, 7, v188
	v_bitop3_b32 v242, v240, v241, 3 bitop3:0x6c
	v_lshlrev_b32_e32 v243, 7, v188
	v_bfe_u32 v244, v188, 4, 2
	v_and_b32_e32 v245, 0xffffc780, v243
	v_and_b32_e32 v243, 0x2780, v243
	v_bitop3_b32 v244, v244, v241, 4 bitop3:0x36
	v_lshlrev_b32_e32 v242, 4, v242
	v_lshlrev_b32_e32 v244, 4, v244
	v_or_b32_e32 v185, v245, v242
	v_or_b32_e32 v184, v243, v242
	v_or_b32_e32 v183, v245, v244
	v_or_b32_e32 v182, v243, v244
	s_waitcnt vmcnt(0)
	s_barrier
	s_waitcnt vmcnt(11)
	ds_write_b128 v176, v[116:119]
	s_waitcnt vmcnt(10)
	ds_write_b128 v176, v[112:115] offset:4096
	s_waitcnt vmcnt(9)
	ds_write_b128 v176, v[104:107] offset:8192
	s_waitcnt vmcnt(8)
	ds_write_b128 v176, v[88:91] offset:12288
	s_waitcnt vmcnt(7)
	ds_write_b128 v176, v[80:83] offset:16384
	s_waitcnt vmcnt(6)
	ds_write_b128 v176, v[68:71] offset:20480
	s_waitcnt vmcnt(5)
	ds_write_b128 v176, v[60:63] offset:24576
	s_waitcnt vmcnt(4)
	ds_write_b128 v176, v[48:51] offset:28672
	s_waitcnt vmcnt(3)
	ds_write_b128 v176, v[100:103] offset:32768
	s_waitcnt vmcnt(2)
	ds_write_b128 v176, v[40:43] offset:36864
	s_waitcnt vmcnt(1)
	ds_write_b128 v176, v[24:27] offset:40960
	s_waitcnt vmcnt(0)
	ds_write_b128 v176, v[20:23] offset:45056
	s_waitcnt lgkmcnt(0)
	s_barrier
	ds_read_b128 v[20:23], v185
	ds_read_b128 v[24:27], v185 offset:2048
	ds_read_b128 v[40:43], v185 offset:4096
	ds_read_b128 v[48:51], v185 offset:6144
	ds_read_b128 v[60:63], v185 offset:8192
	ds_read_b128 v[68:71], v185 offset:10240
	ds_read_b128 v[80:83], v185 offset:12288
	ds_read_b128 v[88:91], v185 offset:14336
	ds_read_b128 v[100:103], v184 offset:32768
	ds_read_b128 v[104:107], v184 offset:34816
	ds_read_b128 v[112:115], v184 offset:36864
	ds_read_b128 v[116:119], v184 offset:38912
	s_waitcnt lgkmcnt(3)
	v_mfma_f32_16x16x32_bf16 v[172:175], v[20:23], v[100:103], v[172:175]
	s_waitcnt lgkmcnt(2)
	v_mfma_f32_16x16x32_bf16 v[168:171], v[20:23], v[104:107], v[168:171]
	s_waitcnt lgkmcnt(1)
	v_mfma_f32_16x16x32_bf16 v[164:167], v[20:23], v[112:115], v[164:167]
	s_waitcnt lgkmcnt(0)
	v_mfma_f32_16x16x32_bf16 v[20:23], v[20:23], v[116:119], v[160:163]
	v_mfma_f32_16x16x32_bf16 v[156:159], v[24:27], v[100:103], v[156:159]
	v_mfma_f32_16x16x32_bf16 v[152:155], v[24:27], v[104:107], v[152:155]
	v_mfma_f32_16x16x32_bf16 v[148:151], v[24:27], v[112:115], v[148:151]
	v_mfma_f32_16x16x32_bf16 v[24:27], v[24:27], v[116:119], v[144:147]
	v_mfma_f32_16x16x32_bf16 v[136:139], v[40:43], v[100:103], v[136:139]
	v_mfma_f32_16x16x32_bf16 v[132:135], v[40:43], v[104:107], v[132:135]
	v_mfma_f32_16x16x32_bf16 v[128:131], v[40:43], v[112:115], v[128:131]
	v_mfma_f32_16x16x32_bf16 v[40:43], v[40:43], v[116:119], v[124:127]
	v_mfma_f32_16x16x32_bf16 v[144:147], v[48:51], v[100:103], v[120:123]
	v_mfma_f32_16x16x32_bf16 v[160:163], v[48:51], v[104:107], v[108:111]
	v_mfma_f32_16x16x32_bf16 v[178:181], v[48:51], v[112:115], v[96:99]
	v_mfma_f32_16x16x32_bf16 v[48:51], v[48:51], v[116:119], v[92:95]
	v_mfma_f32_16x16x32_bf16 v[184:187], v[60:63], v[100:103], v[84:87]
	v_mfma_f32_16x16x32_bf16 v[16:19], v[80:83], v[112:115], v[16:19]
	v_mfma_f32_16x16x32_bf16 v[12:15], v[80:83], v[116:119], v[12:15]
	v_mfma_f32_16x16x32_bf16 v[8:11], v[88:91], v[100:103], v[8:11]
	v_mfma_f32_16x16x32_bf16 v[4:7], v[88:91], v[104:107], v[4:7]
	v_mfma_f32_16x16x32_bf16 v[0:3], v[88:91], v[112:115], v[0:3]
	v_mfma_f32_16x16x32_bf16 v[204:207], v[60:63], v[104:107], v[76:79]
	v_mfma_f32_16x16x32_bf16 v[208:211], v[60:63], v[112:115], v[72:75]
	v_mfma_f32_16x16x32_bf16 v[212:215], v[60:63], v[116:119], v[64:67]
	v_mfma_f32_16x16x32_bf16 v[216:219], v[68:71], v[100:103], v[56:59]
	v_mfma_f32_16x16x32_bf16 v[220:223], v[68:71], v[104:107], v[52:55]
	v_mfma_f32_16x16x32_bf16 v[224:227], v[68:71], v[112:115], v[44:47]
	v_mfma_f32_16x16x32_bf16 v[228:231], v[68:71], v[116:119], v[36:39]
	v_mfma_f32_16x16x32_bf16 v[232:235], v[80:83], v[100:103], v[32:35]
	v_mfma_f32_16x16x32_bf16 v[236:239], v[80:83], v[104:107], v[28:31]
	v_mfma_f32_16x16x32_bf16 v[140:143], v[88:91], v[116:119], v[140:143]
	s_nop 1
	ds_read_b128 v[28:31], v183
	ds_read_b128 v[32:35], v183 offset:2048
	ds_read_b128 v[36:39], v183 offset:4096
	ds_read_b128 v[44:47], v183 offset:6144
	ds_read_b128 v[240:243], v183 offset:8192
	ds_read_b128 v[244:247], v183 offset:10240
	ds_read_b128 v[248:251], v183 offset:12288
	ds_read_b128 v[190:193], v183 offset:14336
	ds_read_b128 v[198:201], v182 offset:32768
	ds_read_b128 v[194:197], v182 offset:34816
	ds_read_b128 v[52:55], v182 offset:36864
	ds_read_b128 v[56:59], v182 offset:38912
	s_waitcnt lgkmcnt(3)
	v_mfma_f32_16x16x32_bf16 v[124:127], v[28:31], v[198:201], v[172:175]
	s_waitcnt lgkmcnt(2)
	v_mfma_f32_16x16x32_bf16 v[120:123], v[28:31], v[194:197], v[168:171]
	s_waitcnt lgkmcnt(1)
	v_mfma_f32_16x16x32_bf16 v[116:119], v[28:31], v[52:55], v[164:167]
	s_waitcnt lgkmcnt(0)
	v_mfma_f32_16x16x32_bf16 v[112:115], v[28:31], v[56:59], v[20:23]
	v_mfma_f32_16x16x32_bf16 v[108:111], v[32:35], v[198:201], v[156:159]
	v_mfma_f32_16x16x32_bf16 v[104:107], v[32:35], v[194:197], v[152:155]
	v_mfma_f32_16x16x32_bf16 v[100:103], v[32:35], v[52:55], v[148:151]
	v_mfma_f32_16x16x32_bf16 v[96:99], v[32:35], v[56:59], v[24:27]
	v_mfma_f32_16x16x32_bf16 v[92:95], v[36:39], v[198:201], v[136:139]
	v_mfma_f32_16x16x32_bf16 v[88:91], v[36:39], v[194:197], v[132:135]
	v_mfma_f32_16x16x32_bf16 v[84:87], v[36:39], v[52:55], v[128:131]
	v_mfma_f32_16x16x32_bf16 v[80:83], v[36:39], v[56:59], v[40:43]
	v_mfma_f32_16x16x32_bf16 v[76:79], v[44:47], v[198:201], v[144:147]
	v_mfma_f32_16x16x32_bf16 v[72:75], v[44:47], v[194:197], v[160:163]
	v_mfma_f32_16x16x32_bf16 v[68:71], v[44:47], v[52:55], v[178:181]
	v_mfma_f32_16x16x32_bf16 v[64:67], v[44:47], v[56:59], v[48:51]
	v_mfma_f32_16x16x32_bf16 v[60:63], v[240:243], v[198:201], v[184:187]
	v_mfma_f32_16x16x32_bf16 v[184:187], v[240:243], v[194:197], v[204:207]
	v_mfma_f32_16x16x32_bf16 v[180:183], v[240:243], v[52:55], v[208:211]
	v_mfma_f32_16x16x32_bf16 v[48:51], v[240:243], v[56:59], v[212:215]
	v_xor_b32_e32 v240, 32, v203
	v_mfma_f32_16x16x32_bf16 v[44:47], v[244:247], v[198:201], v[216:219]
	v_mfma_f32_16x16x32_bf16 v[40:43], v[244:247], v[194:197], v[220:223]
	v_mfma_f32_16x16x32_bf16 v[36:39], v[244:247], v[52:55], v[224:227]
	v_mfma_f32_16x16x32_bf16 v[32:35], v[244:247], v[56:59], v[228:231]
	v_mfma_f32_16x16x32_bf16 v[28:31], v[248:251], v[198:201], v[232:235]
	v_mfma_f32_16x16x32_bf16 v[24:27], v[248:251], v[194:197], v[236:239]
	v_mfma_f32_16x16x32_bf16 v[20:23], v[248:251], v[52:55], v[16:19]
	v_mfma_f32_16x16x32_bf16 v[16:19], v[248:251], v[56:59], v[12:15]
	v_mfma_f32_16x16x32_bf16 v[12:15], v[190:193], v[198:201], v[8:11]
	v_mfma_f32_16x16x32_bf16 v[8:11], v[190:193], v[194:197], v[4:7]
	v_mfma_f32_16x16x32_bf16 v[4:7], v[190:193], v[52:55], v[0:3]
	v_mfma_f32_16x16x32_bf16 v[0:3], v[190:193], v[56:59], v[140:143]
